# GEMM LDS-DMA sites: s_nop dropped by placing the address add between the m0 write and the load; vmcnt(8) folded into the lgkmcnt(0) wait
# baseline (speedup 1.0000x reference)
.LBB0_344:
	s_add_i32 s30, s8, 2
	s_add_u32 s9, s12, 0xfff80080
	s_addc_u32 s16, s13, -1
	s_add_i32 s31, 0, 0x10000
	s_cmp_eq_u32 s60, s8
	s_cselect_b32 s17, s53, s16
	s_cselect_b32 s16, s52, s9
	s_cselect_b32 s9, s2, s10
	s_cselect_b32 s8, s3, s7
	s_add_i32 s33, 0, 0x14000
	v_add_u32_e32 v140, s31, v162
	v_add_u32_e32 v168, s33, v162
	ds_read_b128 v[128:131], v140
	ds_read_b128 v[132:135], v140 offset:1024
	ds_read_b128 v[136:139], v140 offset:2048
	ds_read_b128 v[140:143], v140 offset:3072
	ds_read_b128 v[154:157], v168
	ds_read_b128 v[158:161], v168 offset:1024
	ds_read_b128 v[164:167], v168 offset:2048
	ds_read_b128 v[168:171], v168 offset:3072
	v_lshl_add_u64 v[204:205], s[12:13], 0, v[150:151]
	s_add_i32 m0, s28, 0xc000
	ds_read_b128 v[172:175], v163
	ds_read_b128 v[176:179], v163 offset:1024
	ds_read_b128 v[180:183], v163 offset:2048
	ds_read_b128 v[184:187], v163 offset:3072
	ds_read_b128 v[188:191], v163 offset:4096
	ds_read_b128 v[192:195], v163 offset:5120
	ds_read_b128 v[196:199], v163 offset:6144
	ds_read_b128 v[200:203], v163 offset:7168
	global_load_lds_dwordx4 v[204:205], off
	s_add_i32 m0, s28, 0xe000
	v_lshl_add_u64 v[204:205], s[12:13], 0, v[152:153]
	global_load_lds_dwordx4 v[204:205], off
	s_waitcnt vmcnt(8) lgkmcnt(0)
	s_barrier
	v_mfma_f32_16x16x32_bf16 v[112:115], v[128:131], v[172:175], v[112:115]
	v_mfma_f32_16x16x32_bf16 v[116:119], v[136:139], v[172:175], v[116:119]
	v_mfma_f32_16x16x32_bf16 v[96:99], v[128:131], v[180:183], v[96:99]
	v_mfma_f32_16x16x32_bf16 v[100:103], v[136:139], v[180:183], v[100:103]
	v_mfma_f32_16x16x32_bf16 v[80:83], v[128:131], v[188:191], v[80:83]
	v_mfma_f32_16x16x32_bf16 v[84:87], v[136:139], v[188:191], v[84:87]
	v_mfma_f32_16x16x32_bf16 v[48:51], v[128:131], v[196:199], v[48:51]
	v_mfma_f32_16x16x32_bf16 v[52:55], v[136:139], v[196:199], v[52:55]
	v_mfma_f32_16x16x32_bf16 v[112:115], v[132:135], v[176:179], v[112:115]
	v_mfma_f32_16x16x32_bf16 v[116:119], v[140:143], v[176:179], v[116:119]
	v_mfma_f32_16x16x32_bf16 v[96:99], v[132:135], v[184:187], v[96:99]
	v_mfma_f32_16x16x32_bf16 v[100:103], v[140:143], v[184:187], v[100:103]
	v_mfma_f32_16x16x32_bf16 v[80:83], v[132:135], v[192:195], v[80:83]
	v_mfma_f32_16x16x32_bf16 v[84:87], v[140:143], v[192:195], v[84:87]
	v_mfma_f32_16x16x32_bf16 v[48:51], v[132:135], v[200:203], v[48:51]
	v_mfma_f32_16x16x32_bf16 v[52:55], v[140:143], v[200:203], v[52:55]
	v_mfma_f32_16x16x32_bf16 v[120:123], v[154:157], v[172:175], v[120:123]
	v_mfma_f32_16x16x32_bf16 v[124:127], v[164:167], v[172:175], v[124:127]
	v_mfma_f32_16x16x32_bf16 v[104:107], v[154:157], v[180:183], v[104:107]
	v_mfma_f32_16x16x32_bf16 v[108:111], v[164:167], v[180:183], v[108:111]
	v_mfma_f32_16x16x32_bf16 v[88:91], v[154:157], v[188:191], v[88:91]
	v_mfma_f32_16x16x32_bf16 v[92:95], v[164:167], v[188:191], v[92:95]
	v_mfma_f32_16x16x32_bf16 v[64:67], v[154:157], v[196:199], v[64:67]
	v_mfma_f32_16x16x32_bf16 v[68:71], v[164:167], v[196:199], v[68:71]
	v_mfma_f32_16x16x32_bf16 v[120:123], v[158:161], v[176:179], v[120:123]
	v_mfma_f32_16x16x32_bf16 v[124:127], v[168:171], v[176:179], v[124:127]
	v_mfma_f32_16x16x32_bf16 v[104:107], v[158:161], v[184:187], v[104:107]
	v_mfma_f32_16x16x32_bf16 v[108:111], v[168:171], v[184:187], v[108:111]
	v_mfma_f32_16x16x32_bf16 v[88:91], v[158:161], v[192:195], v[88:91]
	v_mfma_f32_16x16x32_bf16 v[92:95], v[168:171], v[192:195], v[92:95]
	v_mfma_f32_16x16x32_bf16 v[64:67], v[158:161], v[200:203], v[64:67]
	v_mfma_f32_16x16x32_bf16 v[68:71], v[168:171], v[200:203], v[68:71]
	s_barrier
	s_add_i32 s31, s31, s26
	v_lshl_add_u64 v[204:205], s[8:9], 0, v[224:225]
	s_mov_b32 m0, s31
	ds_read_b128 v[172:175], v163 offset:16384
	ds_read_b128 v[176:179], v163 offset:17408
	ds_read_b128 v[180:183], v163 offset:18432
	ds_read_b128 v[184:187], v163 offset:19456
	ds_read_b128 v[188:191], v163 offset:20480
	ds_read_b128 v[192:195], v163 offset:21504
	ds_read_b128 v[196:199], v163 offset:22528
	ds_read_b128 v[200:203], v163 offset:23552
	global_load_lds_dwordx4 v[204:205], off
	s_add_i32 m0, s31, 0x2000
	s_add_u32 s40, s8, 0x80000
	v_lshl_add_u64 v[206:207], s[8:9], 0, v[144:145]
	s_addc_u32 s41, s9, 0
	s_add_i32 s31, s33, s26
	global_load_lds_dwordx4 v[206:207], off
	v_lshl_add_u64 v[208:209], s[40:41], 0, v[224:225]
	s_mov_b32 m0, s31
	v_lshl_add_u64 v[210:211], s[16:17], 0, v[146:147]
	global_load_lds_dwordx4 v[208:209], off
	s_add_i32 m0, s31, 0x2000
	v_lshl_add_u64 v[208:209], s[40:41], 0, v[144:145]
	global_load_lds_dwordx4 v[208:209], off
	s_mov_b32 m0, s28
	v_lshl_add_u64 v[208:209], s[16:17], 0, v[148:149]
	global_load_lds_dwordx4 v[208:209], off
	s_mov_b32 m0, s29
	s_nop 0
	global_load_lds_dwordx4 v[210:211], off
	s_waitcnt vmcnt(8) lgkmcnt(0)
	s_barrier
	v_mfma_f32_16x16x32_bf16 v[56:59], v[128:131], v[172:175], v[56:59]
	v_mfma_f32_16x16x32_bf16 v[60:63], v[136:139], v[172:175], v[60:63]
	v_mfma_f32_16x16x32_bf16 v[32:35], v[128:131], v[180:183], v[32:35]
	v_mfma_f32_16x16x32_bf16 v[36:39], v[136:139], v[180:183], v[36:39]
	v_mfma_f32_16x16x32_bf16 v[16:19], v[128:131], v[188:191], v[16:19]
	v_mfma_f32_16x16x32_bf16 v[20:23], v[136:139], v[188:191], v[20:23]
	v_mfma_f32_16x16x32_bf16 v[0:3], v[128:131], v[196:199], v[0:3]
	v_mfma_f32_16x16x32_bf16 v[4:7], v[136:139], v[196:199], v[4:7]
	v_mfma_f32_16x16x32_bf16 v[56:59], v[132:135], v[176:179], v[56:59]
	v_mfma_f32_16x16x32_bf16 v[60:63], v[140:143], v[176:179], v[60:63]
	v_mfma_f32_16x16x32_bf16 v[32:35], v[132:135], v[184:187], v[32:35]
	v_mfma_f32_16x16x32_bf16 v[36:39], v[140:143], v[184:187], v[36:39]
	v_mfma_f32_16x16x32_bf16 v[16:19], v[132:135], v[192:195], v[16:19]
	v_mfma_f32_16x16x32_bf16 v[20:23], v[140:143], v[192:195], v[20:23]
	v_mfma_f32_16x16x32_bf16 v[0:3], v[132:135], v[200:203], v[0:3]
	v_mfma_f32_16x16x32_bf16 v[4:7], v[140:143], v[200:203], v[4:7]
	v_mfma_f32_16x16x32_bf16 v[72:75], v[154:157], v[172:175], v[72:75]
	v_mfma_f32_16x16x32_bf16 v[76:79], v[164:167], v[172:175], v[76:79]
	v_mfma_f32_16x16x32_bf16 v[40:43], v[154:157], v[180:183], v[40:43]
	v_mfma_f32_16x16x32_bf16 v[44:47], v[164:167], v[180:183], v[44:47]
	v_mfma_f32_16x16x32_bf16 v[24:27], v[154:157], v[188:191], v[24:27]
	v_mfma_f32_16x16x32_bf16 v[28:31], v[164:167], v[188:191], v[28:31]
	v_mfma_f32_16x16x32_bf16 v[8:11], v[154:157], v[196:199], v[8:11]
	v_mfma_f32_16x16x32_bf16 v[12:15], v[164:167], v[196:199], v[12:15]
	v_mfma_f32_16x16x32_bf16 v[72:75], v[158:161], v[176:179], v[72:75]
	v_mfma_f32_16x16x32_bf16 v[76:79], v[168:171], v[176:179], v[76:79]
	v_mfma_f32_16x16x32_bf16 v[40:43], v[158:161], v[184:187], v[40:43]
	v_mfma_f32_16x16x32_bf16 v[44:47], v[168:171], v[184:187], v[44:47]
	v_mfma_f32_16x16x32_bf16 v[24:27], v[158:161], v[192:195], v[24:27]
	v_mfma_f32_16x16x32_bf16 v[28:31], v[168:171], v[192:195], v[28:31]
	v_mfma_f32_16x16x32_bf16 v[8:11], v[158:161], v[200:203], v[8:11]
	v_mfma_f32_16x16x32_bf16 v[12:15], v[168:171], v[200:203], v[12:15]
	s_barrier
	s_add_i32 s31, 0, 0x18000
	s_add_i32 s33, 0, 0x1c000
	v_add_u32_e32 v140, s31, v162
	v_add_u32_e32 v168, s33, v162
	ds_read_b128 v[128:131], v140
	ds_read_b128 v[132:135], v140 offset:1024
	ds_read_b128 v[136:139], v140 offset:2048
	ds_read_b128 v[140:143], v140 offset:3072
	ds_read_b128 v[154:157], v168
	ds_read_b128 v[158:161], v168 offset:1024
	ds_read_b128 v[164:167], v168 offset:2048
	ds_read_b128 v[168:171], v168 offset:3072
	s_add_u32 s16, s16, 0x80000
	s_addc_u32 s17, s17, 0
	s_mov_b32 m0, s34
	v_lshl_add_u64 v[212:213], s[16:17], 0, v[148:149]
	ds_read_b128 v[172:175], v163 offset:32768
	ds_read_b128 v[176:179], v163 offset:33792
	ds_read_b128 v[180:183], v163 offset:34816
	ds_read_b128 v[184:187], v163 offset:35840
	ds_read_b128 v[188:191], v163 offset:36864
	ds_read_b128 v[192:195], v163 offset:37888
	ds_read_b128 v[196:199], v163 offset:38912
	ds_read_b128 v[200:203], v163 offset:39936
	global_load_lds_dwordx4 v[212:213], off
	s_mov_b32 m0, s35
	v_lshl_add_u64 v[212:213], s[16:17], 0, v[146:147]
	global_load_lds_dwordx4 v[212:213], off
	s_waitcnt vmcnt(8) lgkmcnt(0)
	s_barrier
	v_mfma_f32_16x16x32_bf16 v[112:115], v[128:131], v[172:175], v[112:115]
	v_mfma_f32_16x16x32_bf16 v[116:119], v[136:139], v[172:175], v[116:119]
	v_mfma_f32_16x16x32_bf16 v[96:99], v[128:131], v[180:183], v[96:99]
	v_mfma_f32_16x16x32_bf16 v[100:103], v[136:139], v[180:183], v[100:103]
	v_mfma_f32_16x16x32_bf16 v[80:83], v[128:131], v[188:191], v[80:83]
	v_mfma_f32_16x16x32_bf16 v[84:87], v[136:139], v[188:191], v[84:87]
	v_mfma_f32_16x16x32_bf16 v[48:51], v[128:131], v[196:199], v[48:51]
	v_mfma_f32_16x16x32_bf16 v[52:55], v[136:139], v[196:199], v[52:55]
	v_mfma_f32_16x16x32_bf16 v[112:115], v[132:135], v[176:179], v[112:115]
	v_mfma_f32_16x16x32_bf16 v[116:119], v[140:143], v[176:179], v[116:119]
	v_mfma_f32_16x16x32_bf16 v[96:99], v[132:135], v[184:187], v[96:99]
	v_mfma_f32_16x16x32_bf16 v[100:103], v[140:143], v[184:187], v[100:103]
	v_mfma_f32_16x16x32_bf16 v[80:83], v[132:135], v[192:195], v[80:83]
	v_mfma_f32_16x16x32_bf16 v[84:87], v[140:143], v[192:195], v[84:87]
	v_mfma_f32_16x16x32_bf16 v[48:51], v[132:135], v[200:203], v[48:51]
	v_mfma_f32_16x16x32_bf16 v[52:55], v[140:143], v[200:203], v[52:55]
	v_mfma_f32_16x16x32_bf16 v[120:123], v[154:157], v[172:175], v[120:123]
	v_mfma_f32_16x16x32_bf16 v[124:127], v[164:167], v[172:175], v[124:127]
	v_mfma_f32_16x16x32_bf16 v[104:107], v[154:157], v[180:183], v[104:107]
	v_mfma_f32_16x16x32_bf16 v[108:111], v[164:167], v[180:183], v[108:111]
	v_mfma_f32_16x16x32_bf16 v[88:91], v[154:157], v[188:191], v[88:91]
	v_mfma_f32_16x16x32_bf16 v[92:95], v[164:167], v[188:191], v[92:95]
	v_mfma_f32_16x16x32_bf16 v[64:67], v[154:157], v[196:199], v[64:67]
	v_mfma_f32_16x16x32_bf16 v[68:71], v[164:167], v[196:199], v[68:71]
	v_mfma_f32_16x16x32_bf16 v[120:123], v[158:161], v[176:179], v[120:123]
	v_mfma_f32_16x16x32_bf16 v[124:127], v[168:171], v[176:179], v[124:127]
	v_mfma_f32_16x16x32_bf16 v[104:107], v[158:161], v[184:187], v[104:107]
	v_mfma_f32_16x16x32_bf16 v[108:111], v[168:171], v[184:187], v[108:111]
	v_mfma_f32_16x16x32_bf16 v[88:91], v[158:161], v[192:195], v[88:91]
	v_mfma_f32_16x16x32_bf16 v[92:95], v[168:171], v[192:195], v[92:95]
	v_mfma_f32_16x16x32_bf16 v[64:67], v[158:161], v[200:203], v[64:67]
	v_mfma_f32_16x16x32_bf16 v[68:71], v[168:171], v[200:203], v[68:71]
	s_barrier
	s_add_i32 s16, s31, s26
	v_lshl_add_u64 v[204:205], v[204:205], 0, s[24:25]
	s_mov_b32 m0, s16
	ds_read_b128 v[172:175], v163 offset:49152
	ds_read_b128 v[176:179], v163 offset:50176
	ds_read_b128 v[180:183], v163 offset:51200
	ds_read_b128 v[184:187], v163 offset:52224
	ds_read_b128 v[188:191], v163 offset:53248
	ds_read_b128 v[192:195], v163 offset:54272
	ds_read_b128 v[196:199], v163 offset:55296
	ds_read_b128 v[200:203], v163 offset:56320
	global_load_lds_dwordx4 v[204:205], off
	s_add_i32 m0, s16, 0x2000
	s_add_u32 s8, s8, 0x80080
	v_lshl_add_u64 v[204:205], v[206:207], 0, s[24:25]
	s_addc_u32 s9, s9, 0
	s_add_i32 s16, s33, s26
	global_load_lds_dwordx4 v[204:205], off
	s_mov_b32 m0, s16
	v_lshl_add_u64 v[204:205], s[8:9], 0, v[224:225]
	global_load_lds_dwordx4 v[204:205], off
	s_add_i32 m0, s16, 0x2000
	v_lshl_add_u64 v[204:205], s[8:9], 0, v[144:145]
	global_load_lds_dwordx4 v[204:205], off
	s_mov_b32 m0, s58
	v_lshl_add_u64 v[204:205], v[208:209], 0, s[24:25]
	global_load_lds_dwordx4 v[204:205], off
	s_mov_b32 m0, s59
	v_lshl_add_u64 v[204:205], v[210:211], 0, s[24:25]
	global_load_lds_dwordx4 v[204:205], off
	s_waitcnt vmcnt(8) lgkmcnt(0)
	s_barrier
	v_mfma_f32_16x16x32_bf16 v[56:59], v[128:131], v[172:175], v[56:59]
	v_mfma_f32_16x16x32_bf16 v[60:63], v[136:139], v[172:175], v[60:63]
	v_mfma_f32_16x16x32_bf16 v[32:35], v[128:131], v[180:183], v[32:35]
	v_mfma_f32_16x16x32_bf16 v[36:39], v[136:139], v[180:183], v[36:39]
	v_mfma_f32_16x16x32_bf16 v[16:19], v[128:131], v[188:191], v[16:19]
	v_mfma_f32_16x16x32_bf16 v[20:23], v[136:139], v[188:191], v[20:23]
	v_mfma_f32_16x16x32_bf16 v[0:3], v[128:131], v[196:199], v[0:3]
	v_mfma_f32_16x16x32_bf16 v[4:7], v[136:139], v[196:199], v[4:7]
	v_mfma_f32_16x16x32_bf16 v[56:59], v[132:135], v[176:179], v[56:59]
	v_mfma_f32_16x16x32_bf16 v[60:63], v[140:143], v[176:179], v[60:63]
	v_mfma_f32_16x16x32_bf16 v[32:35], v[132:135], v[184:187], v[32:35]
	v_mfma_f32_16x16x32_bf16 v[36:39], v[140:143], v[184:187], v[36:39]
	v_mfma_f32_16x16x32_bf16 v[16:19], v[132:135], v[192:195], v[16:19]
	v_mfma_f32_16x16x32_bf16 v[20:23], v[140:143], v[192:195], v[20:23]
	v_mfma_f32_16x16x32_bf16 v[0:3], v[132:135], v[200:203], v[0:3]
	v_mfma_f32_16x16x32_bf16 v[4:7], v[140:143], v[200:203], v[4:7]
	v_mfma_f32_16x16x32_bf16 v[72:75], v[154:157], v[172:175], v[72:75]
	v_mfma_f32_16x16x32_bf16 v[76:79], v[164:167], v[172:175], v[76:79]
	v_mfma_f32_16x16x32_bf16 v[40:43], v[154:157], v[180:183], v[40:43]
	v_mfma_f32_16x16x32_bf16 v[44:47], v[164:167], v[180:183], v[44:47]
	v_mfma_f32_16x16x32_bf16 v[24:27], v[154:157], v[188:191], v[24:27]
	v_mfma_f32_16x16x32_bf16 v[28:31], v[164:167], v[188:191], v[28:31]
	v_mfma_f32_16x16x32_bf16 v[8:11], v[154:157], v[196:199], v[8:11]
	v_mfma_f32_16x16x32_bf16 v[12:15], v[164:167], v[196:199], v[12:15]
	v_mfma_f32_16x16x32_bf16 v[72:75], v[158:161], v[176:179], v[72:75]
	v_mfma_f32_16x16x32_bf16 v[76:79], v[168:171], v[176:179], v[76:79]
	v_mfma_f32_16x16x32_bf16 v[40:43], v[158:161], v[184:187], v[40:43]
	v_mfma_f32_16x16x32_bf16 v[44:47], v[168:171], v[184:187], v[44:47]
	v_mfma_f32_16x16x32_bf16 v[24:27], v[158:161], v[192:195], v[24:27]
	v_mfma_f32_16x16x32_bf16 v[28:31], v[168:171], v[192:195], v[28:31]
	v_mfma_f32_16x16x32_bf16 v[8:11], v[158:161], v[200:203], v[8:11]
	v_mfma_f32_16x16x32_bf16 v[12:15], v[168:171], v[200:203], v[12:15]
	s_barrier
	s_add_u32 s12, s12, 0x100
	s_addc_u32 s13, s13, 0
	s_add_u32 s7, s7, 0x100
	s_addc_u32 s10, s10, 0
	s_cmp_ge_i32 s30, s57
	s_mov_b32 s8, s30
	s_cbranch_scc0 .LBB0_344

.LBB0_920:
	s_add_i32 s33, s8, 2
	s_add_u32 s9, s12, 0xffff0080
	s_addc_u32 s20, s13, -1
	s_add_i32 s61, 0, 0x10000
	s_cmp_eq_u32 s59, s8
	s_cselect_b32 s21, s3, s20
	s_cselect_b32 s20, s7, s9
	s_cselect_b32 s9, s23, s31
	s_cselect_b32 s8, s27, s30
	s_add_i32 s64, 0, 0x14000
	v_add_u32_e32 v150, s61, v170
	v_add_u32_e32 v166, s64, v170
	ds_read_b128 v[128:131], v150
	ds_read_b128 v[132:135], v150 offset:1024
	ds_read_b128 v[146:149], v150 offset:2048
	ds_read_b128 v[150:153], v150 offset:3072
	ds_read_b128 v[154:157], v166
	ds_read_b128 v[158:161], v166 offset:1024
	ds_read_b128 v[162:165], v166 offset:2048
	ds_read_b128 v[166:169], v166 offset:3072
	v_lshl_add_u64 v[204:205], s[12:13], 0, v[142:143]
	s_add_i32 m0, s49, 0xc000
	ds_read_b128 v[172:175], v171
	ds_read_b128 v[176:179], v171 offset:1024
	ds_read_b128 v[180:183], v171 offset:2048
	ds_read_b128 v[184:187], v171 offset:3072
	ds_read_b128 v[188:191], v171 offset:4096
	ds_read_b128 v[192:195], v171 offset:5120
	ds_read_b128 v[196:199], v171 offset:6144
	ds_read_b128 v[200:203], v171 offset:7168
	global_load_lds_dwordx4 v[204:205], off
	s_add_i32 m0, s49, 0xe000
	v_lshl_add_u64 v[204:205], s[12:13], 0, v[144:145]
	global_load_lds_dwordx4 v[204:205], off
	s_waitcnt vmcnt(8) lgkmcnt(0)
	s_barrier
	v_mfma_f32_16x16x32_bf16 v[120:123], v[128:131], v[172:175], v[120:123]
	v_mfma_f32_16x16x32_bf16 v[124:127], v[146:149], v[172:175], v[124:127]
	v_mfma_f32_16x16x32_bf16 v[116:119], v[128:131], v[180:183], v[116:119]
	v_mfma_f32_16x16x32_bf16 v[112:115], v[146:149], v[180:183], v[112:115]
	v_mfma_f32_16x16x32_bf16 v[108:111], v[128:131], v[188:191], v[108:111]
	v_mfma_f32_16x16x32_bf16 v[104:107], v[146:149], v[188:191], v[104:107]
	v_mfma_f32_16x16x32_bf16 v[100:103], v[128:131], v[196:199], v[100:103]
	v_mfma_f32_16x16x32_bf16 v[96:99], v[146:149], v[196:199], v[96:99]
	v_mfma_f32_16x16x32_bf16 v[120:123], v[132:135], v[176:179], v[120:123]
	v_mfma_f32_16x16x32_bf16 v[124:127], v[150:153], v[176:179], v[124:127]
	v_mfma_f32_16x16x32_bf16 v[116:119], v[132:135], v[184:187], v[116:119]
	v_mfma_f32_16x16x32_bf16 v[112:115], v[150:153], v[184:187], v[112:115]
	v_mfma_f32_16x16x32_bf16 v[108:111], v[132:135], v[192:195], v[108:111]
	v_mfma_f32_16x16x32_bf16 v[104:107], v[150:153], v[192:195], v[104:107]
	v_mfma_f32_16x16x32_bf16 v[100:103], v[132:135], v[200:203], v[100:103]
	v_mfma_f32_16x16x32_bf16 v[96:99], v[150:153], v[200:203], v[96:99]
	v_mfma_f32_16x16x32_bf16 v[60:63], v[154:157], v[172:175], v[60:63]
	v_mfma_f32_16x16x32_bf16 v[56:59], v[162:165], v[172:175], v[56:59]
	v_mfma_f32_16x16x32_bf16 v[52:55], v[154:157], v[180:183], v[52:55]
	v_mfma_f32_16x16x32_bf16 v[48:51], v[162:165], v[180:183], v[48:51]
	v_mfma_f32_16x16x32_bf16 v[44:47], v[154:157], v[188:191], v[44:47]
	v_mfma_f32_16x16x32_bf16 v[40:43], v[162:165], v[188:191], v[40:43]
	v_mfma_f32_16x16x32_bf16 v[36:39], v[154:157], v[196:199], v[36:39]
	v_mfma_f32_16x16x32_bf16 v[32:35], v[162:165], v[196:199], v[32:35]
	v_mfma_f32_16x16x32_bf16 v[60:63], v[158:161], v[176:179], v[60:63]
	v_mfma_f32_16x16x32_bf16 v[56:59], v[166:169], v[176:179], v[56:59]
	v_mfma_f32_16x16x32_bf16 v[52:55], v[158:161], v[184:187], v[52:55]
	v_mfma_f32_16x16x32_bf16 v[48:51], v[166:169], v[184:187], v[48:51]
	v_mfma_f32_16x16x32_bf16 v[44:47], v[158:161], v[192:195], v[44:47]
	v_mfma_f32_16x16x32_bf16 v[40:43], v[166:169], v[192:195], v[40:43]
	v_mfma_f32_16x16x32_bf16 v[36:39], v[158:161], v[200:203], v[36:39]
	v_mfma_f32_16x16x32_bf16 v[32:35], v[166:169], v[200:203], v[32:35]
	s_barrier
	s_add_i32 s61, s61, s35
	v_lshl_add_u64 v[204:205], s[8:9], 0, v[224:225]
	s_mov_b32 m0, s61
	ds_read_b128 v[172:175], v171 offset:16384
	ds_read_b128 v[176:179], v171 offset:17408
	ds_read_b128 v[180:183], v171 offset:18432
	ds_read_b128 v[184:187], v171 offset:19456
	ds_read_b128 v[188:191], v171 offset:20480
	ds_read_b128 v[192:195], v171 offset:21504
	ds_read_b128 v[196:199], v171 offset:22528
	ds_read_b128 v[200:203], v171 offset:23552
	global_load_lds_dwordx4 v[204:205], off
	s_add_i32 m0, s61, 0x2000
	s_add_u32 s62, s8, 0x10000
	v_lshl_add_u64 v[206:207], s[8:9], 0, v[136:137]
	s_addc_u32 s63, s9, 0
	s_add_i32 s61, s64, s35
	global_load_lds_dwordx4 v[206:207], off
	v_lshl_add_u64 v[208:209], s[62:63], 0, v[224:225]
	s_mov_b32 m0, s61
	v_lshl_add_u64 v[210:211], s[20:21], 0, v[138:139]
	global_load_lds_dwordx4 v[208:209], off
	s_add_i32 m0, s61, 0x2000
	v_lshl_add_u64 v[208:209], s[62:63], 0, v[136:137]
	global_load_lds_dwordx4 v[208:209], off
	s_mov_b32 m0, s49
	v_lshl_add_u64 v[208:209], s[20:21], 0, v[140:141]
	global_load_lds_dwordx4 v[208:209], off
	s_mov_b32 m0, s50
	s_nop 0
	global_load_lds_dwordx4 v[210:211], off
	s_waitcnt vmcnt(8) lgkmcnt(0)
	s_barrier
	v_mfma_f32_16x16x32_bf16 v[92:95], v[128:131], v[172:175], v[92:95]
	v_mfma_f32_16x16x32_bf16 v[88:91], v[146:149], v[172:175], v[88:91]
	v_mfma_f32_16x16x32_bf16 v[84:87], v[128:131], v[180:183], v[84:87]
	v_mfma_f32_16x16x32_bf16 v[80:83], v[146:149], v[180:183], v[80:83]
	v_mfma_f32_16x16x32_bf16 v[76:79], v[128:131], v[188:191], v[76:79]
	v_mfma_f32_16x16x32_bf16 v[72:75], v[146:149], v[188:191], v[72:75]
	v_mfma_f32_16x16x32_bf16 v[68:71], v[128:131], v[196:199], v[68:71]
	v_mfma_f32_16x16x32_bf16 v[64:67], v[146:149], v[196:199], v[64:67]
	v_mfma_f32_16x16x32_bf16 v[92:95], v[132:135], v[176:179], v[92:95]
	v_mfma_f32_16x16x32_bf16 v[88:91], v[150:153], v[176:179], v[88:91]
	v_mfma_f32_16x16x32_bf16 v[84:87], v[132:135], v[184:187], v[84:87]
	v_mfma_f32_16x16x32_bf16 v[80:83], v[150:153], v[184:187], v[80:83]
	v_mfma_f32_16x16x32_bf16 v[76:79], v[132:135], v[192:195], v[76:79]
	v_mfma_f32_16x16x32_bf16 v[72:75], v[150:153], v[192:195], v[72:75]
	v_mfma_f32_16x16x32_bf16 v[68:71], v[132:135], v[200:203], v[68:71]
	v_mfma_f32_16x16x32_bf16 v[64:67], v[150:153], v[200:203], v[64:67]
	v_mfma_f32_16x16x32_bf16 v[28:31], v[154:157], v[172:175], v[28:31]
	v_mfma_f32_16x16x32_bf16 v[24:27], v[162:165], v[172:175], v[24:27]
	v_mfma_f32_16x16x32_bf16 v[20:23], v[154:157], v[180:183], v[20:23]
	v_mfma_f32_16x16x32_bf16 v[16:19], v[162:165], v[180:183], v[16:19]
	v_mfma_f32_16x16x32_bf16 v[12:15], v[154:157], v[188:191], v[12:15]
	v_mfma_f32_16x16x32_bf16 v[8:11], v[162:165], v[188:191], v[8:11]
	v_mfma_f32_16x16x32_bf16 v[4:7], v[154:157], v[196:199], v[4:7]
	v_mfma_f32_16x16x32_bf16 v[0:3], v[162:165], v[196:199], v[0:3]
	v_mfma_f32_16x16x32_bf16 v[28:31], v[158:161], v[176:179], v[28:31]
	v_mfma_f32_16x16x32_bf16 v[24:27], v[166:169], v[176:179], v[24:27]
	v_mfma_f32_16x16x32_bf16 v[20:23], v[158:161], v[184:187], v[20:23]
	v_mfma_f32_16x16x32_bf16 v[16:19], v[166:169], v[184:187], v[16:19]
	v_mfma_f32_16x16x32_bf16 v[12:15], v[158:161], v[192:195], v[12:15]
	v_mfma_f32_16x16x32_bf16 v[8:11], v[166:169], v[192:195], v[8:11]
	v_mfma_f32_16x16x32_bf16 v[4:7], v[158:161], v[200:203], v[4:7]
	v_mfma_f32_16x16x32_bf16 v[0:3], v[166:169], v[200:203], v[0:3]
	s_barrier
	s_add_i32 s61, 0, 0x18000
	s_add_i32 s62, 0, 0x1c000
	v_add_u32_e32 v150, s61, v170
	v_add_u32_e32 v166, s62, v170
	ds_read_b128 v[128:131], v150
	ds_read_b128 v[132:135], v150 offset:1024
	ds_read_b128 v[146:149], v150 offset:2048
	ds_read_b128 v[150:153], v150 offset:3072
	ds_read_b128 v[154:157], v166
	ds_read_b128 v[158:161], v166 offset:1024
	ds_read_b128 v[162:165], v166 offset:2048
	ds_read_b128 v[166:169], v166 offset:3072
	s_add_u32 s20, s20, 0x10000
	s_addc_u32 s21, s21, 0
	s_mov_b32 m0, s51
	v_lshl_add_u64 v[212:213], s[20:21], 0, v[140:141]
	ds_read_b128 v[172:175], v171 offset:32768
	ds_read_b128 v[176:179], v171 offset:33792
	ds_read_b128 v[180:183], v171 offset:34816
	ds_read_b128 v[184:187], v171 offset:35840
	ds_read_b128 v[188:191], v171 offset:36864
	ds_read_b128 v[192:195], v171 offset:37888
	ds_read_b128 v[196:199], v171 offset:38912
	ds_read_b128 v[200:203], v171 offset:39936
	global_load_lds_dwordx4 v[212:213], off
	s_mov_b32 m0, s52
	v_lshl_add_u64 v[212:213], s[20:21], 0, v[138:139]
	global_load_lds_dwordx4 v[212:213], off
	s_waitcnt vmcnt(8) lgkmcnt(0)
	s_barrier
	v_mfma_f32_16x16x32_bf16 v[120:123], v[128:131], v[172:175], v[120:123]
	v_mfma_f32_16x16x32_bf16 v[124:127], v[146:149], v[172:175], v[124:127]
	v_mfma_f32_16x16x32_bf16 v[116:119], v[128:131], v[180:183], v[116:119]
	v_mfma_f32_16x16x32_bf16 v[112:115], v[146:149], v[180:183], v[112:115]
	v_mfma_f32_16x16x32_bf16 v[108:111], v[128:131], v[188:191], v[108:111]
	v_mfma_f32_16x16x32_bf16 v[104:107], v[146:149], v[188:191], v[104:107]
	v_mfma_f32_16x16x32_bf16 v[100:103], v[128:131], v[196:199], v[100:103]
	v_mfma_f32_16x16x32_bf16 v[96:99], v[146:149], v[196:199], v[96:99]
	v_mfma_f32_16x16x32_bf16 v[120:123], v[132:135], v[176:179], v[120:123]
	v_mfma_f32_16x16x32_bf16 v[124:127], v[150:153], v[176:179], v[124:127]
	v_mfma_f32_16x16x32_bf16 v[116:119], v[132:135], v[184:187], v[116:119]
	v_mfma_f32_16x16x32_bf16 v[112:115], v[150:153], v[184:187], v[112:115]
	v_mfma_f32_16x16x32_bf16 v[108:111], v[132:135], v[192:195], v[108:111]
	v_mfma_f32_16x16x32_bf16 v[104:107], v[150:153], v[192:195], v[104:107]
	v_mfma_f32_16x16x32_bf16 v[100:103], v[132:135], v[200:203], v[100:103]
	v_mfma_f32_16x16x32_bf16 v[96:99], v[150:153], v[200:203], v[96:99]
	v_mfma_f32_16x16x32_bf16 v[60:63], v[154:157], v[172:175], v[60:63]
	v_mfma_f32_16x16x32_bf16 v[56:59], v[162:165], v[172:175], v[56:59]
	v_mfma_f32_16x16x32_bf16 v[52:55], v[154:157], v[180:183], v[52:55]
	v_mfma_f32_16x16x32_bf16 v[48:51], v[162:165], v[180:183], v[48:51]
	v_mfma_f32_16x16x32_bf16 v[44:47], v[154:157], v[188:191], v[44:47]
	v_mfma_f32_16x16x32_bf16 v[40:43], v[162:165], v[188:191], v[40:43]
	v_mfma_f32_16x16x32_bf16 v[36:39], v[154:157], v[196:199], v[36:39]
	v_mfma_f32_16x16x32_bf16 v[32:35], v[162:165], v[196:199], v[32:35]
	v_mfma_f32_16x16x32_bf16 v[60:63], v[158:161], v[176:179], v[60:63]
	v_mfma_f32_16x16x32_bf16 v[56:59], v[166:169], v[176:179], v[56:59]
	v_mfma_f32_16x16x32_bf16 v[52:55], v[158:161], v[184:187], v[52:55]
	v_mfma_f32_16x16x32_bf16 v[48:51], v[166:169], v[184:187], v[48:51]
	v_mfma_f32_16x16x32_bf16 v[44:47], v[158:161], v[192:195], v[44:47]
	v_mfma_f32_16x16x32_bf16 v[40:43], v[166:169], v[192:195], v[40:43]
	v_mfma_f32_16x16x32_bf16 v[36:39], v[158:161], v[200:203], v[36:39]
	v_mfma_f32_16x16x32_bf16 v[32:35], v[166:169], v[200:203], v[32:35]
	s_barrier
	s_add_i32 s20, s61, s35
	v_lshl_add_u64 v[204:205], v[204:205], 0, s[24:25]
	s_mov_b32 m0, s20
	ds_read_b128 v[172:175], v171 offset:49152
	ds_read_b128 v[176:179], v171 offset:50176
	ds_read_b128 v[180:183], v171 offset:51200
	ds_read_b128 v[184:187], v171 offset:52224
	ds_read_b128 v[188:191], v171 offset:53248
	ds_read_b128 v[192:195], v171 offset:54272
	ds_read_b128 v[196:199], v171 offset:55296
	ds_read_b128 v[200:203], v171 offset:56320
	global_load_lds_dwordx4 v[204:205], off
	s_add_i32 m0, s20, 0x2000
	s_add_u32 s8, s8, 0x10080
	v_lshl_add_u64 v[204:205], v[206:207], 0, s[24:25]
	s_addc_u32 s9, s9, 0
	s_add_i32 s20, s62, s35
	global_load_lds_dwordx4 v[204:205], off
	s_mov_b32 m0, s20
	v_lshl_add_u64 v[204:205], s[8:9], 0, v[224:225]
	global_load_lds_dwordx4 v[204:205], off
	s_add_i32 m0, s20, 0x2000
	v_lshl_add_u64 v[204:205], s[8:9], 0, v[136:137]
	global_load_lds_dwordx4 v[204:205], off
	s_mov_b32 m0, s57
	v_lshl_add_u64 v[204:205], v[208:209], 0, s[24:25]
	global_load_lds_dwordx4 v[204:205], off
	s_mov_b32 m0, s58
	v_lshl_add_u64 v[204:205], v[210:211], 0, s[24:25]
	global_load_lds_dwordx4 v[204:205], off
	s_waitcnt vmcnt(8) lgkmcnt(0)
	s_barrier
	v_mfma_f32_16x16x32_bf16 v[92:95], v[128:131], v[172:175], v[92:95]
	v_mfma_f32_16x16x32_bf16 v[88:91], v[146:149], v[172:175], v[88:91]
	v_mfma_f32_16x16x32_bf16 v[84:87], v[128:131], v[180:183], v[84:87]
	v_mfma_f32_16x16x32_bf16 v[80:83], v[146:149], v[180:183], v[80:83]
	v_mfma_f32_16x16x32_bf16 v[76:79], v[128:131], v[188:191], v[76:79]
	v_mfma_f32_16x16x32_bf16 v[72:75], v[146:149], v[188:191], v[72:75]
	v_mfma_f32_16x16x32_bf16 v[68:71], v[128:131], v[196:199], v[68:71]
	v_mfma_f32_16x16x32_bf16 v[64:67], v[146:149], v[196:199], v[64:67]
	v_mfma_f32_16x16x32_bf16 v[92:95], v[132:135], v[176:179], v[92:95]
	v_mfma_f32_16x16x32_bf16 v[88:91], v[150:153], v[176:179], v[88:91]
	v_mfma_f32_16x16x32_bf16 v[84:87], v[132:135], v[184:187], v[84:87]
	v_mfma_f32_16x16x32_bf16 v[80:83], v[150:153], v[184:187], v[80:83]
	v_mfma_f32_16x16x32_bf16 v[76:79], v[132:135], v[192:195], v[76:79]
	v_mfma_f32_16x16x32_bf16 v[72:75], v[150:153], v[192:195], v[72:75]
	v_mfma_f32_16x16x32_bf16 v[68:71], v[132:135], v[200:203], v[68:71]
	v_mfma_f32_16x16x32_bf16 v[64:67], v[150:153], v[200:203], v[64:67]
	v_mfma_f32_16x16x32_bf16 v[28:31], v[154:157], v[172:175], v[28:31]
	v_mfma_f32_16x16x32_bf16 v[24:27], v[162:165], v[172:175], v[24:27]
	v_mfma_f32_16x16x32_bf16 v[20:23], v[154:157], v[180:183], v[20:23]
	v_mfma_f32_16x16x32_bf16 v[16:19], v[162:165], v[180:183], v[16:19]
	v_mfma_f32_16x16x32_bf16 v[12:15], v[154:157], v[188:191], v[12:15]
	v_mfma_f32_16x16x32_bf16 v[8:11], v[162:165], v[188:191], v[8:11]
	v_mfma_f32_16x16x32_bf16 v[4:7], v[154:157], v[196:199], v[4:7]
	v_mfma_f32_16x16x32_bf16 v[0:3], v[162:165], v[196:199], v[0:3]
	v_mfma_f32_16x16x32_bf16 v[28:31], v[158:161], v[176:179], v[28:31]
	v_mfma_f32_16x16x32_bf16 v[24:27], v[166:169], v[176:179], v[24:27]
	v_mfma_f32_16x16x32_bf16 v[20:23], v[158:161], v[184:187], v[20:23]
	v_mfma_f32_16x16x32_bf16 v[16:19], v[166:169], v[184:187], v[16:19]
	v_mfma_f32_16x16x32_bf16 v[12:15], v[158:161], v[192:195], v[12:15]
	v_mfma_f32_16x16x32_bf16 v[8:11], v[166:169], v[192:195], v[8:11]
	v_mfma_f32_16x16x32_bf16 v[4:7], v[158:161], v[200:203], v[4:7]
	v_mfma_f32_16x16x32_bf16 v[0:3], v[166:169], v[200:203], v[0:3]
	s_barrier
	s_add_u32 s12, s12, 0x100
	s_addc_u32 s13, s13, 0
	s_add_u32 s30, s30, 0x100
	s_addc_u32 s31, s31, 0
	s_cmp_ge_i32 s33, s56
	s_mov_b32 s8, s33
	s_cbranch_scc0 .LBB0_920
	v_readlane_b32 s64, v253, 21
	v_readlane_b32 s63, v253, 24
	v_readlane_b32 s65, v253, 22

.LBB0_1111:
	s_and_b64 vcc, exec, s[40:41]
	s_cbranch_vccnz .LBB0_1113
	v_readlane_b32 s8, v252, 34
	s_mov_b32 m0, s8
	v_lshl_add_u64 v[0:1], v[72:73], 0, s[60:61]
	global_load_lds_dwordx4 v[0:1], off

.LBB0_1164:
	s_and_b64 vcc, exec, s[26:27]
	s_cbranch_vccz .LBB0_1166
	s_lshr_b32 s10, s40, 16
	s_mul_i32 s10, s10, 12
	s_sub_i32 s10, s9, s10
	s_and_b32 s40, s10, 0xffff
	s_lshl_b32 s10, s9, 16
	s_lshl_b32 s9, s40, 10
	s_add_i32 s9, s9, 0
	s_waitcnt lgkmcnt(0)
	s_add_i32 m0, s9, 0x21000
	v_lshl_add_u64 v[0:1], v[72:73], 0, s[10:11]
	global_load_lds_dwordx4 v[0:1], off

.LBB0_1169:
	s_and_b64 vcc, exec, s[26:27]
	s_cbranch_vccz .LBB0_1160
	s_mul_i32 s10, s9, 0x1556
	s_lshr_b32 s10, s10, 16
	s_mul_i32 s10, s10, 12
	s_sub_i32 s10, s9, s10
	s_and_b32 s40, s10, 0xffff
	s_lshl_b32 s10, s9, 16
	s_lshl_b32 s9, s40, 10
	s_add_i32 s9, s9, 0
	s_waitcnt lgkmcnt(0)
	s_add_i32 m0, s9, 0x21000
	v_lshl_add_u64 v[0:1], v[72:73], 0, s[10:11]
	global_load_lds_dwordx4 v[0:1], off
	s_branch .LBB0_1160

.LBB0_1313:
	s_add_i32 s56, s8, 2
	s_add_u32 s9, s12, 0xfff80080
	s_addc_u32 s28, s13, -1
	s_add_i32 s57, 0, 0x10000
	s_cmp_eq_u32 s48, s8
	s_cselect_b32 s29, s27, s28
	s_cselect_b32 s28, s35, s9
	v_add_u32_e32 v138, s57, v139
	s_cselect_b32 s9, s52, s55
	s_cselect_b32 s8, s53, s54
	s_add_i32 s60, 0, 0x14000
	ds_read_b128 v[140:143], v138
	ds_read_b128 v[146:149], v138 offset:1024
	ds_read_b128 v[150:153], v138 offset:2048
	ds_read_b128 v[154:157], v138 offset:3072
	v_add_u32_e32 v138, s60, v139
	ds_read_b128 v[158:161], v138
	ds_read_b128 v[162:165], v138 offset:1024
	ds_read_b128 v[166:169], v138 offset:2048
	ds_read_b128 v[170:173], v138 offset:3072
	v_lshl_add_u64 v[206:207], s[12:13], 0, v[134:135]
	s_add_i32 m0, s31, 0xc000
	ds_read_b128 v[174:177], v144
	ds_read_b128 v[178:181], v144 offset:1024
	ds_read_b128 v[182:185], v144 offset:2048
	ds_read_b128 v[186:189], v144 offset:3072
	ds_read_b128 v[190:193], v144 offset:4096
	ds_read_b128 v[194:197], v144 offset:5120
	ds_read_b128 v[198:201], v144 offset:6144
	ds_read_b128 v[202:205], v144 offset:7168
	global_load_lds_dwordx4 v[206:207], off
	s_add_i32 m0, s31, 0xe000
	v_lshl_add_u64 v[206:207], s[12:13], 0, v[136:137]
	global_load_lds_dwordx4 v[206:207], off
	s_waitcnt vmcnt(8) lgkmcnt(0)
	s_barrier
	v_mfma_f32_16x16x32_bf16 v[116:119], v[140:143], v[174:177], v[116:119]
	v_mfma_f32_16x16x32_bf16 v[112:115], v[150:153], v[174:177], v[112:115]
	v_mfma_f32_16x16x32_bf16 v[100:103], v[140:143], v[182:185], v[100:103]
	v_mfma_f32_16x16x32_bf16 v[96:99], v[150:153], v[182:185], v[96:99]
	v_mfma_f32_16x16x32_bf16 v[84:87], v[140:143], v[190:193], v[84:87]
	v_mfma_f32_16x16x32_bf16 v[80:83], v[150:153], v[190:193], v[80:83]
	v_mfma_f32_16x16x32_bf16 v[68:71], v[140:143], v[198:201], v[68:71]
	v_mfma_f32_16x16x32_bf16 v[60:63], v[150:153], v[198:201], v[60:63]
	v_mfma_f32_16x16x32_bf16 v[116:119], v[146:149], v[178:181], v[116:119]
	v_mfma_f32_16x16x32_bf16 v[112:115], v[154:157], v[178:181], v[112:115]
	v_mfma_f32_16x16x32_bf16 v[100:103], v[146:149], v[186:189], v[100:103]
	v_mfma_f32_16x16x32_bf16 v[96:99], v[154:157], v[186:189], v[96:99]
	v_mfma_f32_16x16x32_bf16 v[84:87], v[146:149], v[194:197], v[84:87]
	v_mfma_f32_16x16x32_bf16 v[80:83], v[154:157], v[194:197], v[80:83]
	v_mfma_f32_16x16x32_bf16 v[68:71], v[146:149], v[202:205], v[68:71]
	v_mfma_f32_16x16x32_bf16 v[60:63], v[154:157], v[202:205], v[60:63]
	v_mfma_f32_16x16x32_bf16 v[124:127], v[158:161], v[174:177], v[124:127]
	v_mfma_f32_16x16x32_bf16 v[120:123], v[166:169], v[174:177], v[120:123]
	v_mfma_f32_16x16x32_bf16 v[108:111], v[158:161], v[182:185], v[108:111]
	v_mfma_f32_16x16x32_bf16 v[104:107], v[166:169], v[182:185], v[104:107]
	v_mfma_f32_16x16x32_bf16 v[92:95], v[158:161], v[190:193], v[92:95]
	v_mfma_f32_16x16x32_bf16 v[88:91], v[166:169], v[190:193], v[88:91]
	v_mfma_f32_16x16x32_bf16 v[76:79], v[158:161], v[198:201], v[76:79]
	v_mfma_f32_16x16x32_bf16 v[72:75], v[166:169], v[198:201], v[72:75]
	v_mfma_f32_16x16x32_bf16 v[124:127], v[162:165], v[178:181], v[124:127]
	v_mfma_f32_16x16x32_bf16 v[120:123], v[170:173], v[178:181], v[120:123]
	v_mfma_f32_16x16x32_bf16 v[108:111], v[162:165], v[186:189], v[108:111]
	v_mfma_f32_16x16x32_bf16 v[104:107], v[170:173], v[186:189], v[104:107]
	v_mfma_f32_16x16x32_bf16 v[92:95], v[162:165], v[194:197], v[92:95]
	v_mfma_f32_16x16x32_bf16 v[88:91], v[170:173], v[194:197], v[88:91]
	v_mfma_f32_16x16x32_bf16 v[76:79], v[162:165], v[202:205], v[76:79]
	v_mfma_f32_16x16x32_bf16 v[72:75], v[170:173], v[202:205], v[72:75]
	s_barrier
	s_add_i32 s57, s57, s10
	v_lshl_add_u64 v[206:207], s[8:9], 0, v[224:225]
	s_mov_b32 m0, s57
	ds_read_b128 v[174:177], v144 offset:16384
	ds_read_b128 v[178:181], v144 offset:17408
	ds_read_b128 v[182:185], v144 offset:18432
	ds_read_b128 v[186:189], v144 offset:19456
	ds_read_b128 v[190:193], v144 offset:20480
	ds_read_b128 v[194:197], v144 offset:21504
	ds_read_b128 v[198:201], v144 offset:22528
	ds_read_b128 v[202:205], v144 offset:23552
	global_load_lds_dwordx4 v[206:207], off
	s_add_i32 m0, s57, 0x2000
	s_add_u32 s58, s8, 0x80000
	v_lshl_add_u64 v[208:209], s[8:9], 0, v[128:129]
	s_addc_u32 s59, s9, 0
	s_add_i32 s57, s60, s10
	global_load_lds_dwordx4 v[208:209], off
	v_lshl_add_u64 v[210:211], s[58:59], 0, v[224:225]
	s_mov_b32 m0, s57
	v_lshl_add_u64 v[212:213], s[28:29], 0, v[130:131]
	global_load_lds_dwordx4 v[210:211], off
	s_add_i32 m0, s57, 0x2000
	v_lshl_add_u64 v[210:211], s[58:59], 0, v[128:129]
	global_load_lds_dwordx4 v[210:211], off
	s_mov_b32 m0, s31
	v_lshl_add_u64 v[210:211], s[28:29], 0, v[132:133]
	global_load_lds_dwordx4 v[210:211], off
	s_mov_b32 m0, s33
	s_nop 0
	global_load_lds_dwordx4 v[212:213], off
	s_waitcnt vmcnt(8) lgkmcnt(0)
	s_barrier
	v_mfma_f32_16x16x32_bf16 v[52:55], v[140:143], v[174:177], v[52:55]
	v_mfma_f32_16x16x32_bf16 v[48:51], v[150:153], v[174:177], v[48:51]
	v_mfma_f32_16x16x32_bf16 v[36:39], v[140:143], v[182:185], v[36:39]
	v_mfma_f32_16x16x32_bf16 v[32:35], v[150:153], v[182:185], v[32:35]
	v_mfma_f32_16x16x32_bf16 v[20:23], v[140:143], v[190:193], v[20:23]
	v_mfma_f32_16x16x32_bf16 v[16:19], v[150:153], v[190:193], v[16:19]
	v_mfma_f32_16x16x32_bf16 v[4:7], v[140:143], v[198:201], v[4:7]
	v_mfma_f32_16x16x32_bf16 v[0:3], v[150:153], v[198:201], v[0:3]
	v_mfma_f32_16x16x32_bf16 v[52:55], v[146:149], v[178:181], v[52:55]
	v_mfma_f32_16x16x32_bf16 v[48:51], v[154:157], v[178:181], v[48:51]
	v_mfma_f32_16x16x32_bf16 v[36:39], v[146:149], v[186:189], v[36:39]
	v_mfma_f32_16x16x32_bf16 v[32:35], v[154:157], v[186:189], v[32:35]
	v_mfma_f32_16x16x32_bf16 v[20:23], v[146:149], v[194:197], v[20:23]
	v_mfma_f32_16x16x32_bf16 v[16:19], v[154:157], v[194:197], v[16:19]
	v_mfma_f32_16x16x32_bf16 v[4:7], v[146:149], v[202:205], v[4:7]
	v_mfma_f32_16x16x32_bf16 v[0:3], v[154:157], v[202:205], v[0:3]
	v_mfma_f32_16x16x32_bf16 v[64:67], v[158:161], v[174:177], v[64:67]
	v_mfma_f32_16x16x32_bf16 v[56:59], v[166:169], v[174:177], v[56:59]
	v_mfma_f32_16x16x32_bf16 v[44:47], v[158:161], v[182:185], v[44:47]
	v_mfma_f32_16x16x32_bf16 v[40:43], v[166:169], v[182:185], v[40:43]
	v_mfma_f32_16x16x32_bf16 v[28:31], v[158:161], v[190:193], v[28:31]
	v_mfma_f32_16x16x32_bf16 v[24:27], v[166:169], v[190:193], v[24:27]
	v_mfma_f32_16x16x32_bf16 v[8:11], v[158:161], v[198:201], v[8:11]
	v_mfma_f32_16x16x32_bf16 v[12:15], v[166:169], v[198:201], v[12:15]
	v_mfma_f32_16x16x32_bf16 v[64:67], v[162:165], v[178:181], v[64:67]
	v_mfma_f32_16x16x32_bf16 v[56:59], v[170:173], v[178:181], v[56:59]
	v_mfma_f32_16x16x32_bf16 v[44:47], v[162:165], v[186:189], v[44:47]
	v_mfma_f32_16x16x32_bf16 v[40:43], v[170:173], v[186:189], v[40:43]
	v_mfma_f32_16x16x32_bf16 v[28:31], v[162:165], v[194:197], v[28:31]
	v_mfma_f32_16x16x32_bf16 v[24:27], v[170:173], v[194:197], v[24:27]
	v_mfma_f32_16x16x32_bf16 v[8:11], v[162:165], v[202:205], v[8:11]
	v_mfma_f32_16x16x32_bf16 v[12:15], v[170:173], v[202:205], v[12:15]
	s_barrier
	s_add_i32 s57, 0, 0x18000
	v_add_u32_e32 v138, s57, v139
	s_add_i32 s58, 0, 0x1c000
	ds_read_b128 v[140:143], v138
	ds_read_b128 v[146:149], v138 offset:1024
	ds_read_b128 v[150:153], v138 offset:2048
	ds_read_b128 v[154:157], v138 offset:3072
	v_add_u32_e32 v138, s58, v139
	ds_read_b128 v[158:161], v138
	ds_read_b128 v[162:165], v138 offset:1024
	ds_read_b128 v[166:169], v138 offset:2048
	ds_read_b128 v[170:173], v138 offset:3072
	s_add_u32 s28, s28, 0x80000
	s_addc_u32 s29, s29, 0
	s_mov_b32 m0, s42
	v_lshl_add_u64 v[214:215], s[28:29], 0, v[132:133]
	ds_read_b128 v[174:177], v144 offset:32768
	ds_read_b128 v[178:181], v144 offset:33792
	ds_read_b128 v[182:185], v144 offset:34816
	ds_read_b128 v[186:189], v144 offset:35840
	ds_read_b128 v[190:193], v144 offset:36864
	ds_read_b128 v[194:197], v144 offset:37888
	ds_read_b128 v[198:201], v144 offset:38912
	ds_read_b128 v[202:205], v144 offset:39936
	global_load_lds_dwordx4 v[214:215], off
	s_mov_b32 m0, s43
	v_lshl_add_u64 v[214:215], s[28:29], 0, v[130:131]
	global_load_lds_dwordx4 v[214:215], off
	s_waitcnt vmcnt(8) lgkmcnt(0)
	s_barrier
	v_mfma_f32_16x16x32_bf16 v[116:119], v[140:143], v[174:177], v[116:119]
	v_mfma_f32_16x16x32_bf16 v[112:115], v[150:153], v[174:177], v[112:115]
	v_mfma_f32_16x16x32_bf16 v[100:103], v[140:143], v[182:185], v[100:103]
	v_mfma_f32_16x16x32_bf16 v[96:99], v[150:153], v[182:185], v[96:99]
	v_mfma_f32_16x16x32_bf16 v[84:87], v[140:143], v[190:193], v[84:87]
	v_mfma_f32_16x16x32_bf16 v[80:83], v[150:153], v[190:193], v[80:83]
	v_mfma_f32_16x16x32_bf16 v[68:71], v[140:143], v[198:201], v[68:71]
	v_mfma_f32_16x16x32_bf16 v[60:63], v[150:153], v[198:201], v[60:63]
	v_mfma_f32_16x16x32_bf16 v[116:119], v[146:149], v[178:181], v[116:119]
	v_mfma_f32_16x16x32_bf16 v[112:115], v[154:157], v[178:181], v[112:115]
	v_mfma_f32_16x16x32_bf16 v[100:103], v[146:149], v[186:189], v[100:103]
	v_mfma_f32_16x16x32_bf16 v[96:99], v[154:157], v[186:189], v[96:99]
	v_mfma_f32_16x16x32_bf16 v[84:87], v[146:149], v[194:197], v[84:87]
	v_mfma_f32_16x16x32_bf16 v[80:83], v[154:157], v[194:197], v[80:83]
	v_mfma_f32_16x16x32_bf16 v[68:71], v[146:149], v[202:205], v[68:71]
	v_mfma_f32_16x16x32_bf16 v[60:63], v[154:157], v[202:205], v[60:63]
	v_mfma_f32_16x16x32_bf16 v[124:127], v[158:161], v[174:177], v[124:127]
	v_mfma_f32_16x16x32_bf16 v[120:123], v[166:169], v[174:177], v[120:123]
	v_mfma_f32_16x16x32_bf16 v[108:111], v[158:161], v[182:185], v[108:111]
	v_mfma_f32_16x16x32_bf16 v[104:107], v[166:169], v[182:185], v[104:107]
	v_mfma_f32_16x16x32_bf16 v[92:95], v[158:161], v[190:193], v[92:95]
	v_mfma_f32_16x16x32_bf16 v[88:91], v[166:169], v[190:193], v[88:91]
	v_mfma_f32_16x16x32_bf16 v[76:79], v[158:161], v[198:201], v[76:79]
	v_mfma_f32_16x16x32_bf16 v[72:75], v[166:169], v[198:201], v[72:75]
	v_mfma_f32_16x16x32_bf16 v[124:127], v[162:165], v[178:181], v[124:127]
	v_mfma_f32_16x16x32_bf16 v[120:123], v[170:173], v[178:181], v[120:123]
	v_mfma_f32_16x16x32_bf16 v[108:111], v[162:165], v[186:189], v[108:111]
	v_mfma_f32_16x16x32_bf16 v[104:107], v[170:173], v[186:189], v[104:107]
	v_mfma_f32_16x16x32_bf16 v[92:95], v[162:165], v[194:197], v[92:95]
	v_mfma_f32_16x16x32_bf16 v[88:91], v[170:173], v[194:197], v[88:91]
	v_mfma_f32_16x16x32_bf16 v[76:79], v[162:165], v[202:205], v[76:79]
	v_mfma_f32_16x16x32_bf16 v[72:75], v[170:173], v[202:205], v[72:75]
	s_barrier
	s_add_i32 s28, s57, s10
	v_lshl_add_u64 v[206:207], v[206:207], 0, s[24:25]
	s_mov_b32 m0, s28
	ds_read_b128 v[174:177], v144 offset:49152
	ds_read_b128 v[178:181], v144 offset:50176
	ds_read_b128 v[182:185], v144 offset:51200
	ds_read_b128 v[186:189], v144 offset:52224
	ds_read_b128 v[190:193], v144 offset:53248
	ds_read_b128 v[194:197], v144 offset:54272
	ds_read_b128 v[198:201], v144 offset:55296
	ds_read_b128 v[202:205], v144 offset:56320
	global_load_lds_dwordx4 v[206:207], off
	s_add_i32 m0, s28, 0x2000
	s_add_u32 s8, s8, 0x80080
	v_lshl_add_u64 v[206:207], v[208:209], 0, s[24:25]
	s_addc_u32 s9, s9, 0
	s_add_i32 s28, s58, s10
	global_load_lds_dwordx4 v[206:207], off
	s_mov_b32 m0, s28
	v_lshl_add_u64 v[206:207], s[8:9], 0, v[224:225]
	global_load_lds_dwordx4 v[206:207], off
	s_add_i32 m0, s28, 0x2000
	v_lshl_add_u64 v[206:207], s[8:9], 0, v[128:129]
	global_load_lds_dwordx4 v[206:207], off
	s_mov_b32 m0, s46
	v_lshl_add_u64 v[206:207], v[210:211], 0, s[24:25]
	global_load_lds_dwordx4 v[206:207], off
	s_mov_b32 m0, s47
	v_lshl_add_u64 v[206:207], v[212:213], 0, s[24:25]
	global_load_lds_dwordx4 v[206:207], off
	s_waitcnt vmcnt(8) lgkmcnt(0)
	s_barrier
	v_mfma_f32_16x16x32_bf16 v[52:55], v[140:143], v[174:177], v[52:55]
	v_mfma_f32_16x16x32_bf16 v[48:51], v[150:153], v[174:177], v[48:51]
	v_mfma_f32_16x16x32_bf16 v[36:39], v[140:143], v[182:185], v[36:39]
	v_mfma_f32_16x16x32_bf16 v[32:35], v[150:153], v[182:185], v[32:35]
	v_mfma_f32_16x16x32_bf16 v[20:23], v[140:143], v[190:193], v[20:23]
	v_mfma_f32_16x16x32_bf16 v[16:19], v[150:153], v[190:193], v[16:19]
	v_mfma_f32_16x16x32_bf16 v[4:7], v[140:143], v[198:201], v[4:7]
	v_mfma_f32_16x16x32_bf16 v[0:3], v[150:153], v[198:201], v[0:3]
	v_mfma_f32_16x16x32_bf16 v[52:55], v[146:149], v[178:181], v[52:55]
	v_mfma_f32_16x16x32_bf16 v[48:51], v[154:157], v[178:181], v[48:51]
	v_mfma_f32_16x16x32_bf16 v[36:39], v[146:149], v[186:189], v[36:39]
	v_mfma_f32_16x16x32_bf16 v[32:35], v[154:157], v[186:189], v[32:35]
	v_mfma_f32_16x16x32_bf16 v[20:23], v[146:149], v[194:197], v[20:23]
	v_mfma_f32_16x16x32_bf16 v[16:19], v[154:157], v[194:197], v[16:19]
	v_mfma_f32_16x16x32_bf16 v[4:7], v[146:149], v[202:205], v[4:7]
	v_mfma_f32_16x16x32_bf16 v[0:3], v[154:157], v[202:205], v[0:3]
	v_mfma_f32_16x16x32_bf16 v[64:67], v[158:161], v[174:177], v[64:67]
	v_mfma_f32_16x16x32_bf16 v[56:59], v[166:169], v[174:177], v[56:59]
	v_mfma_f32_16x16x32_bf16 v[44:47], v[158:161], v[182:185], v[44:47]
	v_mfma_f32_16x16x32_bf16 v[40:43], v[166:169], v[182:185], v[40:43]
	v_mfma_f32_16x16x32_bf16 v[28:31], v[158:161], v[190:193], v[28:31]
	v_mfma_f32_16x16x32_bf16 v[24:27], v[166:169], v[190:193], v[24:27]
	v_mfma_f32_16x16x32_bf16 v[8:11], v[158:161], v[198:201], v[8:11]
	v_mfma_f32_16x16x32_bf16 v[12:15], v[166:169], v[198:201], v[12:15]
	v_mfma_f32_16x16x32_bf16 v[64:67], v[162:165], v[178:181], v[64:67]
	v_mfma_f32_16x16x32_bf16 v[56:59], v[170:173], v[178:181], v[56:59]
	v_mfma_f32_16x16x32_bf16 v[44:47], v[162:165], v[186:189], v[44:47]
	v_mfma_f32_16x16x32_bf16 v[40:43], v[170:173], v[186:189], v[40:43]
	v_mfma_f32_16x16x32_bf16 v[28:31], v[162:165], v[194:197], v[28:31]
	v_mfma_f32_16x16x32_bf16 v[24:27], v[170:173], v[194:197], v[24:27]
	v_mfma_f32_16x16x32_bf16 v[8:11], v[162:165], v[202:205], v[8:11]
	v_mfma_f32_16x16x32_bf16 v[12:15], v[170:173], v[202:205], v[12:15]
	s_barrier
	s_add_u32 s12, s12, 0x100
	s_addc_u32 s13, s13, 0
	s_add_u32 s54, s54, 0x100
	s_addc_u32 s55, s55, 0
	s_cmp_ge_i32 s56, s45
	s_mov_b32 s8, s56
	s_cbranch_scc0 .LBB0_1313
	s_mov_b32 s53, 0x5040100
	s_mov_b64 s[56:57], 0x400000
	s_mov_b64 s[58:59], 0x3fffff
	s_mov_b64 s[60:61], 0x20000

.LBB0_1626:
	s_add_i32 s33, s8, 2
	s_add_u32 s9, s12, 0xfff80080
	s_addc_u32 s28, s13, -1
	s_add_i32 s40, 0, 0x10000
	s_cmp_eq_u32 s68, s8
	s_cselect_b32 s29, s3, s28
	s_cselect_b32 s28, s7, s9
	s_cselect_b32 s9, s10, s31
	s_cselect_b32 s8, s21, s30
	s_add_i32 s43, 0, 0x14000
	v_add_u32_e32 v140, s40, v200
	v_add_u32_e32 v156, s43, v200
	ds_read_b128 v[128:131], v140
	ds_read_b128 v[132:135], v140 offset:1024
	ds_read_b128 v[136:139], v140 offset:2048
	ds_read_b128 v[140:143], v140 offset:3072
	ds_read_b128 v[144:147], v156
	ds_read_b128 v[148:151], v156 offset:1024
	ds_read_b128 v[152:155], v156 offset:2048
	ds_read_b128 v[156:159], v156 offset:3072
	v_lshl_add_u64 v[206:207], s[12:13], 0, v[184:185]
	s_add_i32 m0, s56, 0xc000
	ds_read_b128 v[160:163], v201
	ds_read_b128 v[164:167], v201 offset:1024
	ds_read_b128 v[168:171], v201 offset:2048
	ds_read_b128 v[172:175], v201 offset:3072
	ds_read_b128 v[188:191], v201 offset:4096
	ds_read_b128 v[192:195], v201 offset:5120
	ds_read_b128 v[196:199], v201 offset:6144
	ds_read_b128 v[202:205], v201 offset:7168
	global_load_lds_dwordx4 v[206:207], off
	s_add_i32 m0, s56, 0xe000
	v_lshl_add_u64 v[206:207], s[12:13], 0, v[186:187]
	global_load_lds_dwordx4 v[206:207], off
	s_waitcnt vmcnt(8) lgkmcnt(0)
	s_barrier
	v_mfma_f32_16x16x32_bf16 v[112:115], v[128:131], v[160:163], v[112:115]
	v_mfma_f32_16x16x32_bf16 v[116:119], v[136:139], v[160:163], v[116:119]
	v_mfma_f32_16x16x32_bf16 v[100:103], v[128:131], v[168:171], v[100:103]
	v_mfma_f32_16x16x32_bf16 v[96:99], v[136:139], v[168:171], v[96:99]
	v_mfma_f32_16x16x32_bf16 v[84:87], v[128:131], v[188:191], v[84:87]
	v_mfma_f32_16x16x32_bf16 v[80:83], v[136:139], v[188:191], v[80:83]
	v_mfma_f32_16x16x32_bf16 v[68:71], v[128:131], v[196:199], v[68:71]
	v_mfma_f32_16x16x32_bf16 v[64:67], v[136:139], v[196:199], v[64:67]
	v_mfma_f32_16x16x32_bf16 v[112:115], v[132:135], v[164:167], v[112:115]
	v_mfma_f32_16x16x32_bf16 v[116:119], v[140:143], v[164:167], v[116:119]
	v_mfma_f32_16x16x32_bf16 v[100:103], v[132:135], v[172:175], v[100:103]
	v_mfma_f32_16x16x32_bf16 v[96:99], v[140:143], v[172:175], v[96:99]
	v_mfma_f32_16x16x32_bf16 v[84:87], v[132:135], v[192:195], v[84:87]
	v_mfma_f32_16x16x32_bf16 v[80:83], v[140:143], v[192:195], v[80:83]
	v_mfma_f32_16x16x32_bf16 v[68:71], v[132:135], v[202:205], v[68:71]
	v_mfma_f32_16x16x32_bf16 v[64:67], v[140:143], v[202:205], v[64:67]
	v_mfma_f32_16x16x32_bf16 v[120:123], v[144:147], v[160:163], v[120:123]
	v_mfma_f32_16x16x32_bf16 v[124:127], v[152:155], v[160:163], v[124:127]
	v_mfma_f32_16x16x32_bf16 v[108:111], v[144:147], v[168:171], v[108:111]
	v_mfma_f32_16x16x32_bf16 v[104:107], v[152:155], v[168:171], v[104:107]
	v_mfma_f32_16x16x32_bf16 v[92:95], v[144:147], v[188:191], v[92:95]
	v_mfma_f32_16x16x32_bf16 v[88:91], v[152:155], v[188:191], v[88:91]
	v_mfma_f32_16x16x32_bf16 v[76:79], v[144:147], v[196:199], v[76:79]
	v_mfma_f32_16x16x32_bf16 v[72:75], v[152:155], v[196:199], v[72:75]
	v_mfma_f32_16x16x32_bf16 v[120:123], v[148:151], v[164:167], v[120:123]
	v_mfma_f32_16x16x32_bf16 v[124:127], v[156:159], v[164:167], v[124:127]
	v_mfma_f32_16x16x32_bf16 v[108:111], v[148:151], v[172:175], v[108:111]
	v_mfma_f32_16x16x32_bf16 v[104:107], v[156:159], v[172:175], v[104:107]
	v_mfma_f32_16x16x32_bf16 v[92:95], v[148:151], v[192:195], v[92:95]
	v_mfma_f32_16x16x32_bf16 v[88:91], v[156:159], v[192:195], v[88:91]
	v_mfma_f32_16x16x32_bf16 v[76:79], v[148:151], v[202:205], v[76:79]
	v_mfma_f32_16x16x32_bf16 v[72:75], v[156:159], v[202:205], v[72:75]
	s_barrier
	s_add_i32 s40, s40, s54
	v_lshl_add_u64 v[206:207], s[8:9], 0, v[180:181]
	s_mov_b32 m0, s40
	ds_read_b128 v[160:163], v201 offset:16384
	ds_read_b128 v[164:167], v201 offset:17408
	ds_read_b128 v[168:171], v201 offset:18432
	ds_read_b128 v[172:175], v201 offset:19456
	ds_read_b128 v[188:191], v201 offset:20480
	ds_read_b128 v[192:195], v201 offset:21504
	ds_read_b128 v[196:199], v201 offset:22528
	ds_read_b128 v[202:205], v201 offset:23552
	global_load_lds_dwordx4 v[206:207], off
	s_add_i32 m0, s40, 0x2000
	s_add_u32 s40, s8, 0x80000
	v_lshl_add_u64 v[208:209], s[8:9], 0, v[176:177]
	s_addc_u32 s41, s9, 0
	s_add_i32 s43, s43, s54
	global_load_lds_dwordx4 v[208:209], off
	v_lshl_add_u64 v[210:211], s[40:41], 0, v[180:181]
	s_mov_b32 m0, s43
	v_lshl_add_u64 v[212:213], s[28:29], 0, v[178:179]
	global_load_lds_dwordx4 v[210:211], off
	s_add_i32 m0, s43, 0x2000
	v_lshl_add_u64 v[210:211], s[40:41], 0, v[176:177]
	global_load_lds_dwordx4 v[210:211], off
	s_mov_b32 m0, s56
	v_lshl_add_u64 v[210:211], s[28:29], 0, v[182:183]
	global_load_lds_dwordx4 v[210:211], off
	s_mov_b32 m0, s57
	s_nop 0
	global_load_lds_dwordx4 v[212:213], off
	s_waitcnt vmcnt(8) lgkmcnt(0)
	s_barrier
	v_mfma_f32_16x16x32_bf16 v[52:55], v[128:131], v[160:163], v[52:55]
	v_mfma_f32_16x16x32_bf16 v[48:51], v[136:139], v[160:163], v[48:51]
	v_mfma_f32_16x16x32_bf16 v[36:39], v[128:131], v[168:171], v[36:39]
	v_mfma_f32_16x16x32_bf16 v[32:35], v[136:139], v[168:171], v[32:35]
	v_mfma_f32_16x16x32_bf16 v[20:23], v[128:131], v[188:191], v[20:23]
	v_mfma_f32_16x16x32_bf16 v[16:19], v[136:139], v[188:191], v[16:19]
	v_mfma_f32_16x16x32_bf16 v[4:7], v[128:131], v[196:199], v[4:7]
	v_mfma_f32_16x16x32_bf16 v[0:3], v[136:139], v[196:199], v[0:3]
	v_mfma_f32_16x16x32_bf16 v[52:55], v[132:135], v[164:167], v[52:55]
	v_mfma_f32_16x16x32_bf16 v[48:51], v[140:143], v[164:167], v[48:51]
	v_mfma_f32_16x16x32_bf16 v[36:39], v[132:135], v[172:175], v[36:39]
	v_mfma_f32_16x16x32_bf16 v[32:35], v[140:143], v[172:175], v[32:35]
	v_mfma_f32_16x16x32_bf16 v[20:23], v[132:135], v[192:195], v[20:23]
	v_mfma_f32_16x16x32_bf16 v[16:19], v[140:143], v[192:195], v[16:19]
	v_mfma_f32_16x16x32_bf16 v[4:7], v[132:135], v[202:205], v[4:7]
	v_mfma_f32_16x16x32_bf16 v[0:3], v[140:143], v[202:205], v[0:3]
	v_mfma_f32_16x16x32_bf16 v[60:63], v[144:147], v[160:163], v[60:63]
	v_mfma_f32_16x16x32_bf16 v[56:59], v[152:155], v[160:163], v[56:59]
	v_mfma_f32_16x16x32_bf16 v[44:47], v[144:147], v[168:171], v[44:47]
	v_mfma_f32_16x16x32_bf16 v[40:43], v[152:155], v[168:171], v[40:43]
	v_mfma_f32_16x16x32_bf16 v[28:31], v[144:147], v[188:191], v[28:31]
	v_mfma_f32_16x16x32_bf16 v[24:27], v[152:155], v[188:191], v[24:27]
	v_mfma_f32_16x16x32_bf16 v[8:11], v[144:147], v[196:199], v[8:11]
	v_mfma_f32_16x16x32_bf16 v[12:15], v[152:155], v[196:199], v[12:15]
	v_mfma_f32_16x16x32_bf16 v[60:63], v[148:151], v[164:167], v[60:63]
	v_mfma_f32_16x16x32_bf16 v[56:59], v[156:159], v[164:167], v[56:59]
	v_mfma_f32_16x16x32_bf16 v[44:47], v[148:151], v[172:175], v[44:47]
	v_mfma_f32_16x16x32_bf16 v[40:43], v[156:159], v[172:175], v[40:43]
	v_mfma_f32_16x16x32_bf16 v[28:31], v[148:151], v[192:195], v[28:31]
	v_mfma_f32_16x16x32_bf16 v[24:27], v[156:159], v[192:195], v[24:27]
	v_mfma_f32_16x16x32_bf16 v[8:11], v[148:151], v[202:205], v[8:11]
	v_mfma_f32_16x16x32_bf16 v[12:15], v[156:159], v[202:205], v[12:15]
	s_barrier
	s_add_i32 s40, 0, 0x18000
	s_add_i32 s41, 0, 0x1c000
	v_add_u32_e32 v140, s40, v200
	v_add_u32_e32 v156, s41, v200
	ds_read_b128 v[128:131], v140
	ds_read_b128 v[132:135], v140 offset:1024
	ds_read_b128 v[136:139], v140 offset:2048
	ds_read_b128 v[140:143], v140 offset:3072
	ds_read_b128 v[144:147], v156
	ds_read_b128 v[148:151], v156 offset:1024
	ds_read_b128 v[152:155], v156 offset:2048
	ds_read_b128 v[156:159], v156 offset:3072
	s_add_u32 s28, s28, 0x80000
	s_addc_u32 s29, s29, 0
	s_mov_b32 m0, s58
	v_lshl_add_u64 v[214:215], s[28:29], 0, v[182:183]
	ds_read_b128 v[160:163], v201 offset:32768
	ds_read_b128 v[164:167], v201 offset:33792
	ds_read_b128 v[168:171], v201 offset:34816
	ds_read_b128 v[172:175], v201 offset:35840
	ds_read_b128 v[188:191], v201 offset:36864
	ds_read_b128 v[192:195], v201 offset:37888
	ds_read_b128 v[196:199], v201 offset:38912
	ds_read_b128 v[202:205], v201 offset:39936
	global_load_lds_dwordx4 v[214:215], off
	s_mov_b32 m0, s59
	v_lshl_add_u64 v[214:215], s[28:29], 0, v[178:179]
	global_load_lds_dwordx4 v[214:215], off
	s_waitcnt vmcnt(8) lgkmcnt(0)
	s_barrier
	v_mfma_f32_16x16x32_bf16 v[112:115], v[128:131], v[160:163], v[112:115]
	v_mfma_f32_16x16x32_bf16 v[116:119], v[136:139], v[160:163], v[116:119]
	v_mfma_f32_16x16x32_bf16 v[100:103], v[128:131], v[168:171], v[100:103]
	v_mfma_f32_16x16x32_bf16 v[96:99], v[136:139], v[168:171], v[96:99]
	v_mfma_f32_16x16x32_bf16 v[84:87], v[128:131], v[188:191], v[84:87]
	v_mfma_f32_16x16x32_bf16 v[80:83], v[136:139], v[188:191], v[80:83]
	v_mfma_f32_16x16x32_bf16 v[68:71], v[128:131], v[196:199], v[68:71]
	v_mfma_f32_16x16x32_bf16 v[64:67], v[136:139], v[196:199], v[64:67]
	v_mfma_f32_16x16x32_bf16 v[112:115], v[132:135], v[164:167], v[112:115]
	v_mfma_f32_16x16x32_bf16 v[116:119], v[140:143], v[164:167], v[116:119]
	v_mfma_f32_16x16x32_bf16 v[100:103], v[132:135], v[172:175], v[100:103]
	v_mfma_f32_16x16x32_bf16 v[96:99], v[140:143], v[172:175], v[96:99]
	v_mfma_f32_16x16x32_bf16 v[84:87], v[132:135], v[192:195], v[84:87]
	v_mfma_f32_16x16x32_bf16 v[80:83], v[140:143], v[192:195], v[80:83]
	v_mfma_f32_16x16x32_bf16 v[68:71], v[132:135], v[202:205], v[68:71]
	v_mfma_f32_16x16x32_bf16 v[64:67], v[140:143], v[202:205], v[64:67]
	v_mfma_f32_16x16x32_bf16 v[120:123], v[144:147], v[160:163], v[120:123]
	v_mfma_f32_16x16x32_bf16 v[124:127], v[152:155], v[160:163], v[124:127]
	v_mfma_f32_16x16x32_bf16 v[108:111], v[144:147], v[168:171], v[108:111]
	v_mfma_f32_16x16x32_bf16 v[104:107], v[152:155], v[168:171], v[104:107]
	v_mfma_f32_16x16x32_bf16 v[92:95], v[144:147], v[188:191], v[92:95]
	v_mfma_f32_16x16x32_bf16 v[88:91], v[152:155], v[188:191], v[88:91]
	v_mfma_f32_16x16x32_bf16 v[76:79], v[144:147], v[196:199], v[76:79]
	v_mfma_f32_16x16x32_bf16 v[72:75], v[152:155], v[196:199], v[72:75]
	v_mfma_f32_16x16x32_bf16 v[120:123], v[148:151], v[164:167], v[120:123]
	v_mfma_f32_16x16x32_bf16 v[124:127], v[156:159], v[164:167], v[124:127]
	v_mfma_f32_16x16x32_bf16 v[108:111], v[148:151], v[172:175], v[108:111]
	v_mfma_f32_16x16x32_bf16 v[104:107], v[156:159], v[172:175], v[104:107]
	v_mfma_f32_16x16x32_bf16 v[92:95], v[148:151], v[192:195], v[92:95]
	v_mfma_f32_16x16x32_bf16 v[88:91], v[156:159], v[192:195], v[88:91]
	v_mfma_f32_16x16x32_bf16 v[76:79], v[148:151], v[202:205], v[76:79]
	v_mfma_f32_16x16x32_bf16 v[72:75], v[156:159], v[202:205], v[72:75]
	s_barrier
	s_add_i32 s28, s40, s54
	v_lshl_add_u64 v[206:207], v[206:207], 0, s[24:25]
	s_mov_b32 m0, s28
	ds_read_b128 v[160:163], v201 offset:49152
	ds_read_b128 v[164:167], v201 offset:50176
	ds_read_b128 v[168:171], v201 offset:51200
	ds_read_b128 v[172:175], v201 offset:52224
	ds_read_b128 v[188:191], v201 offset:53248
	ds_read_b128 v[192:195], v201 offset:54272
	ds_read_b128 v[196:199], v201 offset:55296
	ds_read_b128 v[202:205], v201 offset:56320
	global_load_lds_dwordx4 v[206:207], off
	s_add_i32 m0, s28, 0x2000
	s_add_u32 s8, s8, 0x80080
	v_lshl_add_u64 v[206:207], v[208:209], 0, s[24:25]
	s_addc_u32 s9, s9, 0
	s_add_i32 s28, s41, s54
	global_load_lds_dwordx4 v[206:207], off
	s_mov_b32 m0, s28
	v_lshl_add_u64 v[206:207], s[8:9], 0, v[180:181]
	global_load_lds_dwordx4 v[206:207], off
	s_add_i32 m0, s28, 0x2000
	v_lshl_add_u64 v[206:207], s[8:9], 0, v[176:177]
	global_load_lds_dwordx4 v[206:207], off
	s_mov_b32 m0, s66
	v_lshl_add_u64 v[206:207], v[210:211], 0, s[24:25]
	global_load_lds_dwordx4 v[206:207], off
	s_mov_b32 m0, s67
	v_lshl_add_u64 v[206:207], v[212:213], 0, s[24:25]
	global_load_lds_dwordx4 v[206:207], off
	s_waitcnt vmcnt(8) lgkmcnt(0)
	s_barrier
	v_mfma_f32_16x16x32_bf16 v[52:55], v[128:131], v[160:163], v[52:55]
	v_mfma_f32_16x16x32_bf16 v[48:51], v[136:139], v[160:163], v[48:51]
	v_mfma_f32_16x16x32_bf16 v[36:39], v[128:131], v[168:171], v[36:39]
	v_mfma_f32_16x16x32_bf16 v[32:35], v[136:139], v[168:171], v[32:35]
	v_mfma_f32_16x16x32_bf16 v[20:23], v[128:131], v[188:191], v[20:23]
	v_mfma_f32_16x16x32_bf16 v[16:19], v[136:139], v[188:191], v[16:19]
	v_mfma_f32_16x16x32_bf16 v[4:7], v[128:131], v[196:199], v[4:7]
	v_mfma_f32_16x16x32_bf16 v[0:3], v[136:139], v[196:199], v[0:3]
	v_mfma_f32_16x16x32_bf16 v[52:55], v[132:135], v[164:167], v[52:55]
	v_mfma_f32_16x16x32_bf16 v[48:51], v[140:143], v[164:167], v[48:51]
	v_mfma_f32_16x16x32_bf16 v[36:39], v[132:135], v[172:175], v[36:39]
	v_mfma_f32_16x16x32_bf16 v[32:35], v[140:143], v[172:175], v[32:35]
	v_mfma_f32_16x16x32_bf16 v[20:23], v[132:135], v[192:195], v[20:23]
	v_mfma_f32_16x16x32_bf16 v[16:19], v[140:143], v[192:195], v[16:19]
	v_mfma_f32_16x16x32_bf16 v[4:7], v[132:135], v[202:205], v[4:7]
	v_mfma_f32_16x16x32_bf16 v[0:3], v[140:143], v[202:205], v[0:3]
	v_mfma_f32_16x16x32_bf16 v[60:63], v[144:147], v[160:163], v[60:63]
	v_mfma_f32_16x16x32_bf16 v[56:59], v[152:155], v[160:163], v[56:59]
	v_mfma_f32_16x16x32_bf16 v[44:47], v[144:147], v[168:171], v[44:47]
	v_mfma_f32_16x16x32_bf16 v[40:43], v[152:155], v[168:171], v[40:43]
	v_mfma_f32_16x16x32_bf16 v[28:31], v[144:147], v[188:191], v[28:31]
	v_mfma_f32_16x16x32_bf16 v[24:27], v[152:155], v[188:191], v[24:27]
	v_mfma_f32_16x16x32_bf16 v[8:11], v[144:147], v[196:199], v[8:11]
	v_mfma_f32_16x16x32_bf16 v[12:15], v[152:155], v[196:199], v[12:15]
	v_mfma_f32_16x16x32_bf16 v[60:63], v[148:151], v[164:167], v[60:63]
	v_mfma_f32_16x16x32_bf16 v[56:59], v[156:159], v[164:167], v[56:59]
	v_mfma_f32_16x16x32_bf16 v[44:47], v[148:151], v[172:175], v[44:47]
	v_mfma_f32_16x16x32_bf16 v[40:43], v[156:159], v[172:175], v[40:43]
	v_mfma_f32_16x16x32_bf16 v[28:31], v[148:151], v[192:195], v[28:31]
	v_mfma_f32_16x16x32_bf16 v[24:27], v[156:159], v[192:195], v[24:27]
	v_mfma_f32_16x16x32_bf16 v[8:11], v[148:151], v[202:205], v[8:11]
	v_mfma_f32_16x16x32_bf16 v[12:15], v[156:159], v[202:205], v[12:15]
	s_barrier
	s_add_u32 s12, s12, 0x100
	s_addc_u32 s13, s13, 0
	s_add_u32 s30, s30, 0x100
	s_addc_u32 s31, s31, 0
	s_cmp_ge_i32 s33, s65
	s_mov_b32 s8, s33
	s_cbranch_scc0 .LBB0_1626

.LBB0_1667:
	s_add_i32 s56, s8, 2
	s_add_u32 s9, s12, 0xfff80080
	s_addc_u32 s28, s13, -1
	s_add_i32 s57, 0, 0x10000
	s_cmp_eq_u32 s48, s8
	s_cselect_b32 s29, s27, s28
	s_cselect_b32 s28, s35, s9
	s_cselect_b32 s9, s52, s55
	s_cselect_b32 s8, s53, s54
	s_add_i32 s60, 0, 0x14000
	v_add_u32_e32 v152, s57, v138
	v_add_u32_e32 v168, s60, v138
	ds_read_b128 v[140:143], v152
	ds_read_b128 v[144:147], v152 offset:1024
	ds_read_b128 v[148:151], v152 offset:2048
	ds_read_b128 v[152:155], v152 offset:3072
	ds_read_b128 v[156:159], v168
	ds_read_b128 v[160:163], v168 offset:1024
	ds_read_b128 v[164:167], v168 offset:2048
	ds_read_b128 v[168:171], v168 offset:3072
	v_lshl_add_u64 v[204:205], s[12:13], 0, v[134:135]
	s_add_i32 m0, s31, 0xc000
	ds_read_b128 v[172:175], v139
	ds_read_b128 v[176:179], v139 offset:1024
	ds_read_b128 v[180:183], v139 offset:2048
	ds_read_b128 v[184:187], v139 offset:3072
	ds_read_b128 v[188:191], v139 offset:4096
	ds_read_b128 v[192:195], v139 offset:5120
	ds_read_b128 v[196:199], v139 offset:6144
	ds_read_b128 v[200:203], v139 offset:7168
	global_load_lds_dwordx4 v[204:205], off
	s_add_i32 m0, s31, 0xe000
	v_lshl_add_u64 v[204:205], s[12:13], 0, v[136:137]
	global_load_lds_dwordx4 v[204:205], off
	s_waitcnt vmcnt(8) lgkmcnt(0)
	s_barrier
	v_mfma_f32_16x16x32_bf16 v[112:115], v[140:143], v[172:175], v[112:115]
	v_mfma_f32_16x16x32_bf16 v[116:119], v[148:151], v[172:175], v[116:119]
	v_mfma_f32_16x16x32_bf16 v[96:99], v[140:143], v[180:183], v[96:99]
	v_mfma_f32_16x16x32_bf16 v[100:103], v[148:151], v[180:183], v[100:103]
	v_mfma_f32_16x16x32_bf16 v[80:83], v[140:143], v[188:191], v[80:83]
	v_mfma_f32_16x16x32_bf16 v[84:87], v[148:151], v[188:191], v[84:87]
	v_mfma_f32_16x16x32_bf16 v[48:51], v[140:143], v[196:199], v[48:51]
	v_mfma_f32_16x16x32_bf16 v[52:55], v[148:151], v[196:199], v[52:55]
	v_mfma_f32_16x16x32_bf16 v[112:115], v[144:147], v[176:179], v[112:115]
	v_mfma_f32_16x16x32_bf16 v[116:119], v[152:155], v[176:179], v[116:119]
	v_mfma_f32_16x16x32_bf16 v[96:99], v[144:147], v[184:187], v[96:99]
	v_mfma_f32_16x16x32_bf16 v[100:103], v[152:155], v[184:187], v[100:103]
	v_mfma_f32_16x16x32_bf16 v[80:83], v[144:147], v[192:195], v[80:83]
	v_mfma_f32_16x16x32_bf16 v[84:87], v[152:155], v[192:195], v[84:87]
	v_mfma_f32_16x16x32_bf16 v[48:51], v[144:147], v[200:203], v[48:51]
	v_mfma_f32_16x16x32_bf16 v[52:55], v[152:155], v[200:203], v[52:55]
	v_mfma_f32_16x16x32_bf16 v[120:123], v[156:159], v[172:175], v[120:123]
	v_mfma_f32_16x16x32_bf16 v[124:127], v[164:167], v[172:175], v[124:127]
	v_mfma_f32_16x16x32_bf16 v[104:107], v[156:159], v[180:183], v[104:107]
	v_mfma_f32_16x16x32_bf16 v[108:111], v[164:167], v[180:183], v[108:111]
	v_mfma_f32_16x16x32_bf16 v[88:91], v[156:159], v[188:191], v[88:91]
	v_mfma_f32_16x16x32_bf16 v[92:95], v[164:167], v[188:191], v[92:95]
	v_mfma_f32_16x16x32_bf16 v[64:67], v[156:159], v[196:199], v[64:67]
	v_mfma_f32_16x16x32_bf16 v[68:71], v[164:167], v[196:199], v[68:71]
	v_mfma_f32_16x16x32_bf16 v[120:123], v[160:163], v[176:179], v[120:123]
	v_mfma_f32_16x16x32_bf16 v[124:127], v[168:171], v[176:179], v[124:127]
	v_mfma_f32_16x16x32_bf16 v[104:107], v[160:163], v[184:187], v[104:107]
	v_mfma_f32_16x16x32_bf16 v[108:111], v[168:171], v[184:187], v[108:111]
	v_mfma_f32_16x16x32_bf16 v[88:91], v[160:163], v[192:195], v[88:91]
	v_mfma_f32_16x16x32_bf16 v[92:95], v[168:171], v[192:195], v[92:95]
	v_mfma_f32_16x16x32_bf16 v[64:67], v[160:163], v[200:203], v[64:67]
	v_mfma_f32_16x16x32_bf16 v[68:71], v[168:171], v[200:203], v[68:71]
	s_barrier
	s_add_i32 s57, s57, s10
	v_lshl_add_u64 v[204:205], s[8:9], 0, v[224:225]
	s_mov_b32 m0, s57
	ds_read_b128 v[172:175], v139 offset:16384
	ds_read_b128 v[176:179], v139 offset:17408
	ds_read_b128 v[180:183], v139 offset:18432
	ds_read_b128 v[184:187], v139 offset:19456
	ds_read_b128 v[188:191], v139 offset:20480
	ds_read_b128 v[192:195], v139 offset:21504
	ds_read_b128 v[196:199], v139 offset:22528
	ds_read_b128 v[200:203], v139 offset:23552
	global_load_lds_dwordx4 v[204:205], off
	s_add_i32 m0, s57, 0x2000
	s_add_u32 s58, s8, 0x80000
	v_lshl_add_u64 v[206:207], s[8:9], 0, v[128:129]
	s_addc_u32 s59, s9, 0
	s_add_i32 s57, s60, s10
	global_load_lds_dwordx4 v[206:207], off
	v_lshl_add_u64 v[208:209], s[58:59], 0, v[224:225]
	s_mov_b32 m0, s57
	v_lshl_add_u64 v[210:211], s[28:29], 0, v[130:131]
	global_load_lds_dwordx4 v[208:209], off
	s_add_i32 m0, s57, 0x2000
	v_lshl_add_u64 v[208:209], s[58:59], 0, v[128:129]
	global_load_lds_dwordx4 v[208:209], off
	s_mov_b32 m0, s31
	v_lshl_add_u64 v[208:209], s[28:29], 0, v[132:133]
	global_load_lds_dwordx4 v[208:209], off
	s_mov_b32 m0, s33
	s_nop 0
	global_load_lds_dwordx4 v[210:211], off
	s_waitcnt vmcnt(8) lgkmcnt(0)
	s_barrier
	v_mfma_f32_16x16x32_bf16 v[56:59], v[140:143], v[172:175], v[56:59]
	v_mfma_f32_16x16x32_bf16 v[60:63], v[148:151], v[172:175], v[60:63]
	v_mfma_f32_16x16x32_bf16 v[32:35], v[140:143], v[180:183], v[32:35]
	v_mfma_f32_16x16x32_bf16 v[36:39], v[148:151], v[180:183], v[36:39]
	v_mfma_f32_16x16x32_bf16 v[16:19], v[140:143], v[188:191], v[16:19]
	v_mfma_f32_16x16x32_bf16 v[20:23], v[148:151], v[188:191], v[20:23]
	v_mfma_f32_16x16x32_bf16 v[0:3], v[140:143], v[196:199], v[0:3]
	v_mfma_f32_16x16x32_bf16 v[4:7], v[148:151], v[196:199], v[4:7]
	v_mfma_f32_16x16x32_bf16 v[56:59], v[144:147], v[176:179], v[56:59]
	v_mfma_f32_16x16x32_bf16 v[60:63], v[152:155], v[176:179], v[60:63]
	v_mfma_f32_16x16x32_bf16 v[32:35], v[144:147], v[184:187], v[32:35]
	v_mfma_f32_16x16x32_bf16 v[36:39], v[152:155], v[184:187], v[36:39]
	v_mfma_f32_16x16x32_bf16 v[16:19], v[144:147], v[192:195], v[16:19]
	v_mfma_f32_16x16x32_bf16 v[20:23], v[152:155], v[192:195], v[20:23]
	v_mfma_f32_16x16x32_bf16 v[0:3], v[144:147], v[200:203], v[0:3]
	v_mfma_f32_16x16x32_bf16 v[4:7], v[152:155], v[200:203], v[4:7]
	v_mfma_f32_16x16x32_bf16 v[72:75], v[156:159], v[172:175], v[72:75]
	v_mfma_f32_16x16x32_bf16 v[76:79], v[164:167], v[172:175], v[76:79]
	v_mfma_f32_16x16x32_bf16 v[40:43], v[156:159], v[180:183], v[40:43]
	v_mfma_f32_16x16x32_bf16 v[44:47], v[164:167], v[180:183], v[44:47]
	v_mfma_f32_16x16x32_bf16 v[24:27], v[156:159], v[188:191], v[24:27]
	v_mfma_f32_16x16x32_bf16 v[28:31], v[164:167], v[188:191], v[28:31]
	v_mfma_f32_16x16x32_bf16 v[8:11], v[156:159], v[196:199], v[8:11]
	v_mfma_f32_16x16x32_bf16 v[12:15], v[164:167], v[196:199], v[12:15]
	v_mfma_f32_16x16x32_bf16 v[72:75], v[160:163], v[176:179], v[72:75]
	v_mfma_f32_16x16x32_bf16 v[76:79], v[168:171], v[176:179], v[76:79]
	v_mfma_f32_16x16x32_bf16 v[40:43], v[160:163], v[184:187], v[40:43]
	v_mfma_f32_16x16x32_bf16 v[44:47], v[168:171], v[184:187], v[44:47]
	v_mfma_f32_16x16x32_bf16 v[24:27], v[160:163], v[192:195], v[24:27]
	v_mfma_f32_16x16x32_bf16 v[28:31], v[168:171], v[192:195], v[28:31]
	v_mfma_f32_16x16x32_bf16 v[8:11], v[160:163], v[200:203], v[8:11]
	v_mfma_f32_16x16x32_bf16 v[12:15], v[168:171], v[200:203], v[12:15]
	s_barrier
	s_add_i32 s57, 0, 0x18000
	s_add_i32 s58, 0, 0x1c000
	v_add_u32_e32 v152, s57, v138
	v_add_u32_e32 v168, s58, v138
	ds_read_b128 v[140:143], v152
	ds_read_b128 v[144:147], v152 offset:1024
	ds_read_b128 v[148:151], v152 offset:2048
	ds_read_b128 v[152:155], v152 offset:3072
	ds_read_b128 v[156:159], v168
	ds_read_b128 v[160:163], v168 offset:1024
	ds_read_b128 v[164:167], v168 offset:2048
	ds_read_b128 v[168:171], v168 offset:3072
	s_add_u32 s28, s28, 0x80000
	s_addc_u32 s29, s29, 0
	s_mov_b32 m0, s42
	v_lshl_add_u64 v[212:213], s[28:29], 0, v[132:133]
	ds_read_b128 v[172:175], v139 offset:32768
	ds_read_b128 v[176:179], v139 offset:33792
	ds_read_b128 v[180:183], v139 offset:34816
	ds_read_b128 v[184:187], v139 offset:35840
	ds_read_b128 v[188:191], v139 offset:36864
	ds_read_b128 v[192:195], v139 offset:37888
	ds_read_b128 v[196:199], v139 offset:38912
	ds_read_b128 v[200:203], v139 offset:39936
	global_load_lds_dwordx4 v[212:213], off
	s_mov_b32 m0, s43
	v_lshl_add_u64 v[212:213], s[28:29], 0, v[130:131]
	global_load_lds_dwordx4 v[212:213], off
	s_waitcnt vmcnt(8) lgkmcnt(0)
	s_barrier
	v_mfma_f32_16x16x32_bf16 v[112:115], v[140:143], v[172:175], v[112:115]
	v_mfma_f32_16x16x32_bf16 v[116:119], v[148:151], v[172:175], v[116:119]
	v_mfma_f32_16x16x32_bf16 v[96:99], v[140:143], v[180:183], v[96:99]
	v_mfma_f32_16x16x32_bf16 v[100:103], v[148:151], v[180:183], v[100:103]
	v_mfma_f32_16x16x32_bf16 v[80:83], v[140:143], v[188:191], v[80:83]
	v_mfma_f32_16x16x32_bf16 v[84:87], v[148:151], v[188:191], v[84:87]
	v_mfma_f32_16x16x32_bf16 v[48:51], v[140:143], v[196:199], v[48:51]
	v_mfma_f32_16x16x32_bf16 v[52:55], v[148:151], v[196:199], v[52:55]
	v_mfma_f32_16x16x32_bf16 v[112:115], v[144:147], v[176:179], v[112:115]
	v_mfma_f32_16x16x32_bf16 v[116:119], v[152:155], v[176:179], v[116:119]
	v_mfma_f32_16x16x32_bf16 v[96:99], v[144:147], v[184:187], v[96:99]
	v_mfma_f32_16x16x32_bf16 v[100:103], v[152:155], v[184:187], v[100:103]
	v_mfma_f32_16x16x32_bf16 v[80:83], v[144:147], v[192:195], v[80:83]
	v_mfma_f32_16x16x32_bf16 v[84:87], v[152:155], v[192:195], v[84:87]
	v_mfma_f32_16x16x32_bf16 v[48:51], v[144:147], v[200:203], v[48:51]
	v_mfma_f32_16x16x32_bf16 v[52:55], v[152:155], v[200:203], v[52:55]
	v_mfma_f32_16x16x32_bf16 v[120:123], v[156:159], v[172:175], v[120:123]
	v_mfma_f32_16x16x32_bf16 v[124:127], v[164:167], v[172:175], v[124:127]
	v_mfma_f32_16x16x32_bf16 v[104:107], v[156:159], v[180:183], v[104:107]
	v_mfma_f32_16x16x32_bf16 v[108:111], v[164:167], v[180:183], v[108:111]
	v_mfma_f32_16x16x32_bf16 v[88:91], v[156:159], v[188:191], v[88:91]
	v_mfma_f32_16x16x32_bf16 v[92:95], v[164:167], v[188:191], v[92:95]
	v_mfma_f32_16x16x32_bf16 v[64:67], v[156:159], v[196:199], v[64:67]
	v_mfma_f32_16x16x32_bf16 v[68:71], v[164:167], v[196:199], v[68:71]
	v_mfma_f32_16x16x32_bf16 v[120:123], v[160:163], v[176:179], v[120:123]
	v_mfma_f32_16x16x32_bf16 v[124:127], v[168:171], v[176:179], v[124:127]
	v_mfma_f32_16x16x32_bf16 v[104:107], v[160:163], v[184:187], v[104:107]
	v_mfma_f32_16x16x32_bf16 v[108:111], v[168:171], v[184:187], v[108:111]
	v_mfma_f32_16x16x32_bf16 v[88:91], v[160:163], v[192:195], v[88:91]
	v_mfma_f32_16x16x32_bf16 v[92:95], v[168:171], v[192:195], v[92:95]
	v_mfma_f32_16x16x32_bf16 v[64:67], v[160:163], v[200:203], v[64:67]
	v_mfma_f32_16x16x32_bf16 v[68:71], v[168:171], v[200:203], v[68:71]
	s_barrier
	s_add_i32 s28, s57, s10
	v_lshl_add_u64 v[204:205], v[204:205], 0, s[24:25]
	s_mov_b32 m0, s28
	ds_read_b128 v[172:175], v139 offset:49152
	ds_read_b128 v[176:179], v139 offset:50176
	ds_read_b128 v[180:183], v139 offset:51200
	ds_read_b128 v[184:187], v139 offset:52224
	ds_read_b128 v[188:191], v139 offset:53248
	ds_read_b128 v[192:195], v139 offset:54272
	ds_read_b128 v[196:199], v139 offset:55296
	ds_read_b128 v[200:203], v139 offset:56320
	global_load_lds_dwordx4 v[204:205], off
	s_add_i32 m0, s28, 0x2000
	s_add_u32 s8, s8, 0x80080
	v_lshl_add_u64 v[204:205], v[206:207], 0, s[24:25]
	s_addc_u32 s9, s9, 0
	s_add_i32 s28, s58, s10
	global_load_lds_dwordx4 v[204:205], off
	s_mov_b32 m0, s28
	v_lshl_add_u64 v[204:205], s[8:9], 0, v[224:225]
	global_load_lds_dwordx4 v[204:205], off
	s_add_i32 m0, s28, 0x2000
	v_lshl_add_u64 v[204:205], s[8:9], 0, v[128:129]
	global_load_lds_dwordx4 v[204:205], off
	s_mov_b32 m0, s46
	v_lshl_add_u64 v[204:205], v[208:209], 0, s[24:25]
	global_load_lds_dwordx4 v[204:205], off
	s_mov_b32 m0, s47
	v_lshl_add_u64 v[204:205], v[210:211], 0, s[24:25]
	global_load_lds_dwordx4 v[204:205], off
	s_waitcnt vmcnt(8) lgkmcnt(0)
	s_barrier
	v_mfma_f32_16x16x32_bf16 v[56:59], v[140:143], v[172:175], v[56:59]
	v_mfma_f32_16x16x32_bf16 v[60:63], v[148:151], v[172:175], v[60:63]
	v_mfma_f32_16x16x32_bf16 v[32:35], v[140:143], v[180:183], v[32:35]
	v_mfma_f32_16x16x32_bf16 v[36:39], v[148:151], v[180:183], v[36:39]
	v_mfma_f32_16x16x32_bf16 v[16:19], v[140:143], v[188:191], v[16:19]
	v_mfma_f32_16x16x32_bf16 v[20:23], v[148:151], v[188:191], v[20:23]
	v_mfma_f32_16x16x32_bf16 v[0:3], v[140:143], v[196:199], v[0:3]
	v_mfma_f32_16x16x32_bf16 v[4:7], v[148:151], v[196:199], v[4:7]
	v_mfma_f32_16x16x32_bf16 v[56:59], v[144:147], v[176:179], v[56:59]
	v_mfma_f32_16x16x32_bf16 v[60:63], v[152:155], v[176:179], v[60:63]
	v_mfma_f32_16x16x32_bf16 v[32:35], v[144:147], v[184:187], v[32:35]
	v_mfma_f32_16x16x32_bf16 v[36:39], v[152:155], v[184:187], v[36:39]
	v_mfma_f32_16x16x32_bf16 v[16:19], v[144:147], v[192:195], v[16:19]
	v_mfma_f32_16x16x32_bf16 v[20:23], v[152:155], v[192:195], v[20:23]
	v_mfma_f32_16x16x32_bf16 v[0:3], v[144:147], v[200:203], v[0:3]
	v_mfma_f32_16x16x32_bf16 v[4:7], v[152:155], v[200:203], v[4:7]
	v_mfma_f32_16x16x32_bf16 v[72:75], v[156:159], v[172:175], v[72:75]
	v_mfma_f32_16x16x32_bf16 v[76:79], v[164:167], v[172:175], v[76:79]
	v_mfma_f32_16x16x32_bf16 v[40:43], v[156:159], v[180:183], v[40:43]
	v_mfma_f32_16x16x32_bf16 v[44:47], v[164:167], v[180:183], v[44:47]
	v_mfma_f32_16x16x32_bf16 v[24:27], v[156:159], v[188:191], v[24:27]
	v_mfma_f32_16x16x32_bf16 v[28:31], v[164:167], v[188:191], v[28:31]
	v_mfma_f32_16x16x32_bf16 v[8:11], v[156:159], v[196:199], v[8:11]
	v_mfma_f32_16x16x32_bf16 v[12:15], v[164:167], v[196:199], v[12:15]
	v_mfma_f32_16x16x32_bf16 v[72:75], v[160:163], v[176:179], v[72:75]
	v_mfma_f32_16x16x32_bf16 v[76:79], v[168:171], v[176:179], v[76:79]
	v_mfma_f32_16x16x32_bf16 v[40:43], v[160:163], v[184:187], v[40:43]
	v_mfma_f32_16x16x32_bf16 v[44:47], v[168:171], v[184:187], v[44:47]
	v_mfma_f32_16x16x32_bf16 v[24:27], v[160:163], v[192:195], v[24:27]
	v_mfma_f32_16x16x32_bf16 v[28:31], v[168:171], v[192:195], v[28:31]
	v_mfma_f32_16x16x32_bf16 v[8:11], v[160:163], v[200:203], v[8:11]
	v_mfma_f32_16x16x32_bf16 v[12:15], v[168:171], v[200:203], v[12:15]
	s_barrier
	s_add_u32 s12, s12, 0x100
	s_addc_u32 s13, s13, 0
	s_add_u32 s54, s54, 0x100
	s_addc_u32 s55, s55, 0
	s_cmp_ge_i32 s56, s45
	s_mov_b32 s8, s56
	s_cbranch_scc0 .LBB0_1667
	s_mov_b32 s53, 0x5040100
	s_mov_b64 s[56:57], 0x400000
	s_mov_b64 s[58:59], 0x3fffff
	s_mov_b64 s[60:61], 0x20000

.LBB0_1739:
	s_min_u32 s10, s17, 0x7a
	s_add_i32 s10, s10, 5
	s_mul_i32 s18, s10, 0xab
	s_lshr_b32 s18, s18, 10
	s_mul_i32 s18, s18, 6
	s_sub_i32 s18, s10, s18
	s_and_b32 s18, s18, 0xff
	s_mulk_i32 s18, 0x6000
	s_waitcnt vmcnt(12)
	s_add_i32 s18, s18, 0
	s_lshl_b32 s10, s10, 7
	s_barrier
	s_add_i32 m0, s18, s0
	v_lshl_add_u64 v[50:51], v[34:35], 0, s[10:11]
	global_load_lds_dwordx4 v[50:51], off
	s_add_i32 m0, s18, s2
	v_lshl_add_u64 v[50:51], v[36:37], 0, s[10:11]
	global_load_lds_dwordx4 v[50:51], off
	v_lshl_add_u64 v[50:51], v[38:39], 0, s[10:11]
	s_add_i32 m0, s18, s3
	s_bitcmp1_b32 s17, 0
	global_load_lds_dwordx4 v[50:51], off
	s_cselect_b64 s[18:19], -1, 0
	s_and_b64 vcc, exec, s[18:19]
	s_cbranch_vccnz .LBB0_1738
	v_cvt_pk_f16_f32 v50, v4, v5
	v_cvt_pk_f16_f32 v51, v6, v7
	v_add_co_u32_e32 v52, vcc, s26, v42
	global_store_dwordx2 v[42:43], v[50:51], off
	v_cvt_pk_f16_f32 v50, v12, v13
	v_cvt_pk_f16_f32 v51, v14, v15
	v_addc_co_u32_e32 v53, vcc, 0, v43, vcc
	global_store_dwordx2 v[52:53], v[50:51], off
	v_add_co_u32_e32 v52, vcc, s22, v42
	v_cvt_pk_f16_f32 v50, v8, v9
	v_cvt_pk_f16_f32 v51, v10, v11
	v_addc_co_u32_e32 v53, vcc, 0, v43, vcc
	global_store_dwordx2 v[52:53], v[50:51], off
	v_add_co_u32_e32 v52, vcc, s23, v42
	v_mov_b32_e32 v33, v32
	v_cvt_pk_f16_f32 v50, v0, v1
	v_cvt_pk_f16_f32 v51, v2, v3
	v_addc_co_u32_e32 v53, vcc, 0, v43, vcc
	v_pk_mul_f32 v[2:3], v[32:33], v[2:3]
	v_pk_mul_f32 v[0:1], v[32:33], v[0:1]
	v_pk_mul_f32 v[10:11], v[32:33], v[10:11]
	v_pk_mul_f32 v[8:9], v[32:33], v[8:9]
	v_pk_mul_f32 v[14:15], v[32:33], v[14:15]
	v_pk_mul_f32 v[12:13], v[32:33], v[12:13]
	v_pk_mul_f32 v[6:7], v[32:33], v[6:7]
	v_pk_mul_f32 v[4:5], v[40:41], v[4:5]
	global_store_dwordx2 v[52:53], v[50:51], off
	s_branch .LBB0_1738

.LBB0_1892:
	s_add_i32 s33, s8, 2
	s_add_u32 s35, s12, 0x80
	s_addc_u32 s9, s13, 0
	s_add_i32 s37, 0, 0x10000
	s_cmp_eq_u32 s61, s8
	s_cselect_b32 s9, s3, s9
	s_cselect_b32 s8, s7, s35
	s_cselect_b32 s65, s28, s31
	s_cselect_b32 s64, s29, s30
	s_add_i32 s35, 0, 0x14000
	v_add_u32_e32 v140, s37, v214
	v_add_u32_e32 v156, s35, v214
	ds_read_b128 v[128:131], v140
	ds_read_b128 v[132:135], v140 offset:1024
	ds_read_b128 v[136:139], v140 offset:2048
	ds_read_b128 v[140:143], v140 offset:3072
	ds_read_b128 v[144:147], v156
	ds_read_b128 v[148:151], v156 offset:1024
	ds_read_b128 v[152:155], v156 offset:2048
	ds_read_b128 v[156:159], v156 offset:3072
	v_lshl_add_u64 v[202:203], s[12:13], 0, v[194:195]
	s_add_i32 m0, s53, 0xc000
	ds_read_b128 v[160:163], v215
	ds_read_b128 v[164:167], v215 offset:1024
	ds_read_b128 v[168:171], v215 offset:2048
	ds_read_b128 v[172:175], v215 offset:3072
	ds_read_b128 v[176:179], v215 offset:4096
	ds_read_b128 v[180:183], v215 offset:5120
	ds_read_b128 v[184:187], v215 offset:6144
	ds_read_b128 v[198:201], v215 offset:7168
	global_load_lds_dwordx4 v[202:203], off
	s_add_i32 m0, s53, 0xe000
	v_lshl_add_u64 v[202:203], s[12:13], 0, v[196:197]
	global_load_lds_dwordx4 v[202:203], off
	s_waitcnt vmcnt(8) lgkmcnt(0)
	s_barrier
	v_mfma_f32_16x16x32_bf16 v[124:127], v[128:131], v[160:163], v[124:127]
	v_mfma_f32_16x16x32_bf16 v[120:123], v[136:139], v[160:163], v[120:123]
	v_mfma_f32_16x16x32_bf16 v[108:111], v[128:131], v[168:171], v[108:111]
	v_mfma_f32_16x16x32_bf16 v[104:107], v[136:139], v[168:171], v[104:107]
	v_mfma_f32_16x16x32_bf16 v[92:95], v[128:131], v[176:179], v[92:95]
	v_mfma_f32_16x16x32_bf16 v[88:91], v[136:139], v[176:179], v[88:91]
	v_mfma_f32_16x16x32_bf16 v[76:79], v[128:131], v[184:187], v[76:79]
	v_mfma_f32_16x16x32_bf16 v[72:75], v[136:139], v[184:187], v[72:75]
	v_mfma_f32_16x16x32_bf16 v[124:127], v[132:135], v[164:167], v[124:127]
	v_mfma_f32_16x16x32_bf16 v[120:123], v[140:143], v[164:167], v[120:123]
	v_mfma_f32_16x16x32_bf16 v[108:111], v[132:135], v[172:175], v[108:111]
	v_mfma_f32_16x16x32_bf16 v[104:107], v[140:143], v[172:175], v[104:107]
	v_mfma_f32_16x16x32_bf16 v[92:95], v[132:135], v[180:183], v[92:95]
	v_mfma_f32_16x16x32_bf16 v[88:91], v[140:143], v[180:183], v[88:91]
	v_mfma_f32_16x16x32_bf16 v[76:79], v[132:135], v[198:201], v[76:79]
	v_mfma_f32_16x16x32_bf16 v[72:75], v[140:143], v[198:201], v[72:75]
	v_mfma_f32_16x16x32_bf16 v[116:119], v[144:147], v[160:163], v[116:119]
	v_mfma_f32_16x16x32_bf16 v[112:115], v[152:155], v[160:163], v[112:115]
	v_mfma_f32_16x16x32_bf16 v[100:103], v[144:147], v[168:171], v[100:103]
	v_mfma_f32_16x16x32_bf16 v[96:99], v[152:155], v[168:171], v[96:99]
	v_mfma_f32_16x16x32_bf16 v[84:87], v[144:147], v[176:179], v[84:87]
	v_mfma_f32_16x16x32_bf16 v[80:83], v[152:155], v[176:179], v[80:83]
	v_mfma_f32_16x16x32_bf16 v[68:71], v[144:147], v[184:187], v[68:71]
	v_mfma_f32_16x16x32_bf16 v[64:67], v[152:155], v[184:187], v[64:67]
	v_mfma_f32_16x16x32_bf16 v[116:119], v[148:151], v[164:167], v[116:119]
	v_mfma_f32_16x16x32_bf16 v[112:115], v[156:159], v[164:167], v[112:115]
	v_mfma_f32_16x16x32_bf16 v[100:103], v[148:151], v[172:175], v[100:103]
	v_mfma_f32_16x16x32_bf16 v[96:99], v[156:159], v[172:175], v[96:99]
	v_mfma_f32_16x16x32_bf16 v[84:87], v[148:151], v[180:183], v[84:87]
	v_mfma_f32_16x16x32_bf16 v[80:83], v[156:159], v[180:183], v[80:83]
	v_mfma_f32_16x16x32_bf16 v[68:71], v[148:151], v[198:201], v[68:71]
	v_mfma_f32_16x16x32_bf16 v[64:67], v[156:159], v[198:201], v[64:67]
	s_barrier
	s_add_i32 s37, s37, s50
	v_lshl_add_u64 v[202:203], s[64:65], 0, v[224:225]
	s_mov_b32 m0, s37
	ds_read_b128 v[160:163], v215 offset:16384
	ds_read_b128 v[164:167], v215 offset:17408
	ds_read_b128 v[168:171], v215 offset:18432
	ds_read_b128 v[172:175], v215 offset:19456
	ds_read_b128 v[176:179], v215 offset:20480
	ds_read_b128 v[180:183], v215 offset:21504
	ds_read_b128 v[184:187], v215 offset:22528
	ds_read_b128 v[198:201], v215 offset:23552
	global_load_lds_dwordx4 v[202:203], off
	s_add_i32 m0, s37, 0x2000
	v_lshl_add_u64 v[204:205], s[64:65], 0, v[188:189]
	s_add_u32 s64, s64, s10
	s_addc_u32 s65, s65, 0
	s_add_i32 s35, s35, s50
	global_load_lds_dwordx4 v[204:205], off
	v_lshl_add_u64 v[206:207], s[64:65], 0, v[224:225]
	s_mov_b32 m0, s35
	v_lshl_add_u64 v[208:209], s[64:65], 0, v[188:189]
	global_load_lds_dwordx4 v[206:207], off
	s_add_i32 m0, s35, 0x2000
	v_lshl_add_u64 v[210:211], s[8:9], 0, v[192:193]
	global_load_lds_dwordx4 v[208:209], off
	s_mov_b32 m0, s53
	v_lshl_add_u64 v[212:213], s[8:9], 0, v[190:191]
	global_load_lds_dwordx4 v[210:211], off
	s_mov_b32 m0, s54
	s_nop 0
	global_load_lds_dwordx4 v[212:213], off
	s_waitcnt vmcnt(8) lgkmcnt(0)
	s_barrier
	v_mfma_f32_16x16x32_bf16 v[60:63], v[128:131], v[160:163], v[60:63]
	v_mfma_f32_16x16x32_bf16 v[56:59], v[136:139], v[160:163], v[56:59]
	v_mfma_f32_16x16x32_bf16 v[44:47], v[128:131], v[168:171], v[44:47]
	v_mfma_f32_16x16x32_bf16 v[40:43], v[136:139], v[168:171], v[40:43]
	v_mfma_f32_16x16x32_bf16 v[28:31], v[128:131], v[176:179], v[28:31]
	v_mfma_f32_16x16x32_bf16 v[24:27], v[136:139], v[176:179], v[24:27]
	v_mfma_f32_16x16x32_bf16 v[12:15], v[128:131], v[184:187], v[12:15]
	v_mfma_f32_16x16x32_bf16 v[8:11], v[136:139], v[184:187], v[8:11]
	v_mfma_f32_16x16x32_bf16 v[60:63], v[132:135], v[164:167], v[60:63]
	v_mfma_f32_16x16x32_bf16 v[56:59], v[140:143], v[164:167], v[56:59]
	v_mfma_f32_16x16x32_bf16 v[44:47], v[132:135], v[172:175], v[44:47]
	v_mfma_f32_16x16x32_bf16 v[40:43], v[140:143], v[172:175], v[40:43]
	v_mfma_f32_16x16x32_bf16 v[28:31], v[132:135], v[180:183], v[28:31]
	v_mfma_f32_16x16x32_bf16 v[24:27], v[140:143], v[180:183], v[24:27]
	v_mfma_f32_16x16x32_bf16 v[12:15], v[132:135], v[198:201], v[12:15]
	v_mfma_f32_16x16x32_bf16 v[8:11], v[140:143], v[198:201], v[8:11]
	v_mfma_f32_16x16x32_bf16 v[52:55], v[144:147], v[160:163], v[52:55]
	v_mfma_f32_16x16x32_bf16 v[48:51], v[152:155], v[160:163], v[48:51]
	v_mfma_f32_16x16x32_bf16 v[36:39], v[144:147], v[168:171], v[36:39]
	v_mfma_f32_16x16x32_bf16 v[32:35], v[152:155], v[168:171], v[32:35]
	v_mfma_f32_16x16x32_bf16 v[20:23], v[144:147], v[176:179], v[20:23]
	v_mfma_f32_16x16x32_bf16 v[16:19], v[152:155], v[176:179], v[16:19]
	v_mfma_f32_16x16x32_bf16 v[4:7], v[144:147], v[184:187], v[4:7]
	v_mfma_f32_16x16x32_bf16 v[0:3], v[152:155], v[184:187], v[0:3]
	v_mfma_f32_16x16x32_bf16 v[52:55], v[148:151], v[164:167], v[52:55]
	v_mfma_f32_16x16x32_bf16 v[48:51], v[156:159], v[164:167], v[48:51]
	v_mfma_f32_16x16x32_bf16 v[36:39], v[148:151], v[172:175], v[36:39]
	v_mfma_f32_16x16x32_bf16 v[32:35], v[156:159], v[172:175], v[32:35]
	v_mfma_f32_16x16x32_bf16 v[20:23], v[148:151], v[180:183], v[20:23]
	v_mfma_f32_16x16x32_bf16 v[16:19], v[156:159], v[180:183], v[16:19]
	v_mfma_f32_16x16x32_bf16 v[4:7], v[148:151], v[198:201], v[4:7]
	v_mfma_f32_16x16x32_bf16 v[0:3], v[156:159], v[198:201], v[0:3]
	s_barrier
	s_add_i32 s35, 0, 0x18000
	s_add_i32 s37, 0, 0x1c000
	v_add_u32_e32 v140, s35, v214
	v_add_u32_e32 v156, s37, v214
	ds_read_b128 v[128:131], v140
	ds_read_b128 v[132:135], v140 offset:1024
	ds_read_b128 v[136:139], v140 offset:2048
	ds_read_b128 v[140:143], v140 offset:3072
	ds_read_b128 v[144:147], v156
	ds_read_b128 v[148:151], v156 offset:1024
	ds_read_b128 v[152:155], v156 offset:2048
	ds_read_b128 v[156:159], v156 offset:3072
	s_add_u32 s8, s8, s10
	s_addc_u32 s9, s9, 0
	s_mov_b32 m0, s55
	v_lshl_add_u64 v[216:217], s[8:9], 0, v[192:193]
	ds_read_b128 v[160:163], v215 offset:32768
	ds_read_b128 v[164:167], v215 offset:33792
	ds_read_b128 v[168:171], v215 offset:34816
	ds_read_b128 v[172:175], v215 offset:35840
	ds_read_b128 v[176:179], v215 offset:36864
	ds_read_b128 v[180:183], v215 offset:37888
	ds_read_b128 v[184:187], v215 offset:38912
	ds_read_b128 v[198:201], v215 offset:39936
	global_load_lds_dwordx4 v[216:217], off
	s_mov_b32 m0, s56
	v_lshl_add_u64 v[216:217], s[8:9], 0, v[190:191]
	global_load_lds_dwordx4 v[216:217], off
	s_waitcnt vmcnt(8) lgkmcnt(0)
	s_barrier
	v_mfma_f32_16x16x32_bf16 v[124:127], v[128:131], v[160:163], v[124:127]
	v_mfma_f32_16x16x32_bf16 v[120:123], v[136:139], v[160:163], v[120:123]
	v_mfma_f32_16x16x32_bf16 v[108:111], v[128:131], v[168:171], v[108:111]
	v_mfma_f32_16x16x32_bf16 v[104:107], v[136:139], v[168:171], v[104:107]
	v_mfma_f32_16x16x32_bf16 v[92:95], v[128:131], v[176:179], v[92:95]
	v_mfma_f32_16x16x32_bf16 v[88:91], v[136:139], v[176:179], v[88:91]
	v_mfma_f32_16x16x32_bf16 v[76:79], v[128:131], v[184:187], v[76:79]
	v_mfma_f32_16x16x32_bf16 v[72:75], v[136:139], v[184:187], v[72:75]
	v_mfma_f32_16x16x32_bf16 v[124:127], v[132:135], v[164:167], v[124:127]
	v_mfma_f32_16x16x32_bf16 v[120:123], v[140:143], v[164:167], v[120:123]
	v_mfma_f32_16x16x32_bf16 v[108:111], v[132:135], v[172:175], v[108:111]
	v_mfma_f32_16x16x32_bf16 v[104:107], v[140:143], v[172:175], v[104:107]
	v_mfma_f32_16x16x32_bf16 v[92:95], v[132:135], v[180:183], v[92:95]
	v_mfma_f32_16x16x32_bf16 v[88:91], v[140:143], v[180:183], v[88:91]
	v_mfma_f32_16x16x32_bf16 v[76:79], v[132:135], v[198:201], v[76:79]
	v_mfma_f32_16x16x32_bf16 v[72:75], v[140:143], v[198:201], v[72:75]
	v_mfma_f32_16x16x32_bf16 v[116:119], v[144:147], v[160:163], v[116:119]
	v_mfma_f32_16x16x32_bf16 v[112:115], v[152:155], v[160:163], v[112:115]
	v_mfma_f32_16x16x32_bf16 v[100:103], v[144:147], v[168:171], v[100:103]
	v_mfma_f32_16x16x32_bf16 v[96:99], v[152:155], v[168:171], v[96:99]
	v_mfma_f32_16x16x32_bf16 v[84:87], v[144:147], v[176:179], v[84:87]
	v_mfma_f32_16x16x32_bf16 v[80:83], v[152:155], v[176:179], v[80:83]
	v_mfma_f32_16x16x32_bf16 v[68:71], v[144:147], v[184:187], v[68:71]
	v_mfma_f32_16x16x32_bf16 v[64:67], v[152:155], v[184:187], v[64:67]
	v_mfma_f32_16x16x32_bf16 v[116:119], v[148:151], v[164:167], v[116:119]
	v_mfma_f32_16x16x32_bf16 v[112:115], v[156:159], v[164:167], v[112:115]
	v_mfma_f32_16x16x32_bf16 v[100:103], v[148:151], v[172:175], v[100:103]
	v_mfma_f32_16x16x32_bf16 v[96:99], v[156:159], v[172:175], v[96:99]
	v_mfma_f32_16x16x32_bf16 v[84:87], v[148:151], v[180:183], v[84:87]
	v_mfma_f32_16x16x32_bf16 v[80:83], v[156:159], v[180:183], v[80:83]
	v_mfma_f32_16x16x32_bf16 v[68:71], v[148:151], v[198:201], v[68:71]
	v_mfma_f32_16x16x32_bf16 v[64:67], v[156:159], v[198:201], v[64:67]
	s_barrier
	s_add_i32 s8, s35, s50
	v_lshl_add_u64 v[202:203], v[202:203], 0, s[24:25]
	s_mov_b32 m0, s8
	ds_read_b128 v[160:163], v215 offset:49152
	ds_read_b128 v[164:167], v215 offset:50176
	ds_read_b128 v[168:171], v215 offset:51200
	ds_read_b128 v[172:175], v215 offset:52224
	ds_read_b128 v[176:179], v215 offset:53248
	ds_read_b128 v[180:183], v215 offset:54272
	ds_read_b128 v[184:187], v215 offset:55296
	ds_read_b128 v[198:201], v215 offset:56320
	global_load_lds_dwordx4 v[202:203], off
	v_lshl_add_u64 v[202:203], v[204:205], 0, s[24:25]
	s_add_i32 m0, s8, 0x2000
	s_add_i32 s8, s37, s50
	global_load_lds_dwordx4 v[202:203], off
	s_mov_b32 m0, s8
	v_lshl_add_u64 v[202:203], v[206:207], 0, s[24:25]
	global_load_lds_dwordx4 v[202:203], off
	s_add_i32 m0, s8, 0x2000
	v_lshl_add_u64 v[202:203], v[208:209], 0, s[24:25]
	global_load_lds_dwordx4 v[202:203], off
	s_mov_b32 m0, s57
	v_lshl_add_u64 v[202:203], v[210:211], 0, s[24:25]
	global_load_lds_dwordx4 v[202:203], off
	s_mov_b32 m0, s58
	v_lshl_add_u64 v[202:203], v[212:213], 0, s[24:25]
	global_load_lds_dwordx4 v[202:203], off
	s_waitcnt vmcnt(8) lgkmcnt(0)
	s_barrier
	v_mfma_f32_16x16x32_bf16 v[60:63], v[128:131], v[160:163], v[60:63]
	v_mfma_f32_16x16x32_bf16 v[56:59], v[136:139], v[160:163], v[56:59]
	v_mfma_f32_16x16x32_bf16 v[44:47], v[128:131], v[168:171], v[44:47]
	v_mfma_f32_16x16x32_bf16 v[40:43], v[136:139], v[168:171], v[40:43]
	v_mfma_f32_16x16x32_bf16 v[28:31], v[128:131], v[176:179], v[28:31]
	v_mfma_f32_16x16x32_bf16 v[24:27], v[136:139], v[176:179], v[24:27]
	v_mfma_f32_16x16x32_bf16 v[12:15], v[128:131], v[184:187], v[12:15]
	v_mfma_f32_16x16x32_bf16 v[8:11], v[136:139], v[184:187], v[8:11]
	v_mfma_f32_16x16x32_bf16 v[60:63], v[132:135], v[164:167], v[60:63]
	v_mfma_f32_16x16x32_bf16 v[56:59], v[140:143], v[164:167], v[56:59]
	v_mfma_f32_16x16x32_bf16 v[44:47], v[132:135], v[172:175], v[44:47]
	v_mfma_f32_16x16x32_bf16 v[40:43], v[140:143], v[172:175], v[40:43]
	v_mfma_f32_16x16x32_bf16 v[28:31], v[132:135], v[180:183], v[28:31]
	v_mfma_f32_16x16x32_bf16 v[24:27], v[140:143], v[180:183], v[24:27]
	v_mfma_f32_16x16x32_bf16 v[12:15], v[132:135], v[198:201], v[12:15]
	v_mfma_f32_16x16x32_bf16 v[8:11], v[140:143], v[198:201], v[8:11]
	v_mfma_f32_16x16x32_bf16 v[52:55], v[144:147], v[160:163], v[52:55]
	v_mfma_f32_16x16x32_bf16 v[48:51], v[152:155], v[160:163], v[48:51]
	v_mfma_f32_16x16x32_bf16 v[36:39], v[144:147], v[168:171], v[36:39]
	v_mfma_f32_16x16x32_bf16 v[32:35], v[152:155], v[168:171], v[32:35]
	v_mfma_f32_16x16x32_bf16 v[20:23], v[144:147], v[176:179], v[20:23]
	v_mfma_f32_16x16x32_bf16 v[16:19], v[152:155], v[176:179], v[16:19]
	v_mfma_f32_16x16x32_bf16 v[4:7], v[144:147], v[184:187], v[4:7]
	v_mfma_f32_16x16x32_bf16 v[0:3], v[152:155], v[184:187], v[0:3]
	v_mfma_f32_16x16x32_bf16 v[52:55], v[148:151], v[164:167], v[52:55]
	v_mfma_f32_16x16x32_bf16 v[48:51], v[156:159], v[164:167], v[48:51]
	v_mfma_f32_16x16x32_bf16 v[36:39], v[148:151], v[172:175], v[36:39]
	v_mfma_f32_16x16x32_bf16 v[32:35], v[156:159], v[172:175], v[32:35]
	v_mfma_f32_16x16x32_bf16 v[20:23], v[148:151], v[180:183], v[20:23]
	v_mfma_f32_16x16x32_bf16 v[16:19], v[156:159], v[180:183], v[16:19]
	v_mfma_f32_16x16x32_bf16 v[4:7], v[148:151], v[198:201], v[4:7]
	v_mfma_f32_16x16x32_bf16 v[0:3], v[156:159], v[198:201], v[0:3]
	s_barrier
	s_add_u32 s12, s12, 0x100
	s_addc_u32 s13, s13, 0
	s_add_u32 s30, s30, 0x100
	s_addc_u32 s31, s31, 0
	s_cmp_ge_i32 s33, s60
	s_mov_b32 s8, s33
	s_cbranch_scc0 .LBB0_1892
	v_readlane_b32 s64, v253, 21
	v_readlane_b32 s65, v253, 22

.LBB0_2045:
	s_andn2_b64 vcc, exec, s[20:21]
	s_cbranch_vccnz .LBB0_2047
	s_mov_b32 s7, -1
	s_lshl_b32 s28, s0, 7
	v_mbcnt_lo_u32_b32 v128, s7, 0
	v_mbcnt_hi_u32_b32 v128, s7, v128
	s_ashr_i32 s29, s28, 31
	s_lshl_b64 s[28:29], s[28:29], 2
	v_lshlrev_b32_e32 v129, 2, v128
	s_add_u32 s28, s68, s28
	v_add_u32_e32 v130, 0x1500, v129
	v_cmp_gt_i32_e32 vcc, 32, v128
	s_addc_u32 s29, s67, s29
	s_lshl_b32 s7, s3, 12
	v_cndmask_b32_e32 v128, v130, v129, vcc
	v_ashrrev_i32_e32 v129, 31, v128
	s_and_b32 s7, s7, 0x1000
	s_add_i32 m0, s65, s7
	v_lshl_add_u64 v[128:129], v[128:129], 2, s[28:29]
	global_load_lds_dwordx4 v[128:129], off

.LBB0_2049:
	s_add_i32 s48, s28, 2
	s_add_u32 s8, s12, 0x100
	s_addc_u32 s9, s13, 0
	s_add_i32 s49, 0, 0x10000
	s_cmp_eq_u32 s66, s28
	s_cselect_b32 s43, s7, s9
	s_cselect_b32 s42, s30, s8
	s_cselect_b32 s29, s31, s37
	s_cselect_b32 s28, s33, s35
	s_add_i32 s70, 0, 0x14000
	v_add_u32_e32 v140, s49, v248
	v_add_u32_e32 v156, s70, v248
	ds_read_b128 v[128:131], v140
	ds_read_b128 v[132:135], v140 offset:1024
	ds_read_b128 v[136:139], v140 offset:2048
	ds_read_b128 v[140:143], v140 offset:3072
	ds_read_b128 v[144:147], v156
	ds_read_b128 v[148:151], v156 offset:1024
	ds_read_b128 v[152:155], v156 offset:2048
	ds_read_b128 v[156:159], v156 offset:3072
	v_lshl_add_u64 v[192:193], s[12:13], 0, v[236:237]
	s_add_i32 m0, s55, 0xc000
	ds_read_b128 v[160:163], v249
	ds_read_b128 v[164:167], v249 offset:1024
	ds_read_b128 v[168:171], v249 offset:2048
	ds_read_b128 v[172:175], v249 offset:3072
	ds_read_b128 v[176:179], v249 offset:4096
	ds_read_b128 v[180:183], v249 offset:5120
	ds_read_b128 v[184:187], v249 offset:6144
	ds_read_b128 v[188:191], v249 offset:7168
	global_load_lds_dwordx4 v[192:193], off
	s_add_i32 m0, s55, 0xe000
	v_lshl_add_u64 v[192:193], s[12:13], 0, v[238:239]
	global_load_lds_dwordx4 v[192:193], off
	s_waitcnt vmcnt(8) lgkmcnt(0)
	s_barrier
	v_mfma_f32_16x16x32_bf16 v[100:103], v[128:131], v[160:163], v[100:103]
	v_mfma_f32_16x16x32_bf16 v[116:119], v[136:139], v[160:163], v[116:119]
	v_mfma_f32_16x16x32_bf16 v[96:99], v[128:131], v[168:171], v[96:99]
	v_mfma_f32_16x16x32_bf16 v[112:115], v[136:139], v[168:171], v[112:115]
	v_mfma_f32_16x16x32_bf16 v[104:107], v[128:131], v[176:179], v[104:107]
	v_mfma_f32_16x16x32_bf16 v[120:123], v[136:139], v[176:179], v[120:123]
	v_mfma_f32_16x16x32_bf16 v[108:111], v[128:131], v[184:187], v[108:111]
	v_mfma_f32_16x16x32_bf16 v[124:127], v[136:139], v[184:187], v[124:127]
	v_mfma_f32_16x16x32_bf16 v[100:103], v[132:135], v[164:167], v[100:103]
	v_mfma_f32_16x16x32_bf16 v[116:119], v[140:143], v[164:167], v[116:119]
	v_mfma_f32_16x16x32_bf16 v[96:99], v[132:135], v[172:175], v[96:99]
	v_mfma_f32_16x16x32_bf16 v[112:115], v[140:143], v[172:175], v[112:115]
	v_mfma_f32_16x16x32_bf16 v[104:107], v[132:135], v[180:183], v[104:107]
	v_mfma_f32_16x16x32_bf16 v[120:123], v[140:143], v[180:183], v[120:123]
	v_mfma_f32_16x16x32_bf16 v[108:111], v[132:135], v[188:191], v[108:111]
	v_mfma_f32_16x16x32_bf16 v[124:127], v[140:143], v[188:191], v[124:127]
	v_mfma_f32_16x16x32_bf16 v[84:87], v[144:147], v[160:163], v[84:87]
	v_mfma_f32_16x16x32_bf16 v[68:71], v[152:155], v[160:163], v[68:71]
	v_mfma_f32_16x16x32_bf16 v[80:83], v[144:147], v[168:171], v[80:83]
	v_mfma_f32_16x16x32_bf16 v[64:67], v[152:155], v[168:171], v[64:67]
	v_mfma_f32_16x16x32_bf16 v[88:91], v[144:147], v[176:179], v[88:91]
	v_mfma_f32_16x16x32_bf16 v[72:75], v[152:155], v[176:179], v[72:75]
	v_mfma_f32_16x16x32_bf16 v[92:95], v[144:147], v[184:187], v[92:95]
	v_mfma_f32_16x16x32_bf16 v[76:79], v[152:155], v[184:187], v[76:79]
	v_mfma_f32_16x16x32_bf16 v[84:87], v[148:151], v[164:167], v[84:87]
	v_mfma_f32_16x16x32_bf16 v[68:71], v[156:159], v[164:167], v[68:71]
	v_mfma_f32_16x16x32_bf16 v[80:83], v[148:151], v[172:175], v[80:83]
	v_mfma_f32_16x16x32_bf16 v[64:67], v[156:159], v[172:175], v[64:67]
	v_mfma_f32_16x16x32_bf16 v[88:91], v[148:151], v[180:183], v[88:91]
	v_mfma_f32_16x16x32_bf16 v[72:75], v[156:159], v[180:183], v[72:75]
	v_mfma_f32_16x16x32_bf16 v[92:95], v[148:151], v[188:191], v[92:95]
	v_mfma_f32_16x16x32_bf16 v[76:79], v[156:159], v[188:191], v[76:79]
	s_barrier
	s_add_i32 s12, s49, s53
	v_lshl_add_u64 v[192:193], s[28:29], 0, v[224:225]
	s_mov_b32 m0, s12
	ds_read_b128 v[160:163], v249 offset:16384
	ds_read_b128 v[164:167], v249 offset:17408
	ds_read_b128 v[168:171], v249 offset:18432
	ds_read_b128 v[172:175], v249 offset:19456
	ds_read_b128 v[176:179], v249 offset:20480
	ds_read_b128 v[180:183], v249 offset:21504
	ds_read_b128 v[184:187], v249 offset:22528
	ds_read_b128 v[188:191], v249 offset:23552
	global_load_lds_dwordx4 v[192:193], off
	s_add_i32 m0, s12, 0x2000
	s_add_u32 s12, s28, 0x80000
	v_lshl_add_u64 v[194:195], s[28:29], 0, v[230:231]
	s_addc_u32 s13, s29, 0
	s_add_i32 s49, s70, s53
	global_load_lds_dwordx4 v[194:195], off
	v_lshl_add_u64 v[196:197], s[12:13], 0, v[224:225]
	s_mov_b32 m0, s49
	v_lshl_add_u64 v[198:199], s[42:43], 0, v[232:233]
	global_load_lds_dwordx4 v[196:197], off
	s_add_i32 m0, s49, 0x2000
	v_lshl_add_u64 v[196:197], s[12:13], 0, v[230:231]
	global_load_lds_dwordx4 v[196:197], off
	s_mov_b32 m0, s55
	v_lshl_add_u64 v[196:197], s[42:43], 0, v[234:235]
	global_load_lds_dwordx4 v[196:197], off
	s_mov_b32 m0, s56
	s_nop 0
	global_load_lds_dwordx4 v[198:199], off
	s_waitcnt vmcnt(8) lgkmcnt(0)
	s_barrier
	v_mfma_f32_16x16x32_bf16 v[16:19], v[128:131], v[160:163], v[16:19]
	v_mfma_f32_16x16x32_bf16 v[44:47], v[136:139], v[160:163], v[44:47]
	v_mfma_f32_16x16x32_bf16 v[24:27], v[128:131], v[168:171], v[24:27]
	v_mfma_f32_16x16x32_bf16 v[52:55], v[136:139], v[168:171], v[52:55]
	v_mfma_f32_16x16x32_bf16 v[32:35], v[128:131], v[176:179], v[32:35]
	v_mfma_f32_16x16x32_bf16 v[56:59], v[136:139], v[176:179], v[56:59]
	v_mfma_f32_16x16x32_bf16 v[40:43], v[128:131], v[184:187], v[40:43]
	v_mfma_f32_16x16x32_bf16 v[60:63], v[136:139], v[184:187], v[60:63]
	v_mfma_f32_16x16x32_bf16 v[16:19], v[132:135], v[164:167], v[16:19]
	v_mfma_f32_16x16x32_bf16 v[44:47], v[140:143], v[164:167], v[44:47]
	v_mfma_f32_16x16x32_bf16 v[24:27], v[132:135], v[172:175], v[24:27]
	v_mfma_f32_16x16x32_bf16 v[52:55], v[140:143], v[172:175], v[52:55]
	v_mfma_f32_16x16x32_bf16 v[32:35], v[132:135], v[180:183], v[32:35]
	v_mfma_f32_16x16x32_bf16 v[56:59], v[140:143], v[180:183], v[56:59]
	v_mfma_f32_16x16x32_bf16 v[40:43], v[132:135], v[188:191], v[40:43]
	v_mfma_f32_16x16x32_bf16 v[60:63], v[140:143], v[188:191], v[60:63]
	v_mfma_f32_16x16x32_bf16 v[20:23], v[144:147], v[160:163], v[20:23]
	v_mfma_f32_16x16x32_bf16 v[4:7], v[152:155], v[160:163], v[4:7]
	v_mfma_f32_16x16x32_bf16 v[28:31], v[144:147], v[168:171], v[28:31]
	v_mfma_f32_16x16x32_bf16 v[0:3], v[152:155], v[168:171], v[0:3]
	v_mfma_f32_16x16x32_bf16 v[36:39], v[144:147], v[176:179], v[36:39]
	v_mfma_f32_16x16x32_bf16 v[8:11], v[152:155], v[176:179], v[8:11]
	v_mfma_f32_16x16x32_bf16 v[48:51], v[144:147], v[184:187], v[48:51]
	v_mfma_f32_16x16x32_bf16 v[12:15], v[152:155], v[184:187], v[12:15]
	v_mfma_f32_16x16x32_bf16 v[20:23], v[148:151], v[164:167], v[20:23]
	v_mfma_f32_16x16x32_bf16 v[4:7], v[156:159], v[164:167], v[4:7]
	v_mfma_f32_16x16x32_bf16 v[28:31], v[148:151], v[172:175], v[28:31]
	v_mfma_f32_16x16x32_bf16 v[0:3], v[156:159], v[172:175], v[0:3]
	v_mfma_f32_16x16x32_bf16 v[36:39], v[148:151], v[180:183], v[36:39]
	v_mfma_f32_16x16x32_bf16 v[8:11], v[156:159], v[180:183], v[8:11]
	v_mfma_f32_16x16x32_bf16 v[48:51], v[148:151], v[188:191], v[48:51]
	v_mfma_f32_16x16x32_bf16 v[12:15], v[156:159], v[188:191], v[12:15]
	s_barrier
	s_add_i32 s49, 0, 0x18000
	s_add_i32 s70, 0, 0x1c000
	v_add_u32_e32 v140, s49, v248
	v_add_u32_e32 v156, s70, v248
	ds_read_b128 v[128:131], v140
	ds_read_b128 v[132:135], v140 offset:1024
	ds_read_b128 v[136:139], v140 offset:2048
	ds_read_b128 v[140:143], v140 offset:3072
	ds_read_b128 v[144:147], v156
	ds_read_b128 v[148:151], v156 offset:1024
	ds_read_b128 v[152:155], v156 offset:2048
	ds_read_b128 v[156:159], v156 offset:3072
	s_add_u32 s12, s42, 0x80000
	s_addc_u32 s13, s43, 0
	s_mov_b32 m0, s57
	v_lshl_add_u64 v[200:201], s[12:13], 0, v[234:235]
	ds_read_b128 v[160:163], v249 offset:32768
	ds_read_b128 v[164:167], v249 offset:33792
	ds_read_b128 v[168:171], v249 offset:34816
	ds_read_b128 v[172:175], v249 offset:35840
	ds_read_b128 v[176:179], v249 offset:36864
	ds_read_b128 v[180:183], v249 offset:37888
	ds_read_b128 v[184:187], v249 offset:38912
	ds_read_b128 v[188:191], v249 offset:39936
	global_load_lds_dwordx4 v[200:201], off
	s_mov_b32 m0, s58
	v_lshl_add_u64 v[200:201], s[12:13], 0, v[232:233]
	global_load_lds_dwordx4 v[200:201], off
	s_waitcnt vmcnt(8) lgkmcnt(0)
	s_barrier
	v_mfma_f32_16x16x32_bf16 v[100:103], v[128:131], v[160:163], v[100:103]
	v_mfma_f32_16x16x32_bf16 v[116:119], v[136:139], v[160:163], v[116:119]
	v_mfma_f32_16x16x32_bf16 v[96:99], v[128:131], v[168:171], v[96:99]
	v_mfma_f32_16x16x32_bf16 v[112:115], v[136:139], v[168:171], v[112:115]
	v_mfma_f32_16x16x32_bf16 v[104:107], v[128:131], v[176:179], v[104:107]
	v_mfma_f32_16x16x32_bf16 v[120:123], v[136:139], v[176:179], v[120:123]
	v_mfma_f32_16x16x32_bf16 v[108:111], v[128:131], v[184:187], v[108:111]
	v_mfma_f32_16x16x32_bf16 v[124:127], v[136:139], v[184:187], v[124:127]
	v_mfma_f32_16x16x32_bf16 v[100:103], v[132:135], v[164:167], v[100:103]
	v_mfma_f32_16x16x32_bf16 v[116:119], v[140:143], v[164:167], v[116:119]
	v_mfma_f32_16x16x32_bf16 v[96:99], v[132:135], v[172:175], v[96:99]
	v_mfma_f32_16x16x32_bf16 v[112:115], v[140:143], v[172:175], v[112:115]
	v_mfma_f32_16x16x32_bf16 v[104:107], v[132:135], v[180:183], v[104:107]
	v_mfma_f32_16x16x32_bf16 v[120:123], v[140:143], v[180:183], v[120:123]
	v_mfma_f32_16x16x32_bf16 v[108:111], v[132:135], v[188:191], v[108:111]
	v_mfma_f32_16x16x32_bf16 v[124:127], v[140:143], v[188:191], v[124:127]
	v_mfma_f32_16x16x32_bf16 v[84:87], v[144:147], v[160:163], v[84:87]
	v_mfma_f32_16x16x32_bf16 v[68:71], v[152:155], v[160:163], v[68:71]
	v_mfma_f32_16x16x32_bf16 v[80:83], v[144:147], v[168:171], v[80:83]
	v_mfma_f32_16x16x32_bf16 v[64:67], v[152:155], v[168:171], v[64:67]
	v_mfma_f32_16x16x32_bf16 v[88:91], v[144:147], v[176:179], v[88:91]
	v_mfma_f32_16x16x32_bf16 v[72:75], v[152:155], v[176:179], v[72:75]
	v_mfma_f32_16x16x32_bf16 v[92:95], v[144:147], v[184:187], v[92:95]
	v_mfma_f32_16x16x32_bf16 v[76:79], v[152:155], v[184:187], v[76:79]
	v_mfma_f32_16x16x32_bf16 v[84:87], v[148:151], v[164:167], v[84:87]
	v_mfma_f32_16x16x32_bf16 v[68:71], v[156:159], v[164:167], v[68:71]
	v_mfma_f32_16x16x32_bf16 v[80:83], v[148:151], v[172:175], v[80:83]
	v_mfma_f32_16x16x32_bf16 v[64:67], v[156:159], v[172:175], v[64:67]
	v_mfma_f32_16x16x32_bf16 v[88:91], v[148:151], v[180:183], v[88:91]
	v_mfma_f32_16x16x32_bf16 v[72:75], v[156:159], v[180:183], v[72:75]
	v_mfma_f32_16x16x32_bf16 v[92:95], v[148:151], v[188:191], v[92:95]
	v_mfma_f32_16x16x32_bf16 v[76:79], v[156:159], v[188:191], v[76:79]
	s_barrier
	s_add_i32 s12, s49, s53
	v_lshl_add_u64 v[192:193], v[192:193], 0, s[24:25]
	s_mov_b32 m0, s12
	ds_read_b128 v[160:163], v249 offset:49152
	ds_read_b128 v[164:167], v249 offset:50176
	ds_read_b128 v[168:171], v249 offset:51200
	ds_read_b128 v[172:175], v249 offset:52224
	ds_read_b128 v[176:179], v249 offset:53248
	ds_read_b128 v[180:183], v249 offset:54272
	ds_read_b128 v[184:187], v249 offset:55296
	ds_read_b128 v[188:191], v249 offset:56320
	global_load_lds_dwordx4 v[192:193], off
	s_add_i32 m0, s12, 0x2000
	s_add_u32 s12, s28, 0x80080
	v_lshl_add_u64 v[192:193], v[194:195], 0, s[24:25]
	s_addc_u32 s13, s29, 0
	s_add_i32 s28, s70, s53
	global_load_lds_dwordx4 v[192:193], off
	s_mov_b32 m0, s28
	v_lshl_add_u64 v[192:193], s[12:13], 0, v[224:225]
	global_load_lds_dwordx4 v[192:193], off
	s_add_i32 m0, s28, 0x2000
	v_lshl_add_u64 v[192:193], s[12:13], 0, v[230:231]
	global_load_lds_dwordx4 v[192:193], off
	s_mov_b32 m0, s63
	v_lshl_add_u64 v[192:193], v[196:197], 0, s[24:25]
	global_load_lds_dwordx4 v[192:193], off
	s_mov_b32 m0, s64
	v_lshl_add_u64 v[192:193], v[198:199], 0, s[24:25]
	global_load_lds_dwordx4 v[192:193], off
	s_waitcnt vmcnt(8) lgkmcnt(0)
	s_barrier
	v_mfma_f32_16x16x32_bf16 v[16:19], v[128:131], v[160:163], v[16:19]
	v_mfma_f32_16x16x32_bf16 v[44:47], v[136:139], v[160:163], v[44:47]
	v_mfma_f32_16x16x32_bf16 v[24:27], v[128:131], v[168:171], v[24:27]
	v_mfma_f32_16x16x32_bf16 v[52:55], v[136:139], v[168:171], v[52:55]
	v_mfma_f32_16x16x32_bf16 v[32:35], v[128:131], v[176:179], v[32:35]
	v_mfma_f32_16x16x32_bf16 v[56:59], v[136:139], v[176:179], v[56:59]
	v_mfma_f32_16x16x32_bf16 v[40:43], v[128:131], v[184:187], v[40:43]
	v_mfma_f32_16x16x32_bf16 v[60:63], v[136:139], v[184:187], v[60:63]
	v_mfma_f32_16x16x32_bf16 v[16:19], v[132:135], v[164:167], v[16:19]
	v_mfma_f32_16x16x32_bf16 v[44:47], v[140:143], v[164:167], v[44:47]
	v_mfma_f32_16x16x32_bf16 v[24:27], v[132:135], v[172:175], v[24:27]
	v_mfma_f32_16x16x32_bf16 v[52:55], v[140:143], v[172:175], v[52:55]
	v_mfma_f32_16x16x32_bf16 v[32:35], v[132:135], v[180:183], v[32:35]
	v_mfma_f32_16x16x32_bf16 v[56:59], v[140:143], v[180:183], v[56:59]
	v_mfma_f32_16x16x32_bf16 v[40:43], v[132:135], v[188:191], v[40:43]
	v_mfma_f32_16x16x32_bf16 v[60:63], v[140:143], v[188:191], v[60:63]
	v_mfma_f32_16x16x32_bf16 v[20:23], v[144:147], v[160:163], v[20:23]
	v_mfma_f32_16x16x32_bf16 v[4:7], v[152:155], v[160:163], v[4:7]
	v_mfma_f32_16x16x32_bf16 v[28:31], v[144:147], v[168:171], v[28:31]
	v_mfma_f32_16x16x32_bf16 v[0:3], v[152:155], v[168:171], v[0:3]
	v_mfma_f32_16x16x32_bf16 v[36:39], v[144:147], v[176:179], v[36:39]
	v_mfma_f32_16x16x32_bf16 v[8:11], v[152:155], v[176:179], v[8:11]
	v_mfma_f32_16x16x32_bf16 v[48:51], v[144:147], v[184:187], v[48:51]
	v_mfma_f32_16x16x32_bf16 v[12:15], v[152:155], v[184:187], v[12:15]
	v_mfma_f32_16x16x32_bf16 v[20:23], v[148:151], v[164:167], v[20:23]
	v_mfma_f32_16x16x32_bf16 v[4:7], v[156:159], v[164:167], v[4:7]
	v_mfma_f32_16x16x32_bf16 v[28:31], v[148:151], v[172:175], v[28:31]
	v_mfma_f32_16x16x32_bf16 v[0:3], v[156:159], v[172:175], v[0:3]
	v_mfma_f32_16x16x32_bf16 v[36:39], v[148:151], v[180:183], v[36:39]
	v_mfma_f32_16x16x32_bf16 v[8:11], v[156:159], v[180:183], v[8:11]
	v_mfma_f32_16x16x32_bf16 v[48:51], v[148:151], v[188:191], v[48:51]
	v_mfma_f32_16x16x32_bf16 v[12:15], v[156:159], v[188:191], v[12:15]
	s_barrier
	s_add_u32 s35, s35, 0x100
	s_addc_u32 s37, s37, 0
	s_cmp_ge_i32 s48, s62
	s_mov_b64 s[12:13], s[8:9]
	s_mov_b32 s28, s48
	s_cbranch_scc0 .LBB0_2049

.LBB0_2092:
	s_add_i32 s58, s8, 2
	s_add_u32 s9, s12, 0xffff0080
	s_addc_u32 s28, s13, -1
	s_add_i32 s59, 0, 0x10000
	s_cmp_eq_u32 s50, s8
	s_cselect_b32 s29, s27, s28
	s_cselect_b32 s28, s35, s9
	s_cselect_b32 s9, s54, s57
	s_cselect_b32 s8, s55, s56
	s_add_i32 s62, 0, 0x14000
	v_add_u32_e32 v152, s59, v138
	v_add_u32_e32 v168, s62, v138
	ds_read_b128 v[140:143], v152
	ds_read_b128 v[144:147], v152 offset:1024
	ds_read_b128 v[148:151], v152 offset:2048
	ds_read_b128 v[152:155], v152 offset:3072
	ds_read_b128 v[156:159], v168
	ds_read_b128 v[160:163], v168 offset:1024
	ds_read_b128 v[164:167], v168 offset:2048
	ds_read_b128 v[168:171], v168 offset:3072
	v_lshl_add_u64 v[204:205], s[12:13], 0, v[134:135]
	s_add_i32 m0, s31, 0xc000
	ds_read_b128 v[172:175], v139
	ds_read_b128 v[176:179], v139 offset:1024
	ds_read_b128 v[180:183], v139 offset:2048
	ds_read_b128 v[184:187], v139 offset:3072
	ds_read_b128 v[188:191], v139 offset:4096
	ds_read_b128 v[192:195], v139 offset:5120
	ds_read_b128 v[196:199], v139 offset:6144
	ds_read_b128 v[200:203], v139 offset:7168
	global_load_lds_dwordx4 v[204:205], off
	s_add_i32 m0, s31, 0xe000
	v_lshl_add_u64 v[204:205], s[12:13], 0, v[136:137]
	global_load_lds_dwordx4 v[204:205], off
	s_waitcnt vmcnt(8) lgkmcnt(0)
	s_barrier
	v_mfma_f32_16x16x32_bf16 v[112:115], v[140:143], v[172:175], v[112:115]
	v_mfma_f32_16x16x32_bf16 v[116:119], v[148:151], v[172:175], v[116:119]
	v_mfma_f32_16x16x32_bf16 v[96:99], v[140:143], v[180:183], v[96:99]
	v_mfma_f32_16x16x32_bf16 v[100:103], v[148:151], v[180:183], v[100:103]
	v_mfma_f32_16x16x32_bf16 v[80:83], v[140:143], v[188:191], v[80:83]
	v_mfma_f32_16x16x32_bf16 v[84:87], v[148:151], v[188:191], v[84:87]
	v_mfma_f32_16x16x32_bf16 v[48:51], v[140:143], v[196:199], v[48:51]
	v_mfma_f32_16x16x32_bf16 v[52:55], v[148:151], v[196:199], v[52:55]
	v_mfma_f32_16x16x32_bf16 v[112:115], v[144:147], v[176:179], v[112:115]
	v_mfma_f32_16x16x32_bf16 v[116:119], v[152:155], v[176:179], v[116:119]
	v_mfma_f32_16x16x32_bf16 v[96:99], v[144:147], v[184:187], v[96:99]
	v_mfma_f32_16x16x32_bf16 v[100:103], v[152:155], v[184:187], v[100:103]
	v_mfma_f32_16x16x32_bf16 v[80:83], v[144:147], v[192:195], v[80:83]
	v_mfma_f32_16x16x32_bf16 v[84:87], v[152:155], v[192:195], v[84:87]
	v_mfma_f32_16x16x32_bf16 v[48:51], v[144:147], v[200:203], v[48:51]
	v_mfma_f32_16x16x32_bf16 v[52:55], v[152:155], v[200:203], v[52:55]
	v_mfma_f32_16x16x32_bf16 v[120:123], v[156:159], v[172:175], v[120:123]
	v_mfma_f32_16x16x32_bf16 v[124:127], v[164:167], v[172:175], v[124:127]
	v_mfma_f32_16x16x32_bf16 v[104:107], v[156:159], v[180:183], v[104:107]
	v_mfma_f32_16x16x32_bf16 v[108:111], v[164:167], v[180:183], v[108:111]
	v_mfma_f32_16x16x32_bf16 v[88:91], v[156:159], v[188:191], v[88:91]
	v_mfma_f32_16x16x32_bf16 v[92:95], v[164:167], v[188:191], v[92:95]
	v_mfma_f32_16x16x32_bf16 v[64:67], v[156:159], v[196:199], v[64:67]
	v_mfma_f32_16x16x32_bf16 v[68:71], v[164:167], v[196:199], v[68:71]
	v_mfma_f32_16x16x32_bf16 v[120:123], v[160:163], v[176:179], v[120:123]
	v_mfma_f32_16x16x32_bf16 v[124:127], v[168:171], v[176:179], v[124:127]
	v_mfma_f32_16x16x32_bf16 v[104:107], v[160:163], v[184:187], v[104:107]
	v_mfma_f32_16x16x32_bf16 v[108:111], v[168:171], v[184:187], v[108:111]
	v_mfma_f32_16x16x32_bf16 v[88:91], v[160:163], v[192:195], v[88:91]
	v_mfma_f32_16x16x32_bf16 v[92:95], v[168:171], v[192:195], v[92:95]
	v_mfma_f32_16x16x32_bf16 v[64:67], v[160:163], v[200:203], v[64:67]
	v_mfma_f32_16x16x32_bf16 v[68:71], v[168:171], v[200:203], v[68:71]
	s_barrier
	s_add_i32 s59, s59, s10
	v_lshl_add_u64 v[204:205], s[8:9], 0, v[224:225]
	s_mov_b32 m0, s59
	ds_read_b128 v[172:175], v139 offset:16384
	ds_read_b128 v[176:179], v139 offset:17408
	ds_read_b128 v[180:183], v139 offset:18432
	ds_read_b128 v[184:187], v139 offset:19456
	ds_read_b128 v[188:191], v139 offset:20480
	ds_read_b128 v[192:195], v139 offset:21504
	ds_read_b128 v[196:199], v139 offset:22528
	ds_read_b128 v[200:203], v139 offset:23552
	global_load_lds_dwordx4 v[204:205], off
	s_add_i32 m0, s59, 0x2000
	s_add_u32 s60, s8, 0x10000
	v_lshl_add_u64 v[206:207], s[8:9], 0, v[128:129]
	s_addc_u32 s61, s9, 0
	s_add_i32 s59, s62, s10
	global_load_lds_dwordx4 v[206:207], off
	v_lshl_add_u64 v[208:209], s[60:61], 0, v[224:225]
	s_mov_b32 m0, s59
	v_lshl_add_u64 v[210:211], s[28:29], 0, v[130:131]
	global_load_lds_dwordx4 v[208:209], off
	s_add_i32 m0, s59, 0x2000
	v_lshl_add_u64 v[208:209], s[60:61], 0, v[128:129]
	global_load_lds_dwordx4 v[208:209], off
	s_mov_b32 m0, s31
	v_lshl_add_u64 v[208:209], s[28:29], 0, v[132:133]
	global_load_lds_dwordx4 v[208:209], off
	s_mov_b32 m0, s33
	s_nop 0
	global_load_lds_dwordx4 v[210:211], off
	s_waitcnt vmcnt(8) lgkmcnt(0)
	s_barrier
	v_mfma_f32_16x16x32_bf16 v[56:59], v[140:143], v[172:175], v[56:59]
	v_mfma_f32_16x16x32_bf16 v[60:63], v[148:151], v[172:175], v[60:63]
	v_mfma_f32_16x16x32_bf16 v[32:35], v[140:143], v[180:183], v[32:35]
	v_mfma_f32_16x16x32_bf16 v[36:39], v[148:151], v[180:183], v[36:39]
	v_mfma_f32_16x16x32_bf16 v[16:19], v[140:143], v[188:191], v[16:19]
	v_mfma_f32_16x16x32_bf16 v[20:23], v[148:151], v[188:191], v[20:23]
	v_mfma_f32_16x16x32_bf16 v[0:3], v[140:143], v[196:199], v[0:3]
	v_mfma_f32_16x16x32_bf16 v[4:7], v[148:151], v[196:199], v[4:7]
	v_mfma_f32_16x16x32_bf16 v[56:59], v[144:147], v[176:179], v[56:59]
	v_mfma_f32_16x16x32_bf16 v[60:63], v[152:155], v[176:179], v[60:63]
	v_mfma_f32_16x16x32_bf16 v[32:35], v[144:147], v[184:187], v[32:35]
	v_mfma_f32_16x16x32_bf16 v[36:39], v[152:155], v[184:187], v[36:39]
	v_mfma_f32_16x16x32_bf16 v[16:19], v[144:147], v[192:195], v[16:19]
	v_mfma_f32_16x16x32_bf16 v[20:23], v[152:155], v[192:195], v[20:23]
	v_mfma_f32_16x16x32_bf16 v[0:3], v[144:147], v[200:203], v[0:3]
	v_mfma_f32_16x16x32_bf16 v[4:7], v[152:155], v[200:203], v[4:7]
	v_mfma_f32_16x16x32_bf16 v[72:75], v[156:159], v[172:175], v[72:75]
	v_mfma_f32_16x16x32_bf16 v[76:79], v[164:167], v[172:175], v[76:79]
	v_mfma_f32_16x16x32_bf16 v[40:43], v[156:159], v[180:183], v[40:43]
	v_mfma_f32_16x16x32_bf16 v[44:47], v[164:167], v[180:183], v[44:47]
	v_mfma_f32_16x16x32_bf16 v[24:27], v[156:159], v[188:191], v[24:27]
	v_mfma_f32_16x16x32_bf16 v[28:31], v[164:167], v[188:191], v[28:31]
	v_mfma_f32_16x16x32_bf16 v[8:11], v[156:159], v[196:199], v[8:11]
	v_mfma_f32_16x16x32_bf16 v[12:15], v[164:167], v[196:199], v[12:15]
	v_mfma_f32_16x16x32_bf16 v[72:75], v[160:163], v[176:179], v[72:75]
	v_mfma_f32_16x16x32_bf16 v[76:79], v[168:171], v[176:179], v[76:79]
	v_mfma_f32_16x16x32_bf16 v[40:43], v[160:163], v[184:187], v[40:43]
	v_mfma_f32_16x16x32_bf16 v[44:47], v[168:171], v[184:187], v[44:47]
	v_mfma_f32_16x16x32_bf16 v[24:27], v[160:163], v[192:195], v[24:27]
	v_mfma_f32_16x16x32_bf16 v[28:31], v[168:171], v[192:195], v[28:31]
	v_mfma_f32_16x16x32_bf16 v[8:11], v[160:163], v[200:203], v[8:11]
	v_mfma_f32_16x16x32_bf16 v[12:15], v[168:171], v[200:203], v[12:15]
	s_barrier
	s_add_i32 s59, 0, 0x18000
	s_add_i32 s60, 0, 0x1c000
	v_add_u32_e32 v152, s59, v138
	v_add_u32_e32 v168, s60, v138
	ds_read_b128 v[140:143], v152
	ds_read_b128 v[144:147], v152 offset:1024
	ds_read_b128 v[148:151], v152 offset:2048
	ds_read_b128 v[152:155], v152 offset:3072
	ds_read_b128 v[156:159], v168
	ds_read_b128 v[160:163], v168 offset:1024
	ds_read_b128 v[164:167], v168 offset:2048
	ds_read_b128 v[168:171], v168 offset:3072
	s_add_u32 s28, s28, 0x10000
	s_addc_u32 s29, s29, 0
	s_mov_b32 m0, s44
	v_lshl_add_u64 v[212:213], s[28:29], 0, v[132:133]
	ds_read_b128 v[172:175], v139 offset:32768
	ds_read_b128 v[176:179], v139 offset:33792
	ds_read_b128 v[180:183], v139 offset:34816
	ds_read_b128 v[184:187], v139 offset:35840
	ds_read_b128 v[188:191], v139 offset:36864
	ds_read_b128 v[192:195], v139 offset:37888
	ds_read_b128 v[196:199], v139 offset:38912
	ds_read_b128 v[200:203], v139 offset:39936
	global_load_lds_dwordx4 v[212:213], off
	s_mov_b32 m0, s45
	v_lshl_add_u64 v[212:213], s[28:29], 0, v[130:131]
	global_load_lds_dwordx4 v[212:213], off
	s_waitcnt vmcnt(8) lgkmcnt(0)
	s_barrier
	v_mfma_f32_16x16x32_bf16 v[112:115], v[140:143], v[172:175], v[112:115]
	v_mfma_f32_16x16x32_bf16 v[116:119], v[148:151], v[172:175], v[116:119]
	v_mfma_f32_16x16x32_bf16 v[96:99], v[140:143], v[180:183], v[96:99]
	v_mfma_f32_16x16x32_bf16 v[100:103], v[148:151], v[180:183], v[100:103]
	v_mfma_f32_16x16x32_bf16 v[80:83], v[140:143], v[188:191], v[80:83]
	v_mfma_f32_16x16x32_bf16 v[84:87], v[148:151], v[188:191], v[84:87]
	v_mfma_f32_16x16x32_bf16 v[48:51], v[140:143], v[196:199], v[48:51]
	v_mfma_f32_16x16x32_bf16 v[52:55], v[148:151], v[196:199], v[52:55]
	v_mfma_f32_16x16x32_bf16 v[112:115], v[144:147], v[176:179], v[112:115]
	v_mfma_f32_16x16x32_bf16 v[116:119], v[152:155], v[176:179], v[116:119]
	v_mfma_f32_16x16x32_bf16 v[96:99], v[144:147], v[184:187], v[96:99]
	v_mfma_f32_16x16x32_bf16 v[100:103], v[152:155], v[184:187], v[100:103]
	v_mfma_f32_16x16x32_bf16 v[80:83], v[144:147], v[192:195], v[80:83]
	v_mfma_f32_16x16x32_bf16 v[84:87], v[152:155], v[192:195], v[84:87]
	v_mfma_f32_16x16x32_bf16 v[48:51], v[144:147], v[200:203], v[48:51]
	v_mfma_f32_16x16x32_bf16 v[52:55], v[152:155], v[200:203], v[52:55]
	v_mfma_f32_16x16x32_bf16 v[120:123], v[156:159], v[172:175], v[120:123]
	v_mfma_f32_16x16x32_bf16 v[124:127], v[164:167], v[172:175], v[124:127]
	v_mfma_f32_16x16x32_bf16 v[104:107], v[156:159], v[180:183], v[104:107]
	v_mfma_f32_16x16x32_bf16 v[108:111], v[164:167], v[180:183], v[108:111]
	v_mfma_f32_16x16x32_bf16 v[88:91], v[156:159], v[188:191], v[88:91]
	v_mfma_f32_16x16x32_bf16 v[92:95], v[164:167], v[188:191], v[92:95]
	v_mfma_f32_16x16x32_bf16 v[64:67], v[156:159], v[196:199], v[64:67]
	v_mfma_f32_16x16x32_bf16 v[68:71], v[164:167], v[196:199], v[68:71]
	v_mfma_f32_16x16x32_bf16 v[120:123], v[160:163], v[176:179], v[120:123]
	v_mfma_f32_16x16x32_bf16 v[124:127], v[168:171], v[176:179], v[124:127]
	v_mfma_f32_16x16x32_bf16 v[104:107], v[160:163], v[184:187], v[104:107]
	v_mfma_f32_16x16x32_bf16 v[108:111], v[168:171], v[184:187], v[108:111]
	v_mfma_f32_16x16x32_bf16 v[88:91], v[160:163], v[192:195], v[88:91]
	v_mfma_f32_16x16x32_bf16 v[92:95], v[168:171], v[192:195], v[92:95]
	v_mfma_f32_16x16x32_bf16 v[64:67], v[160:163], v[200:203], v[64:67]
	v_mfma_f32_16x16x32_bf16 v[68:71], v[168:171], v[200:203], v[68:71]
	s_barrier
	s_add_i32 s28, s59, s10
	v_lshl_add_u64 v[204:205], v[204:205], 0, s[24:25]
	s_mov_b32 m0, s28
	ds_read_b128 v[172:175], v139 offset:49152
	ds_read_b128 v[176:179], v139 offset:50176
	ds_read_b128 v[180:183], v139 offset:51200
	ds_read_b128 v[184:187], v139 offset:52224
	ds_read_b128 v[188:191], v139 offset:53248
	ds_read_b128 v[192:195], v139 offset:54272
	ds_read_b128 v[196:199], v139 offset:55296
	ds_read_b128 v[200:203], v139 offset:56320
	global_load_lds_dwordx4 v[204:205], off
	s_add_i32 m0, s28, 0x2000
	s_add_u32 s8, s8, 0x10080
	v_lshl_add_u64 v[204:205], v[206:207], 0, s[24:25]
	s_addc_u32 s9, s9, 0
	s_add_i32 s28, s60, s10
	global_load_lds_dwordx4 v[204:205], off
	s_mov_b32 m0, s28
	v_lshl_add_u64 v[204:205], s[8:9], 0, v[224:225]
	global_load_lds_dwordx4 v[204:205], off
	s_add_i32 m0, s28, 0x2000
	v_lshl_add_u64 v[204:205], s[8:9], 0, v[128:129]
	global_load_lds_dwordx4 v[204:205], off
	s_mov_b32 m0, s48
	v_lshl_add_u64 v[204:205], v[208:209], 0, s[24:25]
	global_load_lds_dwordx4 v[204:205], off
	s_mov_b32 m0, s49
	v_lshl_add_u64 v[204:205], v[210:211], 0, s[24:25]
	global_load_lds_dwordx4 v[204:205], off
	s_waitcnt vmcnt(8) lgkmcnt(0)
	s_barrier
	v_mfma_f32_16x16x32_bf16 v[56:59], v[140:143], v[172:175], v[56:59]
	v_mfma_f32_16x16x32_bf16 v[60:63], v[148:151], v[172:175], v[60:63]
	v_mfma_f32_16x16x32_bf16 v[32:35], v[140:143], v[180:183], v[32:35]
	v_mfma_f32_16x16x32_bf16 v[36:39], v[148:151], v[180:183], v[36:39]
	v_mfma_f32_16x16x32_bf16 v[16:19], v[140:143], v[188:191], v[16:19]
	v_mfma_f32_16x16x32_bf16 v[20:23], v[148:151], v[188:191], v[20:23]
	v_mfma_f32_16x16x32_bf16 v[0:3], v[140:143], v[196:199], v[0:3]
	v_mfma_f32_16x16x32_bf16 v[4:7], v[148:151], v[196:199], v[4:7]
	v_mfma_f32_16x16x32_bf16 v[56:59], v[144:147], v[176:179], v[56:59]
	v_mfma_f32_16x16x32_bf16 v[60:63], v[152:155], v[176:179], v[60:63]
	v_mfma_f32_16x16x32_bf16 v[32:35], v[144:147], v[184:187], v[32:35]
	v_mfma_f32_16x16x32_bf16 v[36:39], v[152:155], v[184:187], v[36:39]
	v_mfma_f32_16x16x32_bf16 v[16:19], v[144:147], v[192:195], v[16:19]
	v_mfma_f32_16x16x32_bf16 v[20:23], v[152:155], v[192:195], v[20:23]
	v_mfma_f32_16x16x32_bf16 v[0:3], v[144:147], v[200:203], v[0:3]
	v_mfma_f32_16x16x32_bf16 v[4:7], v[152:155], v[200:203], v[4:7]
	v_mfma_f32_16x16x32_bf16 v[72:75], v[156:159], v[172:175], v[72:75]
	v_mfma_f32_16x16x32_bf16 v[76:79], v[164:167], v[172:175], v[76:79]
	v_mfma_f32_16x16x32_bf16 v[40:43], v[156:159], v[180:183], v[40:43]
	v_mfma_f32_16x16x32_bf16 v[44:47], v[164:167], v[180:183], v[44:47]
	v_mfma_f32_16x16x32_bf16 v[24:27], v[156:159], v[188:191], v[24:27]
	v_mfma_f32_16x16x32_bf16 v[28:31], v[164:167], v[188:191], v[28:31]
	v_mfma_f32_16x16x32_bf16 v[8:11], v[156:159], v[196:199], v[8:11]
	v_mfma_f32_16x16x32_bf16 v[12:15], v[164:167], v[196:199], v[12:15]
	v_mfma_f32_16x16x32_bf16 v[72:75], v[160:163], v[176:179], v[72:75]
	v_mfma_f32_16x16x32_bf16 v[76:79], v[168:171], v[176:179], v[76:79]
	v_mfma_f32_16x16x32_bf16 v[40:43], v[160:163], v[184:187], v[40:43]
	v_mfma_f32_16x16x32_bf16 v[44:47], v[168:171], v[184:187], v[44:47]
	v_mfma_f32_16x16x32_bf16 v[24:27], v[160:163], v[192:195], v[24:27]
	v_mfma_f32_16x16x32_bf16 v[28:31], v[168:171], v[192:195], v[28:31]
	v_mfma_f32_16x16x32_bf16 v[8:11], v[160:163], v[200:203], v[8:11]
	v_mfma_f32_16x16x32_bf16 v[12:15], v[168:171], v[200:203], v[12:15]
	s_barrier
	s_add_u32 s12, s12, 0x100
	s_addc_u32 s13, s13, 0
	s_add_u32 s56, s56, 0x100
	s_addc_u32 s57, s57, 0
	s_cmp_ge_i32 s58, s47
	s_mov_b32 s8, s58
	s_cbranch_scc0 .LBB0_2092
	s_mov_b64 s[56:57], 0x400000
	s_mov_b64 s[58:59], 0x3fffff
	s_mov_b64 s[60:61], 0x20000

.LBB0_2239:
	s_add_i32 s30, s28, 2
	s_add_u32 s8, s12, 0x100
	s_addc_u32 s9, s13, 0
	s_add_i32 s31, 0, 0x10000
	s_cmp_eq_u32 s63, s28
	s_cselect_b32 s49, s43, s9
	s_cselect_b32 s48, s42, s8
	s_cselect_b32 s29, s47, s7
	s_cselect_b32 s28, s46, s3
	s_add_i32 s33, 0, 0x14000
	v_add_u32_e32 v100, s31, v230
	v_add_u32_e32 v124, s33, v230
	ds_read_b128 v[84:87], v100
	ds_read_b128 v[88:91], v100 offset:1024
	ds_read_b128 v[96:99], v100 offset:2048
	ds_read_b128 v[100:103], v100 offset:3072
	ds_read_b128 v[112:115], v124
	ds_read_b128 v[116:119], v124 offset:1024
	ds_read_b128 v[120:123], v124 offset:2048
	ds_read_b128 v[124:127], v124 offset:3072
	v_lshl_add_u64 v[202:203], s[12:13], 0, v[198:199]
	s_add_i32 m0, s56, 0xc000
	ds_read_b128 v[160:163], v231
	ds_read_b128 v[164:167], v231 offset:1024
	ds_read_b128 v[168:171], v231 offset:2048
	ds_read_b128 v[172:175], v231 offset:3072
	ds_read_b128 v[176:179], v231 offset:4096
	ds_read_b128 v[180:183], v231 offset:5120
	ds_read_b128 v[184:187], v231 offset:6144
	ds_read_b128 v[188:191], v231 offset:7168
	global_load_lds_dwordx4 v[202:203], off
	s_add_i32 m0, s56, 0xe000
	v_lshl_add_u64 v[202:203], s[12:13], 0, v[200:201]
	global_load_lds_dwordx4 v[202:203], off
	s_waitcnt vmcnt(8) lgkmcnt(0)
	s_barrier
	v_mfma_f32_16x16x32_bf16 v[152:155], v[84:87], v[160:163], v[152:155]
	v_mfma_f32_16x16x32_bf16 v[156:159], v[96:99], v[160:163], v[156:159]
	v_mfma_f32_16x16x32_bf16 v[140:143], v[84:87], v[168:171], v[140:143]
	v_mfma_f32_16x16x32_bf16 v[136:139], v[96:99], v[168:171], v[136:139]
	v_mfma_f32_16x16x32_bf16 v[108:111], v[84:87], v[176:179], v[108:111]
	v_mfma_f32_16x16x32_bf16 v[104:107], v[96:99], v[176:179], v[104:107]
	v_mfma_f32_16x16x32_bf16 v[76:79], v[84:87], v[184:187], v[76:79]
	v_mfma_f32_16x16x32_bf16 v[72:75], v[96:99], v[184:187], v[72:75]
	v_mfma_f32_16x16x32_bf16 v[152:155], v[88:91], v[164:167], v[152:155]
	v_mfma_f32_16x16x32_bf16 v[156:159], v[100:103], v[164:167], v[156:159]
	v_mfma_f32_16x16x32_bf16 v[140:143], v[88:91], v[172:175], v[140:143]
	v_mfma_f32_16x16x32_bf16 v[136:139], v[100:103], v[172:175], v[136:139]
	v_mfma_f32_16x16x32_bf16 v[108:111], v[88:91], v[180:183], v[108:111]
	v_mfma_f32_16x16x32_bf16 v[104:107], v[100:103], v[180:183], v[104:107]
	v_mfma_f32_16x16x32_bf16 v[76:79], v[88:91], v[188:191], v[76:79]
	v_mfma_f32_16x16x32_bf16 v[72:75], v[100:103], v[188:191], v[72:75]
	v_mfma_f32_16x16x32_bf16 v[148:151], v[112:115], v[160:163], v[148:151]
	v_mfma_f32_16x16x32_bf16 v[144:147], v[120:123], v[160:163], v[144:147]
	v_mfma_f32_16x16x32_bf16 v[132:135], v[112:115], v[168:171], v[132:135]
	v_mfma_f32_16x16x32_bf16 v[128:131], v[120:123], v[168:171], v[128:131]
	v_mfma_f32_16x16x32_bf16 v[92:95], v[112:115], v[176:179], v[92:95]
	v_mfma_f32_16x16x32_bf16 v[80:83], v[120:123], v[176:179], v[80:83]
	v_mfma_f32_16x16x32_bf16 v[68:71], v[112:115], v[184:187], v[68:71]
	v_mfma_f32_16x16x32_bf16 v[64:67], v[120:123], v[184:187], v[64:67]
	v_mfma_f32_16x16x32_bf16 v[148:151], v[116:119], v[164:167], v[148:151]
	v_mfma_f32_16x16x32_bf16 v[144:147], v[124:127], v[164:167], v[144:147]
	v_mfma_f32_16x16x32_bf16 v[132:135], v[116:119], v[172:175], v[132:135]
	v_mfma_f32_16x16x32_bf16 v[128:131], v[124:127], v[172:175], v[128:131]
	v_mfma_f32_16x16x32_bf16 v[92:95], v[116:119], v[180:183], v[92:95]
	v_mfma_f32_16x16x32_bf16 v[80:83], v[124:127], v[180:183], v[80:83]
	v_mfma_f32_16x16x32_bf16 v[68:71], v[116:119], v[188:191], v[68:71]
	v_mfma_f32_16x16x32_bf16 v[64:67], v[124:127], v[188:191], v[64:67]
	s_barrier
	s_add_i32 s12, s31, s54
	v_lshl_add_u64 v[202:203], s[28:29], 0, v[224:225]
	s_mov_b32 m0, s12
	ds_read_b128 v[160:163], v231 offset:16384
	ds_read_b128 v[164:167], v231 offset:17408
	ds_read_b128 v[168:171], v231 offset:18432
	ds_read_b128 v[172:175], v231 offset:19456
	ds_read_b128 v[176:179], v231 offset:20480
	ds_read_b128 v[180:183], v231 offset:21504
	ds_read_b128 v[184:187], v231 offset:22528
	ds_read_b128 v[188:191], v231 offset:23552
	global_load_lds_dwordx4 v[202:203], off
	s_add_i32 m0, s12, 0x2000
	s_add_u32 s12, s28, 0x158000
	v_lshl_add_u64 v[204:205], s[28:29], 0, v[192:193]
	s_addc_u32 s13, s29, 0
	s_add_i32 s31, s33, s54
	global_load_lds_dwordx4 v[204:205], off
	v_lshl_add_u64 v[206:207], s[12:13], 0, v[224:225]
	s_mov_b32 m0, s31
	v_lshl_add_u64 v[208:209], s[48:49], 0, v[194:195]
	global_load_lds_dwordx4 v[206:207], off
	s_add_i32 m0, s31, 0x2000
	v_lshl_add_u64 v[206:207], s[12:13], 0, v[192:193]
	global_load_lds_dwordx4 v[206:207], off
	s_mov_b32 m0, s56
	v_lshl_add_u64 v[206:207], s[48:49], 0, v[196:197]
	global_load_lds_dwordx4 v[206:207], off
	s_mov_b32 m0, s57
	s_nop 0
	global_load_lds_dwordx4 v[208:209], off
	s_waitcnt vmcnt(8) lgkmcnt(0)
	s_barrier
	v_mfma_f32_16x16x32_bf16 v[60:63], v[84:87], v[160:163], v[60:63]
	v_mfma_f32_16x16x32_bf16 v[56:59], v[96:99], v[160:163], v[56:59]
	v_mfma_f32_16x16x32_bf16 v[44:47], v[84:87], v[168:171], v[44:47]
	v_mfma_f32_16x16x32_bf16 v[40:43], v[96:99], v[168:171], v[40:43]
	v_mfma_f32_16x16x32_bf16 v[28:31], v[84:87], v[176:179], v[28:31]
	v_mfma_f32_16x16x32_bf16 v[24:27], v[96:99], v[176:179], v[24:27]
	v_mfma_f32_16x16x32_bf16 v[12:15], v[84:87], v[184:187], v[12:15]
	v_mfma_f32_16x16x32_bf16 v[8:11], v[96:99], v[184:187], v[8:11]
	v_mfma_f32_16x16x32_bf16 v[60:63], v[88:91], v[164:167], v[60:63]
	v_mfma_f32_16x16x32_bf16 v[56:59], v[100:103], v[164:167], v[56:59]
	v_mfma_f32_16x16x32_bf16 v[44:47], v[88:91], v[172:175], v[44:47]
	v_mfma_f32_16x16x32_bf16 v[40:43], v[100:103], v[172:175], v[40:43]
	v_mfma_f32_16x16x32_bf16 v[28:31], v[88:91], v[180:183], v[28:31]
	v_mfma_f32_16x16x32_bf16 v[24:27], v[100:103], v[180:183], v[24:27]
	v_mfma_f32_16x16x32_bf16 v[12:15], v[88:91], v[188:191], v[12:15]
	v_mfma_f32_16x16x32_bf16 v[8:11], v[100:103], v[188:191], v[8:11]
	v_mfma_f32_16x16x32_bf16 v[52:55], v[112:115], v[160:163], v[52:55]
	v_mfma_f32_16x16x32_bf16 v[48:51], v[120:123], v[160:163], v[48:51]
	v_mfma_f32_16x16x32_bf16 v[36:39], v[112:115], v[168:171], v[36:39]
	v_mfma_f32_16x16x32_bf16 v[32:35], v[120:123], v[168:171], v[32:35]
	v_mfma_f32_16x16x32_bf16 v[20:23], v[112:115], v[176:179], v[20:23]
	v_mfma_f32_16x16x32_bf16 v[16:19], v[120:123], v[176:179], v[16:19]
	v_mfma_f32_16x16x32_bf16 v[4:7], v[112:115], v[184:187], v[4:7]
	v_mfma_f32_16x16x32_bf16 v[0:3], v[120:123], v[184:187], v[0:3]
	v_mfma_f32_16x16x32_bf16 v[52:55], v[116:119], v[164:167], v[52:55]
	v_mfma_f32_16x16x32_bf16 v[48:51], v[124:127], v[164:167], v[48:51]
	v_mfma_f32_16x16x32_bf16 v[36:39], v[116:119], v[172:175], v[36:39]
	v_mfma_f32_16x16x32_bf16 v[32:35], v[124:127], v[172:175], v[32:35]
	v_mfma_f32_16x16x32_bf16 v[20:23], v[116:119], v[180:183], v[20:23]
	v_mfma_f32_16x16x32_bf16 v[16:19], v[124:127], v[180:183], v[16:19]
	v_mfma_f32_16x16x32_bf16 v[4:7], v[116:119], v[188:191], v[4:7]
	v_mfma_f32_16x16x32_bf16 v[0:3], v[124:127], v[188:191], v[0:3]
	s_barrier
	s_add_i32 s31, 0, 0x18000
	s_add_i32 s33, 0, 0x1c000
	v_add_u32_e32 v100, s31, v230
	v_add_u32_e32 v124, s33, v230
	ds_read_b128 v[84:87], v100
	ds_read_b128 v[88:91], v100 offset:1024
	ds_read_b128 v[96:99], v100 offset:2048
	ds_read_b128 v[100:103], v100 offset:3072
	ds_read_b128 v[112:115], v124
	ds_read_b128 v[116:119], v124 offset:1024
	ds_read_b128 v[120:123], v124 offset:2048
	ds_read_b128 v[124:127], v124 offset:3072
	s_add_u32 s12, s48, 0x158000
	s_addc_u32 s13, s49, 0
	s_mov_b32 m0, s58
	v_lshl_add_u64 v[210:211], s[12:13], 0, v[196:197]
	ds_read_b128 v[160:163], v231 offset:32768
	ds_read_b128 v[164:167], v231 offset:33792
	ds_read_b128 v[168:171], v231 offset:34816
	ds_read_b128 v[172:175], v231 offset:35840
	ds_read_b128 v[176:179], v231 offset:36864
	ds_read_b128 v[180:183], v231 offset:37888
	ds_read_b128 v[184:187], v231 offset:38912
	ds_read_b128 v[188:191], v231 offset:39936
	global_load_lds_dwordx4 v[210:211], off
	s_mov_b32 m0, s59
	v_lshl_add_u64 v[210:211], s[12:13], 0, v[194:195]
	global_load_lds_dwordx4 v[210:211], off
	s_waitcnt vmcnt(8) lgkmcnt(0)
	s_barrier
	v_mfma_f32_16x16x32_bf16 v[152:155], v[84:87], v[160:163], v[152:155]
	v_mfma_f32_16x16x32_bf16 v[156:159], v[96:99], v[160:163], v[156:159]
	v_mfma_f32_16x16x32_bf16 v[140:143], v[84:87], v[168:171], v[140:143]
	v_mfma_f32_16x16x32_bf16 v[136:139], v[96:99], v[168:171], v[136:139]
	v_mfma_f32_16x16x32_bf16 v[108:111], v[84:87], v[176:179], v[108:111]
	v_mfma_f32_16x16x32_bf16 v[104:107], v[96:99], v[176:179], v[104:107]
	v_mfma_f32_16x16x32_bf16 v[76:79], v[84:87], v[184:187], v[76:79]
	v_mfma_f32_16x16x32_bf16 v[72:75], v[96:99], v[184:187], v[72:75]
	v_mfma_f32_16x16x32_bf16 v[152:155], v[88:91], v[164:167], v[152:155]
	v_mfma_f32_16x16x32_bf16 v[156:159], v[100:103], v[164:167], v[156:159]
	v_mfma_f32_16x16x32_bf16 v[140:143], v[88:91], v[172:175], v[140:143]
	v_mfma_f32_16x16x32_bf16 v[136:139], v[100:103], v[172:175], v[136:139]
	v_mfma_f32_16x16x32_bf16 v[108:111], v[88:91], v[180:183], v[108:111]
	v_mfma_f32_16x16x32_bf16 v[104:107], v[100:103], v[180:183], v[104:107]
	v_mfma_f32_16x16x32_bf16 v[76:79], v[88:91], v[188:191], v[76:79]
	v_mfma_f32_16x16x32_bf16 v[72:75], v[100:103], v[188:191], v[72:75]
	v_mfma_f32_16x16x32_bf16 v[148:151], v[112:115], v[160:163], v[148:151]
	v_mfma_f32_16x16x32_bf16 v[144:147], v[120:123], v[160:163], v[144:147]
	v_mfma_f32_16x16x32_bf16 v[132:135], v[112:115], v[168:171], v[132:135]
	v_mfma_f32_16x16x32_bf16 v[128:131], v[120:123], v[168:171], v[128:131]
	v_mfma_f32_16x16x32_bf16 v[92:95], v[112:115], v[176:179], v[92:95]
	v_mfma_f32_16x16x32_bf16 v[80:83], v[120:123], v[176:179], v[80:83]
	v_mfma_f32_16x16x32_bf16 v[68:71], v[112:115], v[184:187], v[68:71]
	v_mfma_f32_16x16x32_bf16 v[64:67], v[120:123], v[184:187], v[64:67]
	v_mfma_f32_16x16x32_bf16 v[148:151], v[116:119], v[164:167], v[148:151]
	v_mfma_f32_16x16x32_bf16 v[144:147], v[124:127], v[164:167], v[144:147]
	v_mfma_f32_16x16x32_bf16 v[132:135], v[116:119], v[172:175], v[132:135]
	v_mfma_f32_16x16x32_bf16 v[128:131], v[124:127], v[172:175], v[128:131]
	v_mfma_f32_16x16x32_bf16 v[92:95], v[116:119], v[180:183], v[92:95]
	v_mfma_f32_16x16x32_bf16 v[80:83], v[124:127], v[180:183], v[80:83]
	v_mfma_f32_16x16x32_bf16 v[68:71], v[116:119], v[188:191], v[68:71]
	v_mfma_f32_16x16x32_bf16 v[64:67], v[124:127], v[188:191], v[64:67]
	s_barrier
	s_add_i32 s12, s31, s54
	v_lshl_add_u64 v[202:203], v[202:203], 0, s[24:25]
	s_mov_b32 m0, s12
	ds_read_b128 v[160:163], v231 offset:49152
	ds_read_b128 v[164:167], v231 offset:50176
	ds_read_b128 v[168:171], v231 offset:51200
	ds_read_b128 v[172:175], v231 offset:52224
	ds_read_b128 v[176:179], v231 offset:53248
	ds_read_b128 v[180:183], v231 offset:54272
	ds_read_b128 v[184:187], v231 offset:55296
	ds_read_b128 v[188:191], v231 offset:56320
	global_load_lds_dwordx4 v[202:203], off
	s_add_i32 m0, s12, 0x2000
	s_add_u32 s12, s28, 0x158080
	v_lshl_add_u64 v[202:203], v[204:205], 0, s[24:25]
	s_addc_u32 s13, s29, 0
	s_add_i32 s28, s33, s54
	global_load_lds_dwordx4 v[202:203], off
	s_mov_b32 m0, s28
	v_lshl_add_u64 v[202:203], s[12:13], 0, v[224:225]
	global_load_lds_dwordx4 v[202:203], off
	s_add_i32 m0, s28, 0x2000
	v_lshl_add_u64 v[202:203], s[12:13], 0, v[192:193]
	global_load_lds_dwordx4 v[202:203], off
	s_mov_b32 m0, s61
	v_lshl_add_u64 v[202:203], v[206:207], 0, s[24:25]
	global_load_lds_dwordx4 v[202:203], off
	s_mov_b32 m0, s62
	v_lshl_add_u64 v[202:203], v[208:209], 0, s[24:25]
	global_load_lds_dwordx4 v[202:203], off
	s_waitcnt vmcnt(8) lgkmcnt(0)
	s_barrier
	v_mfma_f32_16x16x32_bf16 v[60:63], v[84:87], v[160:163], v[60:63]
	v_mfma_f32_16x16x32_bf16 v[56:59], v[96:99], v[160:163], v[56:59]
	v_mfma_f32_16x16x32_bf16 v[44:47], v[84:87], v[168:171], v[44:47]
	v_mfma_f32_16x16x32_bf16 v[40:43], v[96:99], v[168:171], v[40:43]
	v_mfma_f32_16x16x32_bf16 v[28:31], v[84:87], v[176:179], v[28:31]
	v_mfma_f32_16x16x32_bf16 v[24:27], v[96:99], v[176:179], v[24:27]
	v_mfma_f32_16x16x32_bf16 v[12:15], v[84:87], v[184:187], v[12:15]
	v_mfma_f32_16x16x32_bf16 v[8:11], v[96:99], v[184:187], v[8:11]
	v_mfma_f32_16x16x32_bf16 v[60:63], v[88:91], v[164:167], v[60:63]
	v_mfma_f32_16x16x32_bf16 v[56:59], v[100:103], v[164:167], v[56:59]
	v_mfma_f32_16x16x32_bf16 v[44:47], v[88:91], v[172:175], v[44:47]
	v_mfma_f32_16x16x32_bf16 v[40:43], v[100:103], v[172:175], v[40:43]
	v_mfma_f32_16x16x32_bf16 v[28:31], v[88:91], v[180:183], v[28:31]
	v_mfma_f32_16x16x32_bf16 v[24:27], v[100:103], v[180:183], v[24:27]
	v_mfma_f32_16x16x32_bf16 v[12:15], v[88:91], v[188:191], v[12:15]
	v_mfma_f32_16x16x32_bf16 v[8:11], v[100:103], v[188:191], v[8:11]
	v_mfma_f32_16x16x32_bf16 v[52:55], v[112:115], v[160:163], v[52:55]
	v_mfma_f32_16x16x32_bf16 v[48:51], v[120:123], v[160:163], v[48:51]
	v_mfma_f32_16x16x32_bf16 v[36:39], v[112:115], v[168:171], v[36:39]
	v_mfma_f32_16x16x32_bf16 v[32:35], v[120:123], v[168:171], v[32:35]
	v_mfma_f32_16x16x32_bf16 v[20:23], v[112:115], v[176:179], v[20:23]
	v_mfma_f32_16x16x32_bf16 v[16:19], v[120:123], v[176:179], v[16:19]
	v_mfma_f32_16x16x32_bf16 v[4:7], v[112:115], v[184:187], v[4:7]
	v_mfma_f32_16x16x32_bf16 v[0:3], v[120:123], v[184:187], v[0:3]
	v_mfma_f32_16x16x32_bf16 v[52:55], v[116:119], v[164:167], v[52:55]
	v_mfma_f32_16x16x32_bf16 v[48:51], v[124:127], v[164:167], v[48:51]
	v_mfma_f32_16x16x32_bf16 v[36:39], v[116:119], v[172:175], v[36:39]
	v_mfma_f32_16x16x32_bf16 v[32:35], v[124:127], v[172:175], v[32:35]
	v_mfma_f32_16x16x32_bf16 v[20:23], v[116:119], v[180:183], v[20:23]
	v_mfma_f32_16x16x32_bf16 v[16:19], v[124:127], v[180:183], v[16:19]
	v_mfma_f32_16x16x32_bf16 v[4:7], v[116:119], v[188:191], v[4:7]
	v_mfma_f32_16x16x32_bf16 v[0:3], v[124:127], v[188:191], v[0:3]
	s_barrier
	s_add_u32 s3, s3, 0x100
	s_addc_u32 s7, s7, 0
	s_cmp_ge_i32 s30, s60
	s_mov_b64 s[12:13], s[8:9]
	s_mov_b32 s28, s30
	s_cbranch_scc0 .LBB0_2239
	v_readlane_b32 s48, v253, 35
	v_readlane_b32 s49, v253, 36
	s_and_b64 vcc, exec, s[44:45]
	s_cbranch_vccnz .LBB0_2244
	s_branch .LBB0_2245

.LBB0_2400:
	s_andn2_b64 vcc, exec, s[60:61]
	s_cbranch_vccnz .LBB0_2402
	s_mov_b32 s7, -1
	s_lshl_b32 s16, s2, 8
	s_ashr_i32 s17, s16, 31
	v_mbcnt_lo_u32_b32 v40, s7, 0
	v_mbcnt_hi_u32_b32 v40, s7, v40
	s_lshl_b64 s[16:17], s[16:17], 2
	s_add_u32 s16, s10, s16
	s_addc_u32 s17, s20, s17
	v_lshlrev_b32_e32 v40, 2, v40
	s_lshl_b32 s7, s0, 12
	v_ashrrev_i32_e32 v41, 31, v40
	s_and_b32 s7, s7, 0x1000
	s_add_i32 m0, s92, s7
	v_lshl_add_u64 v[40:41], v[40:41], 2, s[16:17]
	global_load_lds_dwordx4 v[40:41], off

.LBB0_2404:
	s_add_i32 s40, s8, 2
	s_add_u32 s9, s12, 0xfff80080
	s_addc_u32 s16, s13, -1
	s_add_i32 s41, 0, 0x10000
	s_cmp_eq_u32 s93, s8
	s_cselect_b32 s17, s7, s16
	s_cselect_b32 s16, s22, s9
	s_cselect_b32 s9, s23, s33
	s_cselect_b32 s8, s30, s31
	s_add_i32 s71, 0, 0x14000
	v_add_u32_e32 v52, s41, v202
	v_add_u32_e32 v156, s71, v202
	ds_read_b128 v[40:43], v52
	ds_read_b128 v[44:47], v52 offset:1024
	ds_read_b128 v[48:51], v52 offset:2048
	ds_read_b128 v[52:55], v52 offset:3072
	ds_read_b128 v[80:83], v156
	ds_read_b128 v[84:87], v156 offset:1024
	ds_read_b128 v[152:155], v156 offset:2048
	ds_read_b128 v[156:159], v156 offset:3072
	v_lshl_add_u64 v[204:205], s[12:13], 0, v[182:183]
	s_add_i32 m0, s84, 0xc000
	ds_read_b128 v[160:163], v203
	ds_read_b128 v[164:167], v203 offset:1024
	ds_read_b128 v[168:171], v203 offset:2048
	ds_read_b128 v[172:175], v203 offset:3072
	ds_read_b128 v[186:189], v203 offset:4096
	ds_read_b128 v[190:193], v203 offset:5120
	ds_read_b128 v[194:197], v203 offset:6144
	ds_read_b128 v[198:201], v203 offset:7168
	global_load_lds_dwordx4 v[204:205], off
	s_add_i32 m0, s84, 0xe000
	v_lshl_add_u64 v[204:205], s[12:13], 0, v[184:185]
	global_load_lds_dwordx4 v[204:205], off
	s_waitcnt vmcnt(8) lgkmcnt(0)
	s_barrier
	v_mfma_f32_16x16x32_bf16 v[76:79], v[40:43], v[160:163], v[76:79]
	v_mfma_f32_16x16x32_bf16 v[72:75], v[48:51], v[160:163], v[72:75]
	v_mfma_f32_16x16x32_bf16 v[140:143], v[40:43], v[168:171], v[140:143]
	v_mfma_f32_16x16x32_bf16 v[136:139], v[48:51], v[168:171], v[136:139]
	v_mfma_f32_16x16x32_bf16 v[124:127], v[40:43], v[186:189], v[124:127]
	v_mfma_f32_16x16x32_bf16 v[120:123], v[48:51], v[186:189], v[120:123]
	v_mfma_f32_16x16x32_bf16 v[108:111], v[40:43], v[194:197], v[108:111]
	v_mfma_f32_16x16x32_bf16 v[104:107], v[48:51], v[194:197], v[104:107]
	v_mfma_f32_16x16x32_bf16 v[76:79], v[44:47], v[164:167], v[76:79]
	v_mfma_f32_16x16x32_bf16 v[72:75], v[52:55], v[164:167], v[72:75]
	v_mfma_f32_16x16x32_bf16 v[140:143], v[44:47], v[172:175], v[140:143]
	v_mfma_f32_16x16x32_bf16 v[136:139], v[52:55], v[172:175], v[136:139]
	v_mfma_f32_16x16x32_bf16 v[124:127], v[44:47], v[190:193], v[124:127]
	v_mfma_f32_16x16x32_bf16 v[120:123], v[52:55], v[190:193], v[120:123]
	v_mfma_f32_16x16x32_bf16 v[108:111], v[44:47], v[198:201], v[108:111]
	v_mfma_f32_16x16x32_bf16 v[104:107], v[52:55], v[198:201], v[104:107]
	v_mfma_f32_16x16x32_bf16 v[148:151], v[80:83], v[160:163], v[148:151]
	v_mfma_f32_16x16x32_bf16 v[144:147], v[152:155], v[160:163], v[144:147]
	v_mfma_f32_16x16x32_bf16 v[132:135], v[80:83], v[168:171], v[132:135]
	v_mfma_f32_16x16x32_bf16 v[128:131], v[152:155], v[168:171], v[128:131]
	v_mfma_f32_16x16x32_bf16 v[116:119], v[80:83], v[186:189], v[116:119]
	v_mfma_f32_16x16x32_bf16 v[112:115], v[152:155], v[186:189], v[112:115]
	v_mfma_f32_16x16x32_bf16 v[100:103], v[80:83], v[194:197], v[100:103]
	v_mfma_f32_16x16x32_bf16 v[96:99], v[152:155], v[194:197], v[96:99]
	v_mfma_f32_16x16x32_bf16 v[148:151], v[84:87], v[164:167], v[148:151]
	v_mfma_f32_16x16x32_bf16 v[144:147], v[156:159], v[164:167], v[144:147]
	v_mfma_f32_16x16x32_bf16 v[132:135], v[84:87], v[172:175], v[132:135]
	v_mfma_f32_16x16x32_bf16 v[128:131], v[156:159], v[172:175], v[128:131]
	v_mfma_f32_16x16x32_bf16 v[116:119], v[84:87], v[190:193], v[116:119]
	v_mfma_f32_16x16x32_bf16 v[112:115], v[156:159], v[190:193], v[112:115]
	v_mfma_f32_16x16x32_bf16 v[100:103], v[84:87], v[198:201], v[100:103]
	v_mfma_f32_16x16x32_bf16 v[96:99], v[156:159], v[198:201], v[96:99]
	s_barrier
	s_add_i32 s41, s41, s28
	v_lshl_add_u64 v[204:205], s[8:9], 0, v[224:225]
	s_mov_b32 m0, s41
	ds_read_b128 v[160:163], v203 offset:16384
	ds_read_b128 v[164:167], v203 offset:17408
	ds_read_b128 v[168:171], v203 offset:18432
	ds_read_b128 v[172:175], v203 offset:19456
	ds_read_b128 v[186:189], v203 offset:20480
	ds_read_b128 v[190:193], v203 offset:21504
	ds_read_b128 v[194:197], v203 offset:22528
	ds_read_b128 v[198:201], v203 offset:23552
	global_load_lds_dwordx4 v[204:205], off
	s_add_i32 m0, s41, 0x2000
	s_add_u32 s42, s8, 0x80000
	v_lshl_add_u64 v[206:207], s[8:9], 0, v[176:177]
	s_addc_u32 s43, s9, 0
	s_add_i32 s41, s71, s28
	global_load_lds_dwordx4 v[206:207], off
	v_lshl_add_u64 v[208:209], s[42:43], 0, v[224:225]
	s_mov_b32 m0, s41
	v_lshl_add_u64 v[210:211], s[16:17], 0, v[178:179]
	global_load_lds_dwordx4 v[208:209], off
	s_add_i32 m0, s41, 0x2000
	v_lshl_add_u64 v[208:209], s[42:43], 0, v[176:177]
	global_load_lds_dwordx4 v[208:209], off
	s_mov_b32 m0, s84
	v_lshl_add_u64 v[208:209], s[16:17], 0, v[180:181]
	global_load_lds_dwordx4 v[208:209], off
	s_mov_b32 m0, s85
	s_nop 0
	global_load_lds_dwordx4 v[210:211], off
	s_waitcnt vmcnt(8) lgkmcnt(0)
	s_barrier
	v_mfma_f32_16x16x32_bf16 v[92:95], v[40:43], v[160:163], v[92:95]
	v_mfma_f32_16x16x32_bf16 v[88:91], v[48:51], v[160:163], v[88:91]
	v_mfma_f32_16x16x32_bf16 v[60:63], v[40:43], v[168:171], v[60:63]
	v_mfma_f32_16x16x32_bf16 v[56:59], v[48:51], v[168:171], v[56:59]
	v_mfma_f32_16x16x32_bf16 v[28:31], v[40:43], v[186:189], v[28:31]
	v_mfma_f32_16x16x32_bf16 v[24:27], v[48:51], v[186:189], v[24:27]
	v_mfma_f32_16x16x32_bf16 v[12:15], v[40:43], v[194:197], v[12:15]
	v_mfma_f32_16x16x32_bf16 v[8:11], v[48:51], v[194:197], v[8:11]
	v_mfma_f32_16x16x32_bf16 v[92:95], v[44:47], v[164:167], v[92:95]
	v_mfma_f32_16x16x32_bf16 v[88:91], v[52:55], v[164:167], v[88:91]
	v_mfma_f32_16x16x32_bf16 v[60:63], v[44:47], v[172:175], v[60:63]
	v_mfma_f32_16x16x32_bf16 v[56:59], v[52:55], v[172:175], v[56:59]
	v_mfma_f32_16x16x32_bf16 v[28:31], v[44:47], v[190:193], v[28:31]
	v_mfma_f32_16x16x32_bf16 v[24:27], v[52:55], v[190:193], v[24:27]
	v_mfma_f32_16x16x32_bf16 v[12:15], v[44:47], v[198:201], v[12:15]
	v_mfma_f32_16x16x32_bf16 v[8:11], v[52:55], v[198:201], v[8:11]
	v_mfma_f32_16x16x32_bf16 v[36:39], v[80:83], v[168:171], v[36:39]
	v_mfma_f32_16x16x32_bf16 v[32:35], v[152:155], v[168:171], v[32:35]
	v_mfma_f32_16x16x32_bf16 v[20:23], v[80:83], v[186:189], v[20:23]
	v_mfma_f32_16x16x32_bf16 v[16:19], v[152:155], v[186:189], v[16:19]
	v_mfma_f32_16x16x32_bf16 v[4:7], v[80:83], v[194:197], v[4:7]
	v_mfma_f32_16x16x32_bf16 v[0:3], v[152:155], v[194:197], v[0:3]
	v_mfma_f32_16x16x32_bf16 v[40:43], v[80:83], v[160:163], v[68:71]
	v_mfma_f32_16x16x32_bf16 v[44:47], v[152:155], v[160:163], v[64:67]
	v_mfma_f32_16x16x32_bf16 v[36:39], v[84:87], v[172:175], v[36:39]
	v_mfma_f32_16x16x32_bf16 v[32:35], v[156:159], v[172:175], v[32:35]
	v_mfma_f32_16x16x32_bf16 v[20:23], v[84:87], v[190:193], v[20:23]
	v_mfma_f32_16x16x32_bf16 v[16:19], v[156:159], v[190:193], v[16:19]
	v_mfma_f32_16x16x32_bf16 v[4:7], v[84:87], v[198:201], v[4:7]
	v_mfma_f32_16x16x32_bf16 v[0:3], v[156:159], v[198:201], v[0:3]
	v_mfma_f32_16x16x32_bf16 v[40:43], v[84:87], v[164:167], v[40:43]
	v_mfma_f32_16x16x32_bf16 v[44:47], v[156:159], v[164:167], v[44:47]
	s_barrier
	s_add_i32 s41, 0, 0x18000
	s_add_i32 s42, 0, 0x1c000
	v_add_u32_e32 v68, s41, v202
	v_add_u32_e32 v156, s42, v202
	ds_read_b128 v[48:51], v68
	ds_read_b128 v[52:55], v68 offset:1024
	ds_read_b128 v[64:67], v68 offset:2048
	ds_read_b128 v[68:71], v68 offset:3072
	ds_read_b128 v[80:83], v156
	ds_read_b128 v[84:87], v156 offset:1024
	ds_read_b128 v[152:155], v156 offset:2048
	ds_read_b128 v[156:159], v156 offset:3072
	s_add_u32 s16, s16, 0x80000
	s_addc_u32 s17, s17, 0
	s_mov_b32 m0, s86
	v_lshl_add_u64 v[212:213], s[16:17], 0, v[180:181]
	ds_read_b128 v[160:163], v203 offset:32768
	ds_read_b128 v[164:167], v203 offset:33792
	ds_read_b128 v[168:171], v203 offset:34816
	ds_read_b128 v[172:175], v203 offset:35840
	ds_read_b128 v[186:189], v203 offset:36864
	ds_read_b128 v[190:193], v203 offset:37888
	ds_read_b128 v[194:197], v203 offset:38912
	ds_read_b128 v[198:201], v203 offset:39936
	global_load_lds_dwordx4 v[212:213], off
	s_mov_b32 m0, s87
	v_lshl_add_u64 v[212:213], s[16:17], 0, v[178:179]
	global_load_lds_dwordx4 v[212:213], off
	s_waitcnt vmcnt(8) lgkmcnt(0)
	s_barrier
	v_mfma_f32_16x16x32_bf16 v[76:79], v[48:51], v[160:163], v[76:79]
	v_mfma_f32_16x16x32_bf16 v[72:75], v[64:67], v[160:163], v[72:75]
	v_mfma_f32_16x16x32_bf16 v[140:143], v[48:51], v[168:171], v[140:143]
	v_mfma_f32_16x16x32_bf16 v[136:139], v[64:67], v[168:171], v[136:139]
	v_mfma_f32_16x16x32_bf16 v[124:127], v[48:51], v[186:189], v[124:127]
	v_mfma_f32_16x16x32_bf16 v[120:123], v[64:67], v[186:189], v[120:123]
	v_mfma_f32_16x16x32_bf16 v[108:111], v[48:51], v[194:197], v[108:111]
	v_mfma_f32_16x16x32_bf16 v[104:107], v[64:67], v[194:197], v[104:107]
	v_mfma_f32_16x16x32_bf16 v[76:79], v[52:55], v[164:167], v[76:79]
	v_mfma_f32_16x16x32_bf16 v[72:75], v[68:71], v[164:167], v[72:75]
	v_mfma_f32_16x16x32_bf16 v[140:143], v[52:55], v[172:175], v[140:143]
	v_mfma_f32_16x16x32_bf16 v[136:139], v[68:71], v[172:175], v[136:139]
	v_mfma_f32_16x16x32_bf16 v[124:127], v[52:55], v[190:193], v[124:127]
	v_mfma_f32_16x16x32_bf16 v[120:123], v[68:71], v[190:193], v[120:123]
	v_mfma_f32_16x16x32_bf16 v[108:111], v[52:55], v[198:201], v[108:111]
	v_mfma_f32_16x16x32_bf16 v[104:107], v[68:71], v[198:201], v[104:107]
	v_mfma_f32_16x16x32_bf16 v[148:151], v[80:83], v[160:163], v[148:151]
	v_mfma_f32_16x16x32_bf16 v[144:147], v[152:155], v[160:163], v[144:147]
	v_mfma_f32_16x16x32_bf16 v[132:135], v[80:83], v[168:171], v[132:135]
	v_mfma_f32_16x16x32_bf16 v[128:131], v[152:155], v[168:171], v[128:131]
	v_mfma_f32_16x16x32_bf16 v[116:119], v[80:83], v[186:189], v[116:119]
	v_mfma_f32_16x16x32_bf16 v[112:115], v[152:155], v[186:189], v[112:115]
	v_mfma_f32_16x16x32_bf16 v[100:103], v[80:83], v[194:197], v[100:103]
	v_mfma_f32_16x16x32_bf16 v[96:99], v[152:155], v[194:197], v[96:99]
	v_mfma_f32_16x16x32_bf16 v[148:151], v[84:87], v[164:167], v[148:151]
	v_mfma_f32_16x16x32_bf16 v[144:147], v[156:159], v[164:167], v[144:147]
	v_mfma_f32_16x16x32_bf16 v[132:135], v[84:87], v[172:175], v[132:135]
	v_mfma_f32_16x16x32_bf16 v[128:131], v[156:159], v[172:175], v[128:131]
	v_mfma_f32_16x16x32_bf16 v[116:119], v[84:87], v[190:193], v[116:119]
	v_mfma_f32_16x16x32_bf16 v[112:115], v[156:159], v[190:193], v[112:115]
	v_mfma_f32_16x16x32_bf16 v[100:103], v[84:87], v[198:201], v[100:103]
	v_mfma_f32_16x16x32_bf16 v[96:99], v[156:159], v[198:201], v[96:99]
	s_barrier
	s_add_i32 s16, s41, s28
	v_lshl_add_u64 v[204:205], v[204:205], 0, s[24:25]
	s_mov_b32 m0, s16
	ds_read_b128 v[160:163], v203 offset:49152
	ds_read_b128 v[164:167], v203 offset:50176
	ds_read_b128 v[168:171], v203 offset:51200
	ds_read_b128 v[172:175], v203 offset:52224
	ds_read_b128 v[186:189], v203 offset:53248
	ds_read_b128 v[190:193], v203 offset:54272
	ds_read_b128 v[194:197], v203 offset:55296
	ds_read_b128 v[198:201], v203 offset:56320
	global_load_lds_dwordx4 v[204:205], off
	s_add_i32 m0, s16, 0x2000
	s_add_u32 s8, s8, 0x80080
	v_lshl_add_u64 v[204:205], v[206:207], 0, s[24:25]
	s_addc_u32 s9, s9, 0
	s_add_i32 s16, s42, s28
	global_load_lds_dwordx4 v[204:205], off
	s_mov_b32 m0, s16
	v_lshl_add_u64 v[204:205], s[8:9], 0, v[224:225]
	global_load_lds_dwordx4 v[204:205], off
	s_add_i32 m0, s16, 0x2000
	v_lshl_add_u64 v[204:205], s[8:9], 0, v[176:177]
	global_load_lds_dwordx4 v[204:205], off
	s_mov_b32 m0, s18
	v_lshl_add_u64 v[204:205], v[208:209], 0, s[24:25]
	global_load_lds_dwordx4 v[204:205], off
	s_mov_b32 m0, s19
	v_lshl_add_u64 v[204:205], v[210:211], 0, s[24:25]
	global_load_lds_dwordx4 v[204:205], off
	s_waitcnt vmcnt(8) lgkmcnt(0)
	s_barrier
	v_mfma_f32_16x16x32_bf16 v[92:95], v[48:51], v[160:163], v[92:95]
	v_mfma_f32_16x16x32_bf16 v[88:91], v[64:67], v[160:163], v[88:91]
	v_mfma_f32_16x16x32_bf16 v[60:63], v[48:51], v[168:171], v[60:63]
	v_mfma_f32_16x16x32_bf16 v[56:59], v[64:67], v[168:171], v[56:59]
	v_mfma_f32_16x16x32_bf16 v[28:31], v[48:51], v[186:189], v[28:31]
	v_mfma_f32_16x16x32_bf16 v[24:27], v[64:67], v[186:189], v[24:27]
	v_mfma_f32_16x16x32_bf16 v[12:15], v[48:51], v[194:197], v[12:15]
	v_mfma_f32_16x16x32_bf16 v[8:11], v[64:67], v[194:197], v[8:11]
	v_mfma_f32_16x16x32_bf16 v[92:95], v[52:55], v[164:167], v[92:95]
	v_mfma_f32_16x16x32_bf16 v[88:91], v[68:71], v[164:167], v[88:91]
	v_mfma_f32_16x16x32_bf16 v[60:63], v[52:55], v[172:175], v[60:63]
	v_mfma_f32_16x16x32_bf16 v[56:59], v[68:71], v[172:175], v[56:59]
	v_mfma_f32_16x16x32_bf16 v[28:31], v[52:55], v[190:193], v[28:31]
	v_mfma_f32_16x16x32_bf16 v[24:27], v[68:71], v[190:193], v[24:27]
	v_mfma_f32_16x16x32_bf16 v[12:15], v[52:55], v[198:201], v[12:15]
	v_mfma_f32_16x16x32_bf16 v[8:11], v[68:71], v[198:201], v[8:11]
	v_mfma_f32_16x16x32_bf16 v[40:43], v[80:83], v[160:163], v[40:43]
	v_mfma_f32_16x16x32_bf16 v[68:71], v[84:87], v[164:167], v[40:43]
	v_mfma_f32_16x16x32_bf16 v[40:43], v[152:155], v[160:163], v[44:47]
	v_mfma_f32_16x16x32_bf16 v[36:39], v[80:83], v[168:171], v[36:39]
	v_mfma_f32_16x16x32_bf16 v[32:35], v[152:155], v[168:171], v[32:35]
	v_mfma_f32_16x16x32_bf16 v[20:23], v[80:83], v[186:189], v[20:23]
	v_mfma_f32_16x16x32_bf16 v[16:19], v[152:155], v[186:189], v[16:19]
	v_mfma_f32_16x16x32_bf16 v[4:7], v[80:83], v[194:197], v[4:7]
	v_mfma_f32_16x16x32_bf16 v[0:3], v[152:155], v[194:197], v[0:3]
	v_mfma_f32_16x16x32_bf16 v[64:67], v[156:159], v[164:167], v[40:43]
	v_mfma_f32_16x16x32_bf16 v[36:39], v[84:87], v[172:175], v[36:39]
	v_mfma_f32_16x16x32_bf16 v[32:35], v[156:159], v[172:175], v[32:35]
	v_mfma_f32_16x16x32_bf16 v[20:23], v[84:87], v[190:193], v[20:23]
	v_mfma_f32_16x16x32_bf16 v[16:19], v[156:159], v[190:193], v[16:19]
	v_mfma_f32_16x16x32_bf16 v[4:7], v[84:87], v[198:201], v[4:7]
	v_mfma_f32_16x16x32_bf16 v[0:3], v[156:159], v[198:201], v[0:3]
	s_barrier
	s_add_u32 s12, s12, 0x100
	s_addc_u32 s13, s13, 0
	s_add_u32 s31, s31, 0x100
	s_addc_u32 s33, s33, 0
	s_cmp_ge_i32 s40, s27
	s_mov_b32 s8, s40
	s_cbranch_scc0 .LBB0_2404
